# P9 final epilogue: both gate loads of a row block issued together (on top of residual-epilogue load hoisting in P4/P10/P13 and weight-conversion load batching)
# baseline (speedup 1.0000x reference)
; __device__ __forceinline__ float shfl_xor_l(float v, int o) { const int idx = (opq(lane_now()) ^ o) << 2; return __builtin_bit_cast(float, __builtin_amdgcn_ds_bpermute(idx, __builtin_bit_cast(int, v))); }
;     __device__ __forceinline__ void operator()(AccT& acc, const pg8::Unit& u, int wr, int wc, int fr_, int fq_) const {
;     ...
;             for (int m = 0; m < 4; ++m) { const int row = u.pm * 256 + ai * 128 + wr * 64 + m * 16 + fr + zoff;
;                 const float* xin = xp ? xp + (size_t)row * D : X + (size_t)row * D; float sacc = 0.f;
; #pragma unroll
;                 for (int bj = 0; bj < 2; ++bj)
; #pragma unroll
;                     for (int n = 0; n < 2; ++n) { const int col = u.pn * 256 + bj * 128 + wc * 32 + 8 * fq + 4 * n;
;                         const f32x4 xv = *(const f32x4*)(xin + col), gv = *(const f32x4*)(gt + col);
;                         const f32x4 xn = xv + (gv * coef) * acc[ai][bj][m][n]; acc[ai][bj][m][n] = xn;
;                         if (MODE == 0) *(f32x4*)(X + (size_t)row * D + col) = xn;
;                         sacc += (xn[0] * xn[0] + xn[1] * xn[1]) + (xn[2] * xn[2] + xn[3] * xn[3]); }
;                 asm volatile("" : "+v"(zoff) : "v"(sacc));
;                 sacc += shfl_xor_l(sacc, 16); sacc += shfl_xor_l(sacc, 32);
;                 ss[ai][m] = sacc; __builtin_amdgcn_sched_barrier(0); }
.LBB0_576:
	s_ashr_i32 s4, s34, 3
	s_mul_hi_i32 s5, s4, 0x2400
	s_mulk_i32 s4, 0x2400
	s_lshl_b64 s[6:7], s[4:5], 2
	s_add_u32 s4, s12, s6
	v_mov_b32_e32 v134, v165
	s_addc_u32 s5, s13, s7
	s_lshl_b32 s10, s36, 8
	v_mov_b32_e32 v135, v164
	v_add_u32_e32 v152, s80, v134
	s_or_b32 s10, s10, s81
	v_lshl_add_u32 v132, s34, 8, v152
	v_lshl_add_u32 v154, v135, 3, s10
	v_ashrrev_i32_e32 v133, 31, v132
	v_ashrrev_i32_e32 v155, 31, v154
	v_lshlrev_b64 v[174:175], 12, v[132:133]
	v_lshlrev_b64 v[128:129], 2, v[154:155]
	v_lshl_add_u64 v[160:161], s[26:27], 0, v[174:175]
	v_lshl_add_u64 v[130:131], s[4:5], 0, v[128:129]
	global_load_dwordx4 v[196:199], v[130:131], off
	global_load_dwordx4 v[200:203], v[130:131], off offset:16
	global_load_dwordx4 v[204:207], v[130:131], off offset:512
	global_load_dwordx4 v[208:211], v[130:131], off offset:528
	v_lshl_add_u64 v[176:177], v[160:161], 0, v[128:129]
	global_load_dwordx4 v[212:215], v[176:177], off
	global_load_dwordx4 v[216:219], v[176:177], off offset:16
	global_load_dwordx4 v[220:223], v[176:177], off offset:512
	global_load_dwordx4 v[224:227], v[176:177], off offset:528
	v_lshl_add_u64 v[174:175], s[14:15], 0, v[174:175]
	v_lshl_add_u64 v[174:175], v[174:175], 0, v[128:129]
	v_mov_b32_e32 v133, 0
	v_mov_b32_e32 v153, v166
	s_waitcnt vmcnt(7)
	v_pk_mul_f32 v[158:159], v[198:199], 0.5 op_sel_hi:[1,0]
	v_pk_mul_f32 v[156:157], v[196:197], 0.5 op_sel_hi:[1,0]
	s_waitcnt vmcnt(3)
	v_pk_fma_f32 v[58:59], v[58:59], v[158:159], v[214:215]
	v_pk_fma_f32 v[56:57], v[56:57], v[156:157], v[212:213]
	global_store_dwordx4 v[174:175], v[56:59], off
	v_pk_mul_f32 v[178:179], v[56:57], v[56:57]
	v_pk_mul_f32 v[158:159], v[202:203], 0.5 op_sel_hi:[1,0]
	v_pk_mul_f32 v[156:157], v[200:201], 0.5 op_sel_hi:[1,0]
	s_waitcnt vmcnt(3)
	v_pk_fma_f32 v[62:63], v[62:63], v[158:159], v[218:219]
	v_pk_fma_f32 v[60:61], v[60:61], v[156:157], v[216:217]
	global_store_dwordx4 v[174:175], v[60:63], off offset:16
	v_pk_mul_f32 v[158:159], v[206:207], 0.5 op_sel_hi:[1,0]
	v_pk_mul_f32 v[156:157], v[204:205], 0.5 op_sel_hi:[1,0]
	s_waitcnt vmcnt(3)
	v_pk_fma_f32 v[22:23], v[22:23], v[158:159], v[222:223]
	v_pk_fma_f32 v[20:21], v[20:21], v[156:157], v[220:221]
	global_store_dwordx4 v[174:175], v[20:23], off offset:512
	v_pk_mul_f32 v[176:177], v[58:59], v[58:59]
	v_pk_mul_f32 v[158:159], v[210:211], 0.5 op_sel_hi:[1,0]
	v_pk_mov_b32 v[180:181], v[178:179], v[176:177] op_sel:[1,0]
	v_mov_b32_e32 v179, v177
	v_pk_add_f32 v[176:177], v[180:181], v[178:179]
	v_pk_mul_f32 v[178:179], v[62:63], v[62:63]
	v_pk_mul_f32 v[180:181], v[60:61], v[60:61]
	v_pk_mul_f32 v[156:157], v[208:209], 0.5 op_sel_hi:[1,0]
	v_pk_mov_b32 v[182:183], v[180:181], v[178:179] op_sel:[1,0]
	v_mov_b32_e32 v181, v179
	v_pk_add_f32 v[178:179], v[182:183], v[180:181]
	v_mul_f32_e32 v180, v21, v21
	v_mul_f32_e32 v182, v23, v23
	v_pk_add_f32 v[176:177], v[176:177], v[176:177] op_sel:[0,1] op_sel_hi:[1,0]
	v_pk_add_f32 v[178:179], v[178:179], v[178:179] op_sel:[0,1] op_sel_hi:[1,0]
	v_pk_fma_f32 v[180:181], v[20:21], v[20:21], v[180:181] op_sel_hi:[1,1,0]
	v_pk_fma_f32 v[182:183], v[22:23], v[22:23], v[182:183] op_sel_hi:[1,1,0]
	s_waitcnt vmcnt(3)
	v_pk_fma_f32 v[30:31], v[30:31], v[158:159], v[226:227]
	v_pk_fma_f32 v[28:29], v[28:29], v[156:157], v[224:225]
	v_mul_f32_e32 v181, v30, v30
	v_mul_f32_e32 v177, v28, v28
	v_mul_f32_e32 v179, v29, v29
	v_mul_f32_e32 v183, v31, v31
	v_pk_add_f32 v[156:157], v[176:177], v[178:179]
	v_pk_add_f32 v[158:159], v[180:181], v[182:183]
	global_store_dwordx4 v[174:175], v[28:31], off offset:528
	v_pk_add_f32 v[156:157], v[156:157], v[158:159]
	s_nop 0
	v_add_f32_e32 v156, v156, v157
	v_mov_b32_e32 v157, v166
	v_lshlrev_b32_e32 v153, 2, v153
	v_xor_b32_e32 v153, 64, v153
	ds_bpermute_b32 v153, v153, v156
	s_waitcnt lgkmcnt(0)
	v_add_f32_e32 v153, v156, v153
	v_lshlrev_b32_e32 v157, 2, v157
	v_xor_b32_e32 v156, 0x80, v157
	ds_bpermute_b32 v156, v156, v153
	v_add3_u32 v158, v132, v133, 16
	v_ashrrev_i32_e32 v159, 31, v158
	v_lshlrev_b64 v[162:163], 12, v[158:159]
	v_lshl_add_u64 v[174:175], s[26:27], 0, v[162:163]
	v_lshl_add_u64 v[178:179], v[174:175], 0, v[128:129]
	global_load_dwordx4 v[212:215], v[178:179], off
	global_load_dwordx4 v[216:219], v[178:179], off offset:16
	global_load_dwordx4 v[220:223], v[178:179], off offset:512
	global_load_dwordx4 v[224:227], v[178:179], off offset:528
	v_lshl_add_u64 v[162:163], s[14:15], 0, v[162:163]
	v_lshl_add_u64 v[162:163], v[162:163], 0, v[128:129]
	v_mov_b32_e32 v157, v166
	v_pk_mul_f32 v[160:161], v[198:199], 0.5 op_sel_hi:[1,0]
	v_pk_mul_f32 v[158:159], v[196:197], 0.5 op_sel_hi:[1,0]
	s_waitcnt vmcnt(3)
	v_pk_fma_f32 v[86:87], v[86:87], v[160:161], v[214:215]
	v_pk_fma_f32 v[84:85], v[84:85], v[158:159], v[212:213]
	global_store_dwordx4 v[162:163], v[84:87], off
	v_pk_mul_f32 v[180:181], v[84:85], v[84:85]
	v_pk_mul_f32 v[160:161], v[202:203], 0.5 op_sel_hi:[1,0]
	v_pk_mul_f32 v[158:159], v[200:201], 0.5 op_sel_hi:[1,0]
	s_waitcnt vmcnt(3)
	v_pk_fma_f32 v[90:91], v[90:91], v[160:161], v[218:219]
	v_pk_fma_f32 v[88:89], v[88:89], v[158:159], v[216:217]
	global_store_dwordx4 v[162:163], v[88:91], off offset:16
	v_pk_mul_f32 v[160:161], v[206:207], 0.5 op_sel_hi:[1,0]
	v_pk_mul_f32 v[158:159], v[204:205], 0.5 op_sel_hi:[1,0]
	s_waitcnt vmcnt(3)
; __device__ __forceinline__ float shfl_xor_l(float v, int o) { const int idx = (opq(lane_now()) ^ o) << 2; return __builtin_bit_cast(float, __builtin_amdgcn_ds_bpermute(idx, __builtin_bit_cast(int, v))); }
;     __device__ __forceinline__ void operator()(AccT& acc, const pg8::Unit& u, int wr, int wc, int fr_, int fq_) const {
;     ...
;             for (int m = 0; m < 4; ++m) { const int row = u.pm * 256 + ai * 128 + wr * 64 + m * 16 + fr + zoff;
;                 const float* xin = xp ? xp + (size_t)row * D : X + (size_t)row * D; float sacc = 0.f;
; #pragma unroll
;                 for (int bj = 0; bj < 2; ++bj)
; #pragma unroll
;                     for (int n = 0; n < 2; ++n) { const int col = u.pn * 256 + bj * 128 + wc * 32 + 8 * fq + 4 * n;
;                         const f32x4 xv = *(const f32x4*)(xin + col), gv = *(const f32x4*)(gt + col);
;                         const f32x4 xn = xv + (gv * coef) * acc[ai][bj][m][n]; acc[ai][bj][m][n] = xn;
;                         if (MODE == 0) *(f32x4*)(X + (size_t)row * D + col) = xn;
;                         sacc += (xn[0] * xn[0] + xn[1] * xn[1]) + (xn[2] * xn[2] + xn[3] * xn[3]); }
;                 asm volatile("" : "+v"(zoff) : "v"(sacc));
;                 sacc += shfl_xor_l(sacc, 16); sacc += shfl_xor_l(sacc, 32);
;                 ss[ai][m] = sacc; __builtin_amdgcn_sched_barrier(0); }
	v_pk_fma_f32 v[42:43], v[42:43], v[160:161], v[222:223]
	v_pk_fma_f32 v[40:41], v[40:41], v[158:159], v[220:221]
	global_store_dwordx4 v[162:163], v[40:43], off offset:512
	v_pk_mul_f32 v[178:179], v[86:87], v[86:87]
	v_pk_mul_f32 v[160:161], v[210:211], 0.5 op_sel_hi:[1,0]
	v_pk_mov_b32 v[182:183], v[180:181], v[178:179] op_sel:[1,0]
	v_mov_b32_e32 v181, v179
	v_pk_add_f32 v[178:179], v[182:183], v[180:181]
	v_pk_mul_f32 v[180:181], v[90:91], v[90:91]
	v_pk_mul_f32 v[182:183], v[88:89], v[88:89]
	v_pk_mul_f32 v[158:159], v[208:209], 0.5 op_sel_hi:[1,0]
	v_pk_mov_b32 v[184:185], v[182:183], v[180:181] op_sel:[1,0]
	v_mov_b32_e32 v183, v181
	v_pk_add_f32 v[180:181], v[184:185], v[182:183]
	v_mul_f32_e32 v182, v41, v41
	v_mul_f32_e32 v184, v43, v43
	v_pk_add_f32 v[178:179], v[178:179], v[178:179] op_sel:[0,1] op_sel_hi:[1,0]
	v_pk_add_f32 v[180:181], v[180:181], v[180:181] op_sel:[0,1] op_sel_hi:[1,0]
	v_pk_fma_f32 v[182:183], v[40:41], v[40:41], v[182:183] op_sel_hi:[1,1,0]
	v_pk_fma_f32 v[184:185], v[42:43], v[42:43], v[184:185] op_sel_hi:[1,1,0]
	s_waitcnt vmcnt(3)
	v_pk_fma_f32 v[50:51], v[50:51], v[160:161], v[226:227]
	v_pk_fma_f32 v[48:49], v[48:49], v[158:159], v[224:225]
	v_mul_f32_e32 v183, v50, v50
	v_mul_f32_e32 v179, v48, v48
	v_mul_f32_e32 v181, v49, v49
	v_mul_f32_e32 v185, v51, v51
	v_pk_add_f32 v[158:159], v[178:179], v[180:181]
	v_pk_add_f32 v[160:161], v[182:183], v[184:185]
	global_store_dwordx4 v[162:163], v[48:51], off offset:528
	v_pk_add_f32 v[158:159], v[158:159], v[160:161]
	s_nop 0
	v_add_f32_e32 v158, v158, v159
	v_mov_b32_e32 v159, v166
	v_lshlrev_b32_e32 v157, 2, v157
	v_xor_b32_e32 v157, 64, v157
	ds_bpermute_b32 v157, v157, v158
	s_waitcnt lgkmcnt(0)
	v_add_f32_e32 v157, v158, v157
	v_lshlrev_b32_e32 v159, 2, v159
	v_xor_b32_e32 v158, 0x80, v159
	ds_bpermute_b32 v158, v158, v157
	v_add3_u32 v160, v132, v133, 32
	v_ashrrev_i32_e32 v161, 31, v160
	v_lshlrev_b64 v[178:179], 12, v[160:161]
	v_lshl_add_u64 v[174:175], s[26:27], 0, v[178:179]
	v_lshl_add_u64 v[180:181], v[174:175], 0, v[128:129]
	global_load_dwordx4 v[212:215], v[180:181], off
	global_load_dwordx4 v[216:219], v[180:181], off offset:16
	global_load_dwordx4 v[220:223], v[180:181], off offset:512
	global_load_dwordx4 v[224:227], v[180:181], off offset:528
	v_lshl_add_u64 v[178:179], s[14:15], 0, v[178:179]
	v_lshl_add_u64 v[178:179], v[178:179], 0, v[128:129]
	v_mov_b32_e32 v159, v166
	v_pk_mul_f32 v[162:163], v[198:199], 0.5 op_sel_hi:[1,0]
	v_pk_mul_f32 v[160:161], v[196:197], 0.5 op_sel_hi:[1,0]
	s_waitcnt vmcnt(3)
	v_pk_fma_f32 v[114:115], v[114:115], v[162:163], v[214:215]
	v_pk_fma_f32 v[112:113], v[112:113], v[160:161], v[212:213]
	global_store_dwordx4 v[178:179], v[112:115], off
	v_pk_mul_f32 v[182:183], v[112:113], v[112:113]
	v_pk_mul_f32 v[162:163], v[202:203], 0.5 op_sel_hi:[1,0]
	v_pk_mul_f32 v[160:161], v[200:201], 0.5 op_sel_hi:[1,0]
	s_waitcnt vmcnt(3)
	v_pk_fma_f32 v[118:119], v[118:119], v[162:163], v[218:219]
	v_pk_fma_f32 v[116:117], v[116:117], v[160:161], v[216:217]
	global_store_dwordx4 v[178:179], v[116:119], off offset:16
	v_pk_mul_f32 v[162:163], v[206:207], 0.5 op_sel_hi:[1,0]
	v_pk_mul_f32 v[160:161], v[204:205], 0.5 op_sel_hi:[1,0]
	s_waitcnt vmcnt(3)
	v_pk_fma_f32 v[66:67], v[66:67], v[162:163], v[222:223]
	v_pk_fma_f32 v[64:65], v[64:65], v[160:161], v[220:221]
	global_store_dwordx4 v[178:179], v[64:67], off offset:512
	v_pk_mul_f32 v[180:181], v[114:115], v[114:115]
	v_pk_mul_f32 v[162:163], v[210:211], 0.5 op_sel_hi:[1,0]
	v_pk_mov_b32 v[184:185], v[182:183], v[180:181] op_sel:[1,0]
	v_mov_b32_e32 v183, v181
	v_pk_add_f32 v[180:181], v[184:185], v[182:183]
	v_pk_mul_f32 v[182:183], v[118:119], v[118:119]
	v_pk_mul_f32 v[184:185], v[116:117], v[116:117]
	v_pk_mul_f32 v[160:161], v[208:209], 0.5 op_sel_hi:[1,0]
	v_pk_mov_b32 v[186:187], v[184:185], v[182:183] op_sel:[1,0]
	v_mov_b32_e32 v185, v183
	v_pk_add_f32 v[182:183], v[186:187], v[184:185]
	v_mul_f32_e32 v184, v65, v65
	v_mul_f32_e32 v186, v67, v67
	v_pk_add_f32 v[180:181], v[180:181], v[180:181] op_sel:[0,1] op_sel_hi:[1,0]
	v_pk_add_f32 v[182:183], v[182:183], v[182:183] op_sel:[0,1] op_sel_hi:[1,0]
	v_pk_fma_f32 v[184:185], v[64:65], v[64:65], v[184:185] op_sel_hi:[1,1,0]
	v_pk_fma_f32 v[186:187], v[66:67], v[66:67], v[186:187] op_sel_hi:[1,1,0]
	s_waitcnt vmcnt(3)
	v_pk_fma_f32 v[82:83], v[82:83], v[162:163], v[226:227]
	v_pk_fma_f32 v[80:81], v[80:81], v[160:161], v[224:225]
	v_mul_f32_e32 v185, v82, v82
	v_mul_f32_e32 v181, v80, v80
	v_mul_f32_e32 v183, v81, v81
	v_mul_f32_e32 v187, v83, v83
	v_pk_add_f32 v[160:161], v[180:181], v[182:183]
	v_pk_add_f32 v[162:163], v[184:185], v[186:187]
	global_store_dwordx4 v[178:179], v[80:83], off offset:528
	v_pk_add_f32 v[160:161], v[160:161], v[162:163]
	s_nop 0
	v_add_f32_e32 v160, v160, v161
	v_mov_b32_e32 v161, v166
	v_lshlrev_b32_e32 v159, 2, v159
	v_xor_b32_e32 v159, 64, v159
	ds_bpermute_b32 v159, v159, v160
	s_waitcnt lgkmcnt(0)
	v_add_f32_e32 v159, v160, v159
	v_lshlrev_b32_e32 v161, 2, v161
	v_xor_b32_e32 v160, 0x80, v161
	ds_bpermute_b32 v160, v160, v159
	v_add3_u32 v162, v132, v133, 48
	v_ashrrev_i32_e32 v163, 31, v162
	v_lshlrev_b64 v[162:163], 12, v[162:163]
	v_lshl_add_u64 v[178:179], s[26:27], 0, v[162:163]
	v_lshl_add_u64 v[182:183], v[178:179], 0, v[128:129]
	global_load_dwordx4 v[212:215], v[182:183], off
	global_load_dwordx4 v[216:219], v[182:183], off offset:16
	global_load_dwordx4 v[220:223], v[182:183], off offset:512
	global_load_dwordx4 v[224:227], v[182:183], off offset:528
	v_lshl_add_u64 v[162:163], s[14:15], 0, v[162:163]
	v_lshl_add_u64 v[162:163], v[162:163], 0, v[128:129]
	v_mov_b32_e32 v161, v166
	v_pk_mul_f32 v[176:177], v[198:199], 0.5 op_sel_hi:[1,0]
	v_pk_mul_f32 v[174:175], v[196:197], 0.5 op_sel_hi:[1,0]
	s_waitcnt vmcnt(3)
; __device__ __forceinline__ float shfl_xor_l(float v, int o) { const int idx = (opq(lane_now()) ^ o) << 2; return __builtin_bit_cast(float, __builtin_amdgcn_ds_bpermute(idx, __builtin_bit_cast(int, v))); }
;     __device__ __forceinline__ void operator()(AccT& acc, const pg8::Unit& u, int wr, int wc, int fr_, int fq_) const {
;     ...
;             for (int m = 0; m < 4; ++m) { const int row = u.pm * 256 + ai * 128 + wr * 64 + m * 16 + fr + zoff;
;                 const float* xin = xp ? xp + (size_t)row * D : X + (size_t)row * D; float sacc = 0.f;
; #pragma unroll
;                 for (int bj = 0; bj < 2; ++bj)
; #pragma unroll
;                     for (int n = 0; n < 2; ++n) { const int col = u.pn * 256 + bj * 128 + wc * 32 + 8 * fq + 4 * n;
;                         const f32x4 xv = *(const f32x4*)(xin + col), gv = *(const f32x4*)(gt + col);
;                         const f32x4 xn = xv + (gv * coef) * acc[ai][bj][m][n]; acc[ai][bj][m][n] = xn;
;                         if (MODE == 0) *(f32x4*)(X + (size_t)row * D + col) = xn;
;                         sacc += (xn[0] * xn[0] + xn[1] * xn[1]) + (xn[2] * xn[2] + xn[3] * xn[3]); }
;                 asm volatile("" : "+v"(zoff) : "v"(sacc));
;                 sacc += shfl_xor_l(sacc, 16); sacc += shfl_xor_l(sacc, 32);
;                 ss[ai][m] = sacc; __builtin_amdgcn_sched_barrier(0); }
	v_pk_fma_f32 v[122:123], v[122:123], v[176:177], v[214:215]
	v_pk_fma_f32 v[120:121], v[120:121], v[174:175], v[212:213]
	global_store_dwordx4 v[162:163], v[120:123], off
	v_pk_mul_f32 v[184:185], v[120:121], v[120:121]
	v_pk_mul_f32 v[176:177], v[202:203], 0.5 op_sel_hi:[1,0]
	v_pk_mul_f32 v[174:175], v[200:201], 0.5 op_sel_hi:[1,0]
	s_waitcnt vmcnt(3)
	v_pk_fma_f32 v[126:127], v[126:127], v[176:177], v[218:219]
	v_pk_fma_f32 v[124:125], v[124:125], v[174:175], v[216:217]
	global_store_dwordx4 v[162:163], v[124:127], off offset:16
	v_pk_mul_f32 v[176:177], v[206:207], 0.5 op_sel_hi:[1,0]
	v_pk_mul_f32 v[174:175], v[204:205], 0.5 op_sel_hi:[1,0]
	s_waitcnt vmcnt(3)
	v_pk_fma_f32 v[98:99], v[98:99], v[176:177], v[222:223]
	v_pk_fma_f32 v[96:97], v[96:97], v[174:175], v[220:221]
	global_store_dwordx4 v[162:163], v[96:99], off offset:512
	v_pk_mul_f32 v[182:183], v[122:123], v[122:123]
	v_pk_mul_f32 v[176:177], v[210:211], 0.5 op_sel_hi:[1,0]
	v_pk_mov_b32 v[186:187], v[184:185], v[182:183] op_sel:[1,0]
	v_mov_b32_e32 v185, v183
	v_pk_add_f32 v[182:183], v[186:187], v[184:185]
	v_pk_mul_f32 v[184:185], v[126:127], v[126:127]
	v_pk_mul_f32 v[186:187], v[124:125], v[124:125]
	v_pk_mul_f32 v[174:175], v[208:209], 0.5 op_sel_hi:[1,0]
	v_pk_mov_b32 v[188:189], v[186:187], v[184:185] op_sel:[1,0]
	v_mov_b32_e32 v187, v185
	v_pk_add_f32 v[184:185], v[188:189], v[186:187]
	v_mul_f32_e32 v186, v97, v97
	v_mul_f32_e32 v188, v99, v99
	v_pk_add_f32 v[182:183], v[182:183], v[182:183] op_sel:[0,1] op_sel_hi:[1,0]
	v_pk_add_f32 v[184:185], v[184:185], v[184:185] op_sel:[0,1] op_sel_hi:[1,0]
	v_pk_fma_f32 v[186:187], v[96:97], v[96:97], v[186:187] op_sel_hi:[1,1,0]
	v_pk_fma_f32 v[188:189], v[98:99], v[98:99], v[188:189] op_sel_hi:[1,1,0]
	s_waitcnt vmcnt(3)
	v_pk_fma_f32 v[106:107], v[106:107], v[176:177], v[226:227]
	v_pk_fma_f32 v[104:105], v[104:105], v[174:175], v[224:225]
	v_mul_f32_e32 v187, v106, v106
	v_mul_f32_e32 v183, v104, v104
	v_mul_f32_e32 v185, v105, v105
	v_mul_f32_e32 v189, v107, v107
	global_store_dwordx4 v[162:163], v[104:107], off offset:528
	v_pk_add_f32 v[162:163], v[182:183], v[184:185]
	v_pk_add_f32 v[174:175], v[186:187], v[188:189]
	s_nop 0
	v_pk_add_f32 v[162:163], v[162:163], v[174:175]
	s_nop 0
	v_add_f32_e32 v162, v162, v163
	v_mov_b32_e32 v163, v166
	v_lshlrev_b32_e32 v161, 2, v161
	v_xor_b32_e32 v161, 64, v161
	ds_bpermute_b32 v161, v161, v162
	s_waitcnt lgkmcnt(0)
	v_add_f32_e32 v161, v162, v161
	v_lshlrev_b32_e32 v163, 2, v163
	v_xor_b32_e32 v162, 0x80, v163
	ds_bpermute_b32 v162, v162, v161
	v_add3_u32 v174, v132, v133, s63
	v_ashrrev_i32_e32 v175, 31, v174
	v_lshlrev_b64 v[182:183], 12, v[174:175]
	v_lshl_add_u64 v[178:179], s[26:27], 0, v[182:183]
	v_lshl_add_u64 v[184:185], v[178:179], 0, v[128:129]
	global_load_dwordx4 v[212:215], v[184:185], off
	global_load_dwordx4 v[216:219], v[184:185], off offset:16
	global_load_dwordx4 v[220:223], v[184:185], off offset:512
	global_load_dwordx4 v[224:227], v[184:185], off offset:528
	v_lshl_add_u64 v[182:183], s[14:15], 0, v[182:183]
	v_lshl_add_u64 v[182:183], v[182:183], 0, v[128:129]
	v_mov_b32_e32 v163, v166
	v_pk_mul_f32 v[176:177], v[198:199], 0.5 op_sel_hi:[1,0]
	v_pk_mul_f32 v[174:175], v[196:197], 0.5 op_sel_hi:[1,0]
	s_waitcnt vmcnt(3)
	v_pk_fma_f32 v[110:111], v[110:111], v[176:177], v[214:215]
	v_pk_fma_f32 v[108:109], v[108:109], v[174:175], v[212:213]
	global_store_dwordx4 v[182:183], v[108:111], off
	v_pk_mul_f32 v[186:187], v[108:109], v[108:109]
	v_pk_mul_f32 v[176:177], v[202:203], 0.5 op_sel_hi:[1,0]
	v_pk_mul_f32 v[174:175], v[200:201], 0.5 op_sel_hi:[1,0]
	s_waitcnt vmcnt(3)
	v_pk_fma_f32 v[102:103], v[102:103], v[176:177], v[218:219]
	v_pk_fma_f32 v[100:101], v[100:101], v[174:175], v[216:217]
	global_store_dwordx4 v[182:183], v[100:103], off offset:16
	v_pk_mul_f32 v[176:177], v[206:207], 0.5 op_sel_hi:[1,0]
	v_pk_mul_f32 v[174:175], v[204:205], 0.5 op_sel_hi:[1,0]
	s_waitcnt vmcnt(3)
	v_pk_fma_f32 v[94:95], v[94:95], v[176:177], v[222:223]
	v_pk_fma_f32 v[92:93], v[92:93], v[174:175], v[220:221]
	global_store_dwordx4 v[182:183], v[92:95], off offset:512
	v_pk_mul_f32 v[184:185], v[110:111], v[110:111]
	v_pk_mul_f32 v[176:177], v[210:211], 0.5 op_sel_hi:[1,0]
	v_pk_mov_b32 v[188:189], v[186:187], v[184:185] op_sel:[1,0]
	v_mov_b32_e32 v187, v185
	v_pk_add_f32 v[184:185], v[188:189], v[186:187]
	v_pk_mul_f32 v[186:187], v[102:103], v[102:103]
	v_pk_mul_f32 v[188:189], v[100:101], v[100:101]
	v_pk_mul_f32 v[174:175], v[208:209], 0.5 op_sel_hi:[1,0]
	v_pk_mov_b32 v[190:191], v[188:189], v[186:187] op_sel:[1,0]
	v_mov_b32_e32 v189, v187
	v_pk_add_f32 v[186:187], v[190:191], v[188:189]
	v_mul_f32_e32 v188, v93, v93
	v_mul_f32_e32 v190, v95, v95
	v_pk_add_f32 v[184:185], v[184:185], v[184:185] op_sel:[0,1] op_sel_hi:[1,0]
	v_pk_add_f32 v[186:187], v[186:187], v[186:187] op_sel:[0,1] op_sel_hi:[1,0]
	v_pk_fma_f32 v[188:189], v[92:93], v[92:93], v[188:189] op_sel_hi:[1,1,0]
	v_pk_fma_f32 v[190:191], v[94:95], v[94:95], v[190:191] op_sel_hi:[1,1,0]
	s_waitcnt vmcnt(3)
	v_pk_fma_f32 v[78:79], v[78:79], v[176:177], v[226:227]
	v_pk_fma_f32 v[76:77], v[76:77], v[174:175], v[224:225]
	v_mul_f32_e32 v189, v78, v78
	v_mul_f32_e32 v185, v76, v76
	v_mul_f32_e32 v187, v77, v77
	v_mul_f32_e32 v191, v79, v79
	v_pk_add_f32 v[174:175], v[184:185], v[186:187]
	v_pk_add_f32 v[176:177], v[188:189], v[190:191]
	global_store_dwordx4 v[182:183], v[76:79], off offset:528
	v_pk_add_f32 v[174:175], v[174:175], v[176:177]
	s_nop 0
	v_add_f32_e32 v173, v174, v175
	v_mov_b32_e32 v174, v166
	v_lshlrev_b32_e32 v163, 2, v163
	v_xor_b32_e32 v163, 64, v163
	ds_bpermute_b32 v163, v163, v173
	s_waitcnt lgkmcnt(0)
; __device__ __forceinline__ float shfl_xor_l(float v, int o) { const int idx = (opq(lane_now()) ^ o) << 2; return __builtin_bit_cast(float, __builtin_amdgcn_ds_bpermute(idx, __builtin_bit_cast(int, v))); }
;     __device__ __forceinline__ void operator()(AccT& acc, const pg8::Unit& u, int wr, int wc, int fr_, int fq_) const {
;     ...
;             for (int m = 0; m < 4; ++m) { const int row = u.pm * 256 + ai * 128 + wr * 64 + m * 16 + fr + zoff;
;                 const float* xin = xp ? xp + (size_t)row * D : X + (size_t)row * D; float sacc = 0.f;
; #pragma unroll
;                 for (int bj = 0; bj < 2; ++bj)
; #pragma unroll
;                     for (int n = 0; n < 2; ++n) { const int col = u.pn * 256 + bj * 128 + wc * 32 + 8 * fq + 4 * n;
;                         const f32x4 xv = *(const f32x4*)(xin + col), gv = *(const f32x4*)(gt + col);
;                         const f32x4 xn = xv + (gv * coef) * acc[ai][bj][m][n]; acc[ai][bj][m][n] = xn;
;                         if (MODE == 0) *(f32x4*)(X + (size_t)row * D + col) = xn;
;                         sacc += (xn[0] * xn[0] + xn[1] * xn[1]) + (xn[2] * xn[2] + xn[3] * xn[3]); }
;                 asm volatile("" : "+v"(zoff) : "v"(sacc));
;                 sacc += shfl_xor_l(sacc, 16); sacc += shfl_xor_l(sacc, 32);
;                 ss[ai][m] = sacc; __builtin_amdgcn_sched_barrier(0); }
	v_add_f32_e32 v163, v173, v163
	v_lshlrev_b32_e32 v174, 2, v174
	v_xor_b32_e32 v173, 0x80, v174
	ds_bpermute_b32 v173, v173, v163
	v_add3_u32 v174, v132, v133, s64
	v_ashrrev_i32_e32 v175, 31, v174
	v_lshlrev_b64 v[182:183], 12, v[174:175]
	v_lshl_add_u64 v[178:179], s[26:27], 0, v[182:183]
	v_lshl_add_u64 v[184:185], v[178:179], 0, v[128:129]
	global_load_dwordx4 v[212:215], v[184:185], off
	global_load_dwordx4 v[216:219], v[184:185], off offset:16
	global_load_dwordx4 v[220:223], v[184:185], off offset:512
	global_load_dwordx4 v[224:227], v[184:185], off offset:528
	v_lshl_add_u64 v[182:183], s[14:15], 0, v[182:183]
	v_lshl_add_u64 v[182:183], v[182:183], 0, v[128:129]
	v_mov_b32_e32 v192, v166
	v_pk_mul_f32 v[176:177], v[198:199], 0.5 op_sel_hi:[1,0]
	v_pk_mul_f32 v[174:175], v[196:197], 0.5 op_sel_hi:[1,0]
	s_waitcnt vmcnt(3)
	v_pk_fma_f32 v[74:75], v[74:75], v[176:177], v[214:215]
	v_pk_fma_f32 v[72:73], v[72:73], v[174:175], v[212:213]
	global_store_dwordx4 v[182:183], v[72:75], off
	v_pk_mul_f32 v[186:187], v[72:73], v[72:73]
	v_pk_mul_f32 v[176:177], v[202:203], 0.5 op_sel_hi:[1,0]
	v_pk_mul_f32 v[174:175], v[200:201], 0.5 op_sel_hi:[1,0]
	s_waitcnt vmcnt(3)
	v_pk_fma_f32 v[70:71], v[70:71], v[176:177], v[218:219]
	v_pk_fma_f32 v[68:69], v[68:69], v[174:175], v[216:217]
	global_store_dwordx4 v[182:183], v[68:71], off offset:16
	v_pk_mul_f32 v[176:177], v[206:207], 0.5 op_sel_hi:[1,0]
	v_pk_mul_f32 v[174:175], v[204:205], 0.5 op_sel_hi:[1,0]
	s_waitcnt vmcnt(3)
	v_pk_fma_f32 v[54:55], v[54:55], v[176:177], v[222:223]
	v_pk_fma_f32 v[52:53], v[52:53], v[174:175], v[220:221]
	global_store_dwordx4 v[182:183], v[52:55], off offset:512
	v_pk_mul_f32 v[184:185], v[74:75], v[74:75]
	v_pk_mul_f32 v[176:177], v[210:211], 0.5 op_sel_hi:[1,0]
	v_pk_mov_b32 v[188:189], v[186:187], v[184:185] op_sel:[1,0]
	v_mov_b32_e32 v187, v185
	v_pk_add_f32 v[184:185], v[188:189], v[186:187]
	v_pk_mul_f32 v[186:187], v[70:71], v[70:71]
	v_pk_mul_f32 v[188:189], v[68:69], v[68:69]
	v_pk_mul_f32 v[174:175], v[208:209], 0.5 op_sel_hi:[1,0]
	v_pk_mov_b32 v[190:191], v[188:189], v[186:187] op_sel:[1,0]
	v_mov_b32_e32 v189, v187
	v_pk_add_f32 v[186:187], v[190:191], v[188:189]
	v_mul_f32_e32 v188, v53, v53
	v_mul_f32_e32 v190, v55, v55
	v_pk_add_f32 v[184:185], v[184:185], v[184:185] op_sel:[0,1] op_sel_hi:[1,0]
	v_pk_add_f32 v[186:187], v[186:187], v[186:187] op_sel:[0,1] op_sel_hi:[1,0]
	v_pk_fma_f32 v[188:189], v[52:53], v[52:53], v[188:189] op_sel_hi:[1,1,0]
	v_pk_fma_f32 v[190:191], v[54:55], v[54:55], v[190:191] op_sel_hi:[1,1,0]
	s_waitcnt vmcnt(3)
	v_pk_fma_f32 v[46:47], v[46:47], v[176:177], v[226:227]
	v_pk_fma_f32 v[44:45], v[44:45], v[174:175], v[224:225]
	v_mul_f32_e32 v189, v46, v46
	v_mul_f32_e32 v185, v44, v44
	v_mul_f32_e32 v187, v45, v45
	v_mul_f32_e32 v191, v47, v47
	v_pk_add_f32 v[174:175], v[184:185], v[186:187]
	v_pk_add_f32 v[176:177], v[188:189], v[190:191]
	global_store_dwordx4 v[182:183], v[44:47], off offset:528
	v_pk_add_f32 v[174:175], v[174:175], v[176:177]
	v_mov_b32_e32 v176, v166
	v_add_f32_e32 v174, v174, v175
	s_nop 0
	v_lshlrev_b32_e32 v175, 2, v192
	v_xor_b32_e32 v175, 64, v175
	ds_bpermute_b32 v175, v175, v174
	v_lshlrev_b32_e32 v176, 2, v176
	s_waitcnt lgkmcnt(0)
	v_add_f32_e32 v174, v174, v175
	v_xor_b32_e32 v175, 0x80, v176
	ds_bpermute_b32 v175, v175, v174
	v_add3_u32 v176, v132, v133, s65
	v_ashrrev_i32_e32 v177, 31, v176
	v_lshlrev_b64 v[184:185], 12, v[176:177]
	v_lshl_add_u64 v[180:181], s[26:27], 0, v[184:185]
	v_lshl_add_u64 v[186:187], v[180:181], 0, v[128:129]
	global_load_dwordx4 v[212:215], v[186:187], off
	global_load_dwordx4 v[216:219], v[186:187], off offset:16
	global_load_dwordx4 v[220:223], v[186:187], off offset:512
	global_load_dwordx4 v[224:227], v[186:187], off offset:528
	v_lshl_add_u64 v[184:185], s[14:15], 0, v[184:185]
	v_lshl_add_u64 v[184:185], v[184:185], 0, v[128:129]
	v_mov_b32_e32 v194, v166
	v_pk_mul_f32 v[178:179], v[198:199], 0.5 op_sel_hi:[1,0]
	v_pk_mul_f32 v[176:177], v[196:197], 0.5 op_sel_hi:[1,0]
	s_waitcnt vmcnt(3)
	v_pk_fma_f32 v[38:39], v[38:39], v[178:179], v[214:215]
	v_pk_fma_f32 v[36:37], v[36:37], v[176:177], v[212:213]
	global_store_dwordx4 v[184:185], v[36:39], off
	v_pk_mul_f32 v[188:189], v[36:37], v[36:37]
	v_pk_mul_f32 v[178:179], v[202:203], 0.5 op_sel_hi:[1,0]
	v_pk_mul_f32 v[176:177], v[200:201], 0.5 op_sel_hi:[1,0]
	s_waitcnt vmcnt(3)
	v_pk_fma_f32 v[34:35], v[34:35], v[178:179], v[218:219]
	v_pk_fma_f32 v[32:33], v[32:33], v[176:177], v[216:217]
	global_store_dwordx4 v[184:185], v[32:35], off offset:16
	v_pk_mul_f32 v[178:179], v[206:207], 0.5 op_sel_hi:[1,0]
	v_pk_mul_f32 v[176:177], v[204:205], 0.5 op_sel_hi:[1,0]
	s_waitcnt vmcnt(3)
; __device__ __forceinline__ float shfl_xor_l(float v, int o) { const int idx = (opq(lane_now()) ^ o) << 2; return __builtin_bit_cast(float, __builtin_amdgcn_ds_bpermute(idx, __builtin_bit_cast(int, v))); }
;     __device__ __forceinline__ void operator()(AccT& acc, const pg8::Unit& u, int wr, int wc, int fr_, int fq_) const {
;     ...
;             for (int m = 0; m < 4; ++m) { const int row = u.pm * 256 + ai * 128 + wr * 64 + m * 16 + fr + zoff;
;                 const float* xin = xp ? xp + (size_t)row * D : X + (size_t)row * D; float sacc = 0.f;
; #pragma unroll
;                 for (int bj = 0; bj < 2; ++bj)
; #pragma unroll
;                     for (int n = 0; n < 2; ++n) { const int col = u.pn * 256 + bj * 128 + wc * 32 + 8 * fq + 4 * n;
;                         const f32x4 xv = *(const f32x4*)(xin + col), gv = *(const f32x4*)(gt + col);
;                         const f32x4 xn = xv + (gv * coef) * acc[ai][bj][m][n]; acc[ai][bj][m][n] = xn;
;                         if (MODE == 0) *(f32x4*)(X + (size_t)row * D + col) = xn;
;                         sacc += (xn[0] * xn[0] + xn[1] * xn[1]) + (xn[2] * xn[2] + xn[3] * xn[3]); }
;                 asm volatile("" : "+v"(zoff) : "v"(sacc));
;                 sacc += shfl_xor_l(sacc, 16); sacc += shfl_xor_l(sacc, 32);
;                 ss[ai][m] = sacc; __builtin_amdgcn_sched_barrier(0); }
;         if (fq == 0) {
; #pragma unroll
;             for (int ai = 0; ai < 2; ++ai)
; #pragma unroll
;                 for (int m = 0; m < 4; ++m) sred[wc * 256 + ai * 128 + wr * 64 + m * 16 + fr] = ss[ai][m]; }
	v_pk_fma_f32 v[26:27], v[26:27], v[178:179], v[222:223]
	v_pk_fma_f32 v[24:25], v[24:25], v[176:177], v[220:221]
	global_store_dwordx4 v[184:185], v[24:27], off offset:512
	v_pk_mul_f32 v[186:187], v[38:39], v[38:39]
	v_pk_mul_f32 v[178:179], v[210:211], 0.5 op_sel_hi:[1,0]
	v_pk_mov_b32 v[190:191], v[188:189], v[186:187] op_sel:[1,0]
	v_mov_b32_e32 v189, v187
	v_pk_add_f32 v[186:187], v[190:191], v[188:189]
	v_pk_mul_f32 v[188:189], v[34:35], v[34:35]
	v_pk_mul_f32 v[190:191], v[32:33], v[32:33]
	v_pk_mul_f32 v[176:177], v[208:209], 0.5 op_sel_hi:[1,0]
	v_pk_mov_b32 v[192:193], v[190:191], v[188:189] op_sel:[1,0]
	v_mov_b32_e32 v191, v189
	v_pk_add_f32 v[188:189], v[192:193], v[190:191]
	v_mul_f32_e32 v190, v25, v25
	v_mul_f32_e32 v192, v27, v27
	v_pk_add_f32 v[186:187], v[186:187], v[186:187] op_sel:[0,1] op_sel_hi:[1,0]
	v_pk_add_f32 v[188:189], v[188:189], v[188:189] op_sel:[0,1] op_sel_hi:[1,0]
	v_pk_fma_f32 v[190:191], v[24:25], v[24:25], v[190:191] op_sel_hi:[1,1,0]
	v_pk_fma_f32 v[192:193], v[26:27], v[26:27], v[192:193] op_sel_hi:[1,1,0]
	s_waitcnt vmcnt(3)
	v_pk_fma_f32 v[18:19], v[18:19], v[178:179], v[226:227]
	v_pk_fma_f32 v[16:17], v[16:17], v[176:177], v[224:225]
	v_mul_f32_e32 v191, v18, v18
	v_mul_f32_e32 v187, v16, v16
	v_mul_f32_e32 v189, v17, v17
	v_mul_f32_e32 v193, v19, v19
	v_pk_add_f32 v[176:177], v[186:187], v[188:189]
	v_pk_add_f32 v[178:179], v[190:191], v[192:193]
	global_store_dwordx4 v[184:185], v[16:19], off offset:528
	v_pk_add_f32 v[176:177], v[176:177], v[178:179]
	v_mov_b32_e32 v178, v166
	v_add_f32_e32 v176, v176, v177
	s_nop 0
	v_lshlrev_b32_e32 v177, 2, v194
	v_xor_b32_e32 v177, 64, v177
	ds_bpermute_b32 v177, v177, v176
	v_lshlrev_b32_e32 v178, 2, v178
	s_waitcnt lgkmcnt(0)
	v_add_f32_e32 v176, v176, v177
	v_xor_b32_e32 v177, 0x80, v178
	ds_bpermute_b32 v177, v177, v176
	v_add3_u32 v178, v132, v133, s66
	v_ashrrev_i32_e32 v179, 31, v178
	v_lshlrev_b64 v[186:187], 12, v[178:179]
	v_lshl_add_u64 v[182:183], s[26:27], 0, v[186:187]
	v_lshl_add_u64 v[188:189], v[182:183], 0, v[128:129]
	global_load_dwordx4 v[212:215], v[188:189], off
	global_load_dwordx4 v[216:219], v[188:189], off offset:16
	global_load_dwordx4 v[220:223], v[188:189], off offset:512
	global_load_dwordx4 v[224:227], v[188:189], off offset:528
	v_lshl_add_u64 v[186:187], s[14:15], 0, v[186:187]
	v_lshl_add_u64 v[186:187], v[186:187], 0, v[128:129]
	v_mov_b32_e32 v194, v166
	v_pk_mul_f32 v[180:181], v[198:199], 0.5 op_sel_hi:[1,0]
	v_pk_mul_f32 v[178:179], v[196:197], 0.5 op_sel_hi:[1,0]
	s_waitcnt vmcnt(3)
	v_pk_fma_f32 v[14:15], v[14:15], v[180:181], v[214:215]
	v_pk_fma_f32 v[12:13], v[12:13], v[178:179], v[212:213]
	global_store_dwordx4 v[186:187], v[12:15], off
	v_pk_mul_f32 v[180:181], v[202:203], 0.5 op_sel_hi:[1,0]
	v_pk_mul_f32 v[178:179], v[200:201], 0.5 op_sel_hi:[1,0]
	s_waitcnt vmcnt(3)
	v_pk_fma_f32 v[10:11], v[10:11], v[180:181], v[218:219]
	v_pk_fma_f32 v[8:9], v[8:9], v[178:179], v[216:217]
	global_store_dwordx4 v[186:187], v[8:11], off offset:16
	v_pk_mul_f32 v[180:181], v[206:207], 0.5 op_sel_hi:[1,0]
	v_pk_mul_f32 v[178:179], v[204:205], 0.5 op_sel_hi:[1,0]
	s_waitcnt vmcnt(3)
	v_pk_fma_f32 v[6:7], v[6:7], v[180:181], v[222:223]
	v_pk_fma_f32 v[4:5], v[4:5], v[178:179], v[220:221]
	global_store_dwordx4 v[186:187], v[4:7], off offset:512
	v_pk_mul_f32 v[130:131], v[14:15], v[14:15]
	v_pk_mul_f32 v[188:189], v[12:13], v[12:13]
	v_mul_f32_e32 v132, v5, v5
	v_pk_mov_b32 v[190:191], v[188:189], v[130:131] op_sel:[1,0]
	v_mov_b32_e32 v189, v131
	v_pk_add_f32 v[130:131], v[190:191], v[188:189]
	v_pk_mul_f32 v[188:189], v[10:11], v[10:11]
	v_pk_mul_f32 v[190:191], v[8:9], v[8:9]
	v_pk_add_f32 v[130:131], v[130:131], v[130:131] op_sel:[0,1] op_sel_hi:[1,0]
	v_pk_mov_b32 v[192:193], v[190:191], v[188:189] op_sel:[1,0]
	v_mov_b32_e32 v191, v189
	v_pk_add_f32 v[188:189], v[192:193], v[190:191]
	v_mul_f32_e32 v190, v7, v7
	v_pk_add_f32 v[188:189], v[188:189], v[188:189] op_sel:[0,1] op_sel_hi:[1,0]
	v_pk_fma_f32 v[192:193], v[4:5], v[4:5], v[132:133] op_sel_hi:[1,1,0]
	v_pk_fma_f32 v[190:191], v[6:7], v[6:7], v[190:191] op_sel_hi:[1,1,0]
	v_mov_b32_e32 v132, v166
	v_pk_mul_f32 v[180:181], v[210:211], 0.5 op_sel_hi:[1,0]
	v_pk_mul_f32 v[178:179], v[208:209], 0.5 op_sel_hi:[1,0]
	s_waitcnt vmcnt(3)
	v_pk_fma_f32 v[2:3], v[2:3], v[180:181], v[226:227]
	v_pk_fma_f32 v[0:1], v[0:1], v[178:179], v[224:225]
	v_mul_f32_e32 v193, v2, v2
	v_mul_f32_e32 v131, v0, v0
	v_mul_f32_e32 v189, v1, v1
	v_mul_f32_e32 v191, v3, v3
	v_pk_add_f32 v[130:131], v[130:131], v[188:189]
	v_pk_add_f32 v[178:179], v[192:193], v[190:191]
	global_store_dwordx4 v[186:187], v[0:3], off offset:528
	v_pk_add_f32 v[130:131], v[130:131], v[178:179]
	s_nop 0
	v_add_f32_e32 v130, v130, v131
	s_nop 0
	v_lshlrev_b32_e32 v131, 2, v194
	v_xor_b32_e32 v131, 64, v131
	ds_bpermute_b32 v131, v131, v130
	v_lshlrev_b32_e32 v132, 2, v132
	s_waitcnt lgkmcnt(0)
	v_add_f32_e32 v130, v130, v131
	v_xor_b32_e32 v131, 0x80, v132
	ds_bpermute_b32 v131, v131, v130
	v_cmp_eq_u32_e32 vcc, 0, v135
	s_and_saveexec_b64 s[4:5], vcc
	s_cbranch_execz .LBB0_578
	v_add_f32_e32 v157, v157, v158
	v_add_f32_e32 v153, v153, v156
	s_waitcnt lgkmcnt(0)
	v_add_f32_e32 v130, v130, v131
	v_lshl_add_u32 v131, v134, 2, s60
	v_add_f32_e32 v132, v176, v177
	v_add_f32_e32 v133, v174, v175
	v_add_f32_e32 v163, v163, v173
	v_add_f32_e32 v161, v161, v162
	v_add_f32_e32 v159, v159, v160
	ds_write2_b32 v131, v153, v157 offset1:16
	ds_write2_b32 v131, v159, v161 offset0:32 offset1:48
	ds_write2_b32 v131, v163, v133 offset0:128 offset1:144
	ds_write2_b32 v131, v132, v130 offset0:160 offset1:176

; #define RG_RAW_LOAD(tile_) do { _Pragma("unroll") for (int i = 0; i < 5; ++i) { const int q = tid + 512 * i, row = q >> 4, c16 = q & 15, tl = (tile_) * 128 - 3 + row; \
;         pre[i] = (q < 131 * 16 && tl >= 0) ? *(const u32x4*)(XR + ((size_t)b * SEQ + tl) * D + cb0 + c16 * 8) : (u32x4){0u, 0u, 0u, 0u}; } } while (0)
; __device__ __forceinline__ void rglru_task(const Params& P, LAS unsigned char* lds, int b, int n, int qd, int tid, int t0, int t1) {
;     ...
;     const int ntiles = t1;
;     for (int tile = t0; tile < ntiles; ++tile) {
;         const int row0 = prompt ? b * SEQ + tile * 128 : MPR;
;         if (prompt && tile + 1 < ntiles) RG_RAW_LOAD(tile + 1);
.LBB0_1296:
	s_or_b64 exec, exec, s[4:5]
	s_add_i32 s61, s61, 1
	s_cmp_eq_u32 s61, 7
	s_cbranch_scc1 .LBB0_1407
.LBB0_1297:
	s_lshl_b32 s64, s61, 7
	s_cmp_lt_u32 s61, 6
	s_cselect_b64 s[4:5], -1, 0
	s_and_b64 s[68:69], s[58:59], s[4:5]
	s_andn2_b64 vcc, exec, s[68:69]
	s_cbranch_vccnz .LBB0_1309
	s_or_b32 s6, s64, 0x7d
	v_add_u32_e32 v0, s6, v149
	s_waitcnt vmcnt(0)
	v_mov_b32_e32 v50, v68
	v_mov_b32_e32 v51, v68
	v_cmp_lt_i32_e32 vcc, -1, v0
	v_mov_b32_e32 v48, v68
	v_mov_b32_e32 v49, v68
	v_mov_b64_e32 v[54:55], v[50:51]
	s_and_b64 s[52:53], s[10:11], vcc
	v_mov_b64_e32 v[52:53], v[48:49]
	s_and_saveexec_b64 s[4:5], s[52:53]
	s_cbranch_execz .LBB0_1300
	v_mov_b32_e32 v1, v68
	v_lshlrev_b64 v[0:1], 11, v[0:1]
	v_lshl_add_u64 v[0:1], v[74:75], 0, v[0:1]
	global_load_dwordx4 v[52:55], v[0:1], off

; #define RG_RAW_LOAD(tile_) do { _Pragma("unroll") for (int i = 0; i < 5; ++i) { const int q = tid + 512 * i, row = q >> 4, c16 = q & 15, tl = (tile_) * 128 - 3 + row; \
;         pre[i] = (q < 131 * 16 && tl >= 0) ? *(const u32x4*)(XR + ((size_t)b * SEQ + tl) * D + cb0 + c16 * 8) : (u32x4){0u, 0u, 0u, 0u}; } } while (0)
; #define RG_RAW_STORE() do { _Pragma("unroll") for (int i = 0; i < 5; ++i) { const int q = tid + 512 * i; if (q < 131 * 16) *(LAS u32x4*)(rawt + (q >> 4) * 136 + (q & 15) * 8) = pre[i]; } } while (0)
; __device__ __forceinline__ void rglru_task(const Params& P, LAS unsigned char* lds, int b, int n, int qd, int tid, int t0, int t1) {
;     ...
;     if (prompt) { RG_RAW_LOAD(t0); RG_RAW_STORE(); }
.LBB0_1634:
	s_or_b64 exec, exec, s[12:13]
	s_lshl_b64 s[8:9], s[6:7], 22
	s_add_u32 s8, s10, s8
	s_addc_u32 s9, s11, s9
	s_lshl_b32 s10, s18, 1
	v_lshlrev_b32_e32 v2, 3, v0
	s_add_u32 s8, s8, s10
	v_and_b32_e32 v2, 0x78, v2
	s_addc_u32 s9, s9, 0
	v_lshlrev_b32_e32 v48, 1, v2
	v_lshl_add_u64 v[4:5], s[8:9], 0, v[48:49]
	s_mov_b64 s[8:9], 0x5040000
	v_lshl_add_u64 v[74:75], v[4:5], 0, s[8:9]
	v_ashrrev_i32_e32 v79, 4, v0
	s_movk_i32 s8, 0x830
	s_movk_i32 s12, 0xfc82
	v_cmp_gt_i32_e64 s[8:9], s8, v0
	v_cmp_lt_i32_e64 s[10:11], s12, v79
	s_and_b64 s[14:15], s[8:9], s[10:11]
	v_mov_b32_e32 v48, v49
	v_mov_b32_e32 v50, v49
	v_mov_b32_e32 v51, v49
	s_and_saveexec_b64 s[10:11], s[14:15]
	s_cbranch_execz .LBB0_1636
	v_add_u32_e32 v4, 0x37d, v79
	v_mov_b32_e32 v5, 0
	v_lshlrev_b64 v[4:5], 11, v[4:5]
	v_lshl_add_u64 v[4:5], v[74:75], 0, v[4:5]
	global_load_dwordx4 v[48:51], v[4:5], off
.LBB0_1636:
	s_or_b64 exec, exec, s[10:11]
	v_add_u32_e32 v3, 0x200, v0
	v_mov_b32_e32 v56, 0
	v_ashrrev_i32_e32 v80, 4, v3
	s_movk_i32 s10, 0x630
	v_mov_b32_e32 v57, v56
	v_cmp_gt_i32_e64 s[10:11], s10, v0
	v_cmp_lt_i32_e64 s[12:13], s12, v80
	v_mov_b32_e32 v58, v56
	v_mov_b32_e32 v59, v56
	v_mov_b64_e32 v[52:53], v[56:57]
	s_and_b64 s[14:15], s[10:11], s[12:13]
	v_mov_b64_e32 v[54:55], v[58:59]
	s_and_saveexec_b64 s[12:13], s[14:15]
	s_cbranch_execz .LBB0_1638
	v_add_u32_e32 v4, 0x37d, v80
	v_mov_b32_e32 v5, v56
	v_lshlrev_b64 v[4:5], 11, v[4:5]
	v_lshl_add_u64 v[4:5], v[74:75], 0, v[4:5]
	global_load_dwordx4 v[52:55], v[4:5], off
.LBB0_1638:
	s_or_b64 exec, exec, s[12:13]
	v_add_u32_e32 v3, 0x400, v0
	v_ashrrev_i32_e32 v81, 4, v3
	s_movk_i32 s12, 0x430
	s_movk_i32 s16, 0xfc82
	v_cmp_gt_i32_e64 s[12:13], s12, v0
	v_cmp_lt_i32_e64 s[14:15], s16, v81
	s_and_b64 s[18:19], s[12:13], s[14:15]
	s_and_saveexec_b64 s[14:15], s[18:19]
	s_cbranch_execz .LBB0_1640
	v_add_u32_e32 v4, 0x37d, v81
	v_mov_b32_e32 v5, 0
	v_lshlrev_b64 v[4:5], 11, v[4:5]
	v_lshl_add_u64 v[4:5], v[74:75], 0, v[4:5]
	global_load_dwordx4 v[56:59], v[4:5], off
.LBB0_1640:
	s_or_b64 exec, exec, s[14:15]
	v_add_u32_e32 v3, 0x600, v0
	v_mov_b32_e32 v64, 0
	v_ashrrev_i32_e32 v82, 4, v3
	s_movk_i32 s14, 0x230
	v_mov_b32_e32 v65, v64
	v_cmp_gt_i32_e64 s[14:15], s14, v0
	v_cmp_lt_i32_e64 s[16:17], s16, v82
	v_mov_b32_e32 v66, v64
	v_mov_b32_e32 v67, v64
	v_mov_b64_e32 v[60:61], v[64:65]
	s_and_b64 s[18:19], s[14:15], s[16:17]
	v_mov_b64_e32 v[62:63], v[66:67]
	s_and_saveexec_b64 s[16:17], s[18:19]
	s_cbranch_execz .LBB0_1642
	v_add_u32_e32 v4, 0x37d, v82
	v_mov_b32_e32 v5, 0
	v_lshlrev_b64 v[4:5], 11, v[4:5]
	v_lshl_add_u64 v[4:5], v[74:75], 0, v[4:5]
	global_load_dwordx4 v[60:63], v[4:5], off
.LBB0_1642:
	s_or_b64 exec, exec, s[16:17]
	v_add_u32_e32 v3, 0x800, v0
	v_ashrrev_i32_e32 v83, 4, v3
	s_movk_i32 s18, 0xfc82
	v_cmp_gt_i32_e64 s[16:17], 48, v0
	v_cmp_lt_i32_e64 s[18:19], s18, v83
	s_and_b64 s[20:21], s[16:17], s[18:19]
	v_mov_b32_e32 v65, 0
	v_mov_b32_e32 v66, 0
	v_mov_b32_e32 v67, 0
	s_and_saveexec_b64 s[18:19], s[20:21]
	s_cbranch_execz .LBB0_1644
	v_add_u32_e32 v4, 0x37d, v83
	v_mov_b32_e32 v5, 0
	v_lshlrev_b64 v[4:5], 11, v[4:5]
	v_lshl_add_u64 v[4:5], v[74:75], 0, v[4:5]
	global_load_dwordx4 v[64:67], v[4:5], off

; __device__ __forceinline__ float softplus_f(float x) { return x > 20.f ? x : log1pf(__expf(x)); }
; __device__ __forceinline__ unsigned char* karg_ws() { return *(volatile KAS ucptr_t*)((const KAS char*)__builtin_amdgcn_kernarg_segment_ptr() + 264); }
; #define INP(k) karg_in(k)
; #define RG_RAW_LOAD(tile_) do { _Pragma("unroll") for (int i = 0; i < 5; ++i) { const int q = tid + 512 * i, row = q >> 4, c16 = q & 15, tl = (tile_) * 128 - 3 + row; \
;         pre[i] = (q < 131 * 16 && tl >= 0) ? *(const u32x4*)(XR + ((size_t)b * SEQ + tl) * D + cb0 + c16 * 8) : (u32x4){0u, 0u, 0u, 0u}; } } while (0)
; #define RG_RAW_STORE() do { _Pragma("unroll") for (int i = 0; i < 5; ++i) { const int q = tid + 512 * i; if (q < 131 * 16) *(LAS u32x4*)(rawt + (q >> 4) * 136 + (q & 15) * 8) = pre[i]; } } while (0)
; #define lane opq(lane_now())
; #define tid opq((wave << 6) | lane_now())
; __device__ __forceinline__ void rglru_task(const Params& P, LAS unsigned char* lds, int b, int n, int qd, int tid, int t0, int t1) {
;     ...
;     bf16* XR = (bf16*)(karg_ws() + WS_Z); bf16* GR = (bf16*)(karg_ws() + WS_Z + ZB);
;     const bf16* WRG = (const bf16*)(karg_ws() + WS_WRG);
;     const int cb0 = n * 128, oc0 = cb0 + qd * 32;
;     const bool prompt = b >= 0;
;     for (int i = tid; i < 640; i += NTHR) cw[i] = i < 512 ? INP(15)[(size_t)(i >> 7) * D + cb0 + (i & 127)] : INP(16)[cb0 + (i - 512)];
;     if (tid < 32) hc[tid] = t0 > 0 ? ((const float*)(karg_ws() + WS_HCARRY))[(size_t)b * D + oc0 + tid] : 0.f;
;     const int tb = wave & 3, cbk = wave >> 2;
;     bf16x8 Bf[8];
;     { const bf16* wrow = WRG + (size_t)(n * 256 + cbk * 128 + qd * 32 + (lane & 31)) * 128 + (lane >> 5) * 8;
; #pragma unroll
;       for (int ks = 0; ks < 8; ++ks) Bf[ks] = *(const bf16x8*)(wrow + ks * 16); }
;     const float gbias = INP(cbk ? 20 : 18)[oc0 + (lane & 31)];
;     const int ch = tid & 31, seg = tid >> 5;
;     const float sp = softplus_f(-INP(21)[oc0 + ch]);
;     float hlast = 0.f;
;     u32x4 pre[5];
;     ...
;     if (prompt) { RG_RAW_LOAD(t0); RG_RAW_STORE(); }
;     __syncthreads();
;     const int ntiles = t1;
;     for (int tile = t0; tile < ntiles; ++tile) {
.LBB0_1651:
	s_or_b64 exec, exec, s[18:19]
	v_lshrrev_b32_e32 v4, 1, v0
	v_and_b32_e32 v10, 0x60, v4
	s_add_i32 s20, 0, 0xc800
	s_lshl_b32 s65, s6, 11
	v_or_b32_e32 v4, v10, v72
	s_add_i32 s57, 0, 0x10800
	v_mov_b32_e32 v5, s20
	s_add_i32 s58, 0, 0x14800
	s_add_i32 s59, 0, 0x15000
	s_add_i32 s63, 0, 0x15800
	s_lshl_b32 s20, s64, 1
	v_mul_u32_u24_e32 v11, 0x110, v4
	v_mov_b32_e32 v4, s57
	v_mov_b32_e32 v68, 0
	s_add_u32 s4, s4, s20
	v_cndmask_b32_e32 v12, v4, v5, vcc
	s_addc_u32 s5, s5, 0
	v_lshlrev_b32_e32 v4, 1, v72
	v_mov_b32_e32 v5, v68
	v_lshlrev_b32_e32 v13, 2, v72
	v_lshl_add_u64 v[4:5], s[4:5], 0, v[4:5]
	s_mov_b64 s[4:5], 0x7080000
	v_lshl_add_u64 v[76:77], v[4:5], 0, s[4:5]
	v_or_b32_e32 v4, 0x80, v13
	v_add_u32_e32 v89, s58, v4
	v_add_u32_e32 v90, s59, v4
	v_or_b32_e32 v4, 0x100, v13
	v_add_u32_e32 v91, s58, v4
	v_add_u32_e32 v92, s59, v4
	v_or_b32_e32 v4, 0x180, v13
	v_add_u32_e32 v93, s58, v4
	v_add_u32_e32 v94, s59, v4
	v_or_b32_e32 v4, 0x200, v13
	v_add_u32_e32 v95, s58, v4
	v_add_u32_e32 v96, s59, v4
	v_or_b32_e32 v4, 0x280, v13
	v_add_u32_e32 v97, s58, v4
	v_add_u32_e32 v98, s59, v4
	v_or_b32_e32 v4, 0x300, v13
	v_add_u32_e32 v99, s58, v4
	v_add_u32_e32 v100, s59, v4
	v_or_b32_e32 v4, 0x380, v13
	v_add_u32_e32 v101, s58, v4
	v_add_u32_e32 v102, s59, v4
	v_or_b32_e32 v4, 0x400, v13
	v_add_u32_e32 v103, s58, v4
	v_add_u32_e32 v104, s59, v4
	v_or_b32_e32 v4, 0x480, v13
	v_add_u32_e32 v105, s58, v4
	v_add_u32_e32 v106, s59, v4
	v_or_b32_e32 v4, 0x500, v13
	v_add_u32_e32 v107, s58, v4
	v_add_u32_e32 v108, s59, v4
	v_or_b32_e32 v4, 0x580, v13
	v_add_u32_e32 v109, s58, v4
	v_add_u32_e32 v110, s59, v4
	v_or_b32_e32 v4, 0x600, v13
	v_ashrrev_i32_e32 v6, 5, v0
	v_add_u32_e32 v111, s58, v4
	v_add_u32_e32 v112, s59, v4
	v_or_b32_e32 v4, 0x680, v13
	v_lshlrev_b32_e32 v85, 3, v6
	v_add_u32_e32 v113, s58, v4
	v_add_u32_e32 v114, s59, v4
	v_or_b32_e32 v4, 0x700, v13
	v_add_u32_e32 v115, s58, v4
	v_add_u32_e32 v116, s59, v4
	v_or_b32_e32 v119, 1, v85
	v_lshl_or_b32 v4, v6, 10, v13
	v_or_b32_e32 v120, 2, v85
	v_add_u32_e32 v126, 0, v4
	v_add_u32_e32 v127, s57, v4
	v_lshl_or_b32 v4, v119, 7, v13
	v_or_b32_e32 v121, 3, v85
	v_add_u32_e32 v128, 0, v4
	v_add_u32_e32 v129, s57, v4
	v_lshl_or_b32 v4, v120, 7, v13
	v_or_b32_e32 v122, 4, v85
	v_add_u32_e32 v130, 0, v4
	v_add_u32_e32 v131, s57, v4
	v_lshl_or_b32 v4, v121, 7, v13
	v_or_b32_e32 v123, 5, v85
	v_add_u32_e32 v132, 0, v4
	v_add_u32_e32 v133, s57, v4
	v_lshl_or_b32 v4, v122, 7, v13
	v_or_b32_e32 v124, 6, v85
	v_add_u32_e32 v134, 0, v4
	v_add_u32_e32 v135, s57, v4
	v_lshl_or_b32 v4, v123, 7, v13
	v_ashrrev_i32_e32 v7, 2, v0
	v_and_b32_e32 v8, 3, v0
	v_lshlrev_b32_e32 v0, 2, v0
	v_or_b32_e32 v125, 7, v85
	v_add_u32_e32 v136, 0, v4
	v_add_u32_e32 v137, s57, v4
	v_lshl_or_b32 v4, v124, 7, v13
	v_add_u32_e32 v86, s58, v0
	v_add_u32_e32 v87, s59, v0
	v_lshlrev_b32_e32 v0, 9, v1
	v_add_u32_e32 v138, 0, v4
	v_add_u32_e32 v139, s57, v4
	v_lshl_or_b32 v4, v125, 7, v13
	v_lshl_add_u32 v3, v3, 1, 0
	v_mul_lo_u32 v9, v7, s54
	v_cmp_eq_u32_e64 s[20:21], 15, v6
	v_lshlrev_b32_e32 v1, 7, v10
	v_add3_u32 v0, v12, v13, v0
	v_cmp_lt_i32_e64 s[22:23], 0, v6
	v_cmp_lt_i32_e64 s[24:25], 1, v6
	v_cmp_lt_i32_e64 s[26:27], 2, v6
	v_cmp_lt_i32_e64 s[28:29], 3, v6
	v_cmp_lt_i32_e64 s[30:31], 4, v6
	v_cmp_lt_i32_e64 s[34:35], 5, v6
	v_cmp_lt_i32_e64 s[36:37], 6, v6
	v_cmp_lt_i32_e64 s[38:39], 7, v6
	v_cmp_lt_i32_e64 s[40:41], 8, v6
	v_cmp_lt_i32_e64 s[42:43], 9, v6
	v_cmp_lt_i32_e64 s[44:45], 10, v6
	v_cmp_lt_i32_e64 s[46:47], 11, v6
	v_cmp_lt_i32_e64 s[48:49], 12, v6
	v_cmp_lt_i32_e64 s[50:51], 13, v6
	v_cmp_lt_i32_e64 s[52:53], 14, v6
	v_add_u32_e32 v140, 0, v4
	v_add_u32_e32 v141, s57, v4
	v_mul_lo_u32 v4, v79, s54
	v_mul_lo_u32 v5, v80, s54
	v_mul_lo_u32 v6, v81, s54
	v_mul_lo_u32 v10, v82, s54
	v_mov_b32_e32 v12, 0x8800
	v_cmp_eq_u32_e64 s[18:19], s3, v8
	v_add_u32_e32 v88, s63, v13
	s_mov_b32 s68, 7
	v_add_u32_e32 v117, s59, v13
	v_add_u32_e32 v118, s58, v13
	v_lshlrev_b32_e32 v142, 7, v8
	v_lshl_add_u32 v143, v7, 7, v12
	v_lshl_add_u32 v144, v8, 6, v9
	v_add_u32_e32 v145, v3, v11
	v_add_u32_e32 v146, v0, v1
	v_mov_b32_e32 v147, 0x3c088889
	s_mov_b32 s66, 0xbe99999a
	v_add_u32_e32 v148, v2, v4
	v_add_u32_e32 v149, v2, v5
	v_add_u32_e32 v150, v2, v6
	v_add_u32_e32 v151, v2, v10
	s_waitcnt lgkmcnt(0)
	s_barrier
	s_branch .LBB0_1653

; #define RG_RAW_LOAD(tile_) do { _Pragma("unroll") for (int i = 0; i < 5; ++i) { const int q = tid + 512 * i, row = q >> 4, c16 = q & 15, tl = (tile_) * 128 - 3 + row; \
;         pre[i] = (q < 131 * 16 && tl >= 0) ? *(const u32x4*)(XR + ((size_t)b * SEQ + tl) * D + cb0 + c16 * 8) : (u32x4){0u, 0u, 0u, 0u}; } } while (0)
; #define RG_RAW_STORE() do { _Pragma("unroll") for (int i = 0; i < 5; ++i) { const int q = tid + 512 * i; if (q < 131 * 16) *(LAS u32x4*)(rawt + (q >> 4) * 136 + (q & 15) * 8) = pre[i]; } } while (0)
; __device__ __forceinline__ void rglru_task(const Params& P, LAS unsigned char* lds, int b, int n, int qd, int tid, int t0, int t1) {
;     ...
;     if (prompt) { RG_RAW_LOAD(t0); RG_RAW_STORE(); }
.LBB0_1706:
	s_or_b64 exec, exec, s[14:15]
	s_lshl_b32 s7, s56, 17
	s_add_u32 s7, s10, s7
	s_addc_u32 s10, s11, 0
	s_lshl_b64 s[8:9], s[12:13], 1
	v_lshlrev_b32_e32 v2, 3, v0
	s_add_u32 s8, s7, s8
	v_and_b32_e32 v2, 0x78, v2
	s_addc_u32 s9, s10, s9
	v_lshlrev_b32_e32 v48, 1, v2
	v_lshl_add_u64 v[4:5], s[8:9], 0, v[48:49]
	s_mov_b64 s[8:9], 0x5040000
	s_movk_i32 s7, 0x830
	v_lshl_add_u64 v[74:75], v[4:5], 0, s[8:9]
	v_ashrrev_i32_e32 v79, 4, v0
	v_cmp_gt_i32_e64 s[8:9], s7, v0
	s_movk_i32 s7, 0xfc82
	v_cmp_lt_i32_e64 s[10:11], s7, v79
	s_and_b64 s[12:13], s[8:9], s[10:11]
	v_mov_b32_e32 v48, v49
	v_mov_b32_e32 v50, v49
	v_mov_b32_e32 v51, v49
	s_and_saveexec_b64 s[10:11], s[12:13]
	s_cbranch_execz .LBB0_1708
	v_add_u32_e32 v4, 0x37d, v79
	v_mov_b32_e32 v5, 0
	v_lshlrev_b64 v[4:5], 11, v[4:5]
	v_lshl_add_u64 v[4:5], v[74:75], 0, v[4:5]
	global_load_dwordx4 v[48:51], v[4:5], off
.LBB0_1708:
	s_or_b64 exec, exec, s[10:11]
	v_add_u32_e32 v3, 0x200, v0
	v_mov_b32_e32 v56, 0
	v_ashrrev_i32_e32 v80, 4, v3
	s_movk_i32 s10, 0x630
	v_mov_b32_e32 v57, v56
	v_cmp_gt_i32_e64 s[10:11], s10, v0
	v_cmp_lt_i32_e64 s[12:13], s7, v80
	v_mov_b32_e32 v58, v56
	v_mov_b32_e32 v59, v56
	v_mov_b64_e32 v[52:53], v[56:57]
	s_and_b64 s[14:15], s[10:11], s[12:13]
	v_mov_b64_e32 v[54:55], v[58:59]
	s_and_saveexec_b64 s[12:13], s[14:15]
	s_cbranch_execz .LBB0_1710
	v_add_u32_e32 v4, 0x37d, v80
	v_mov_b32_e32 v5, v56
	v_lshlrev_b64 v[4:5], 11, v[4:5]
	v_lshl_add_u64 v[4:5], v[74:75], 0, v[4:5]
	global_load_dwordx4 v[52:55], v[4:5], off
.LBB0_1710:
	s_or_b64 exec, exec, s[12:13]
	v_add_u32_e32 v3, 0x400, v0
	s_movk_i32 s7, 0x430
	v_ashrrev_i32_e32 v81, 4, v3
	v_cmp_gt_i32_e64 s[12:13], s7, v0
	s_movk_i32 s7, 0xfc82
	v_cmp_lt_i32_e64 s[14:15], s7, v81
	s_and_b64 s[16:17], s[12:13], s[14:15]
	s_and_saveexec_b64 s[14:15], s[16:17]
	s_cbranch_execz .LBB0_1712
	v_add_u32_e32 v4, 0x37d, v81
	v_mov_b32_e32 v5, 0
	v_lshlrev_b64 v[4:5], 11, v[4:5]
	v_lshl_add_u64 v[4:5], v[74:75], 0, v[4:5]
	global_load_dwordx4 v[56:59], v[4:5], off
.LBB0_1712:
	s_or_b64 exec, exec, s[14:15]
	v_add_u32_e32 v3, 0x600, v0
	v_mov_b32_e32 v64, 0
	v_ashrrev_i32_e32 v82, 4, v3
	s_movk_i32 s14, 0x230
	v_mov_b32_e32 v65, v64
	v_cmp_gt_i32_e64 s[14:15], s14, v0
	v_cmp_lt_i32_e64 s[16:17], s7, v82
	v_mov_b32_e32 v66, v64
	v_mov_b32_e32 v67, v64
	v_mov_b64_e32 v[60:61], v[64:65]
	s_and_b64 s[18:19], s[14:15], s[16:17]
	v_mov_b64_e32 v[62:63], v[66:67]
	s_and_saveexec_b64 s[16:17], s[18:19]
	s_cbranch_execz .LBB0_1714
	v_add_u32_e32 v4, 0x37d, v82
	v_mov_b32_e32 v5, 0
	v_lshlrev_b64 v[4:5], 11, v[4:5]
	v_lshl_add_u64 v[4:5], v[74:75], 0, v[4:5]
	global_load_dwordx4 v[60:63], v[4:5], off

; __device__ __forceinline__ float softplus_f(float x) { return x > 20.f ? x : log1pf(__expf(x)); }
; __device__ __forceinline__ unsigned char* karg_ws() { return *(volatile KAS ucptr_t*)((const KAS char*)__builtin_amdgcn_kernarg_segment_ptr() + 264); }
; #define INP(k) karg_in(k)
; #define RG_RAW_LOAD(tile_) do { _Pragma("unroll") for (int i = 0; i < 5; ++i) { const int q = tid + 512 * i, row = q >> 4, c16 = q & 15, tl = (tile_) * 128 - 3 + row; \
;         pre[i] = (q < 131 * 16 && tl >= 0) ? *(const u32x4*)(XR + ((size_t)b * SEQ + tl) * D + cb0 + c16 * 8) : (u32x4){0u, 0u, 0u, 0u}; } } while (0)
; #define RG_RAW_STORE() do { _Pragma("unroll") for (int i = 0; i < 5; ++i) { const int q = tid + 512 * i; if (q < 131 * 16) *(LAS u32x4*)(rawt + (q >> 4) * 136 + (q & 15) * 8) = pre[i]; } } while (0)
; #define lane opq(lane_now())
; #define tid opq((wave << 6) | lane_now())
; __device__ __forceinline__ void rglru_task(const Params& P, LAS unsigned char* lds, int b, int n, int qd, int tid, int t0, int t1) {
;     ...
;     bf16* XR = (bf16*)(karg_ws() + WS_Z); bf16* GR = (bf16*)(karg_ws() + WS_Z + ZB);
;     const bf16* WRG = (const bf16*)(karg_ws() + WS_WRG);
;     const int cb0 = n * 128, oc0 = cb0 + qd * 32;
;     const bool prompt = b >= 0;
;     for (int i = tid; i < 640; i += NTHR) cw[i] = i < 512 ? INP(15)[(size_t)(i >> 7) * D + cb0 + (i & 127)] : INP(16)[cb0 + (i - 512)];
;     if (tid < 32) hc[tid] = t0 > 0 ? ((const float*)(karg_ws() + WS_HCARRY))[(size_t)b * D + oc0 + tid] : 0.f;
;     const int tb = wave & 3, cbk = wave >> 2;
;     bf16x8 Bf[8];
;     { const bf16* wrow = WRG + (size_t)(n * 256 + cbk * 128 + qd * 32 + (lane & 31)) * 128 + (lane >> 5) * 8;
; #pragma unroll
;       for (int ks = 0; ks < 8; ++ks) Bf[ks] = *(const bf16x8*)(wrow + ks * 16); }
;     const float gbias = INP(cbk ? 20 : 18)[oc0 + (lane & 31)];
;     const int ch = tid & 31, seg = tid >> 5;
;     const float sp = softplus_f(-INP(21)[oc0 + ch]);
;     float hlast = 0.f;
;     u32x4 pre[5];
;     ...
;     if (prompt) { RG_RAW_LOAD(t0); RG_RAW_STORE(); }
;     __syncthreads();
;     const int ntiles = t1;
;     for (int tile = t0; tile < ntiles; ++tile) {
.LBB0_1722:
	s_or_b64 exec, exec, s[18:19]
	v_lshrrev_b32_e32 v4, 1, v0
	s_mov_b32 s7, 0
	v_and_b32_e32 v8, 3, v0
	v_and_b32_e32 v10, 0x60, v4
	s_lshl_b32 s61, s56, 6
	v_cmp_eq_u32_e64 s[18:19], s3, v8
	v_or_b32_e32 v4, v10, v72
	s_add_i32 s3, 0, 0xc800
	s_lshl_b64 s[20:21], s[6:7], 1
	v_mul_u32_u24_e32 v11, 0x110, v4
	v_mov_b32_e32 v4, s57
	v_mov_b32_e32 v5, s3
	v_mov_b32_e32 v68, 0
	s_add_u32 s4, s4, s20
	v_cndmask_b32_e32 v12, v4, v5, vcc
	s_addc_u32 s5, s5, s21
	v_lshlrev_b32_e32 v4, 1, v72
	v_mov_b32_e32 v5, v68
	v_lshlrev_b32_e32 v13, 2, v72
	v_lshl_add_u64 v[4:5], s[4:5], 0, v[4:5]
	s_mov_b64 s[4:5], 0x7080000
	v_lshl_add_u64 v[76:77], v[4:5], 0, s[4:5]
	v_or_b32_e32 v4, 0x80, v13
	v_add_u32_e32 v89, s58, v4
	v_add_u32_e32 v90, s59, v4
	v_or_b32_e32 v4, 0x100, v13
	v_add_u32_e32 v91, s58, v4
	v_add_u32_e32 v92, s59, v4
	v_or_b32_e32 v4, 0x180, v13
	v_add_u32_e32 v93, s58, v4
	v_add_u32_e32 v94, s59, v4
	v_or_b32_e32 v4, 0x200, v13
	v_add_u32_e32 v95, s58, v4
	v_add_u32_e32 v96, s59, v4
	v_or_b32_e32 v4, 0x280, v13
	v_add_u32_e32 v97, s58, v4
	v_add_u32_e32 v98, s59, v4
	v_or_b32_e32 v4, 0x300, v13
	v_add_u32_e32 v99, s58, v4
	v_add_u32_e32 v100, s59, v4
	v_or_b32_e32 v4, 0x380, v13
	v_add_u32_e32 v101, s58, v4
	v_add_u32_e32 v102, s59, v4
	v_or_b32_e32 v4, 0x400, v13
	v_add_u32_e32 v103, s58, v4
	v_add_u32_e32 v104, s59, v4
	v_or_b32_e32 v4, 0x480, v13
	v_add_u32_e32 v105, s58, v4
	v_add_u32_e32 v106, s59, v4
	v_or_b32_e32 v4, 0x500, v13
	v_add_u32_e32 v107, s58, v4
	v_add_u32_e32 v108, s59, v4
	v_or_b32_e32 v4, 0x580, v13
	v_add_u32_e32 v109, s58, v4
	v_add_u32_e32 v110, s59, v4
	v_or_b32_e32 v4, 0x600, v13
	v_ashrrev_i32_e32 v6, 5, v0
	v_add_u32_e32 v111, s58, v4
	v_add_u32_e32 v112, s59, v4
	v_or_b32_e32 v4, 0x680, v13
	v_lshlrev_b32_e32 v85, 3, v6
	v_add_u32_e32 v113, s58, v4
	v_add_u32_e32 v114, s59, v4
	v_or_b32_e32 v4, 0x700, v13
	v_add_u32_e32 v115, s58, v4
	v_add_u32_e32 v116, s59, v4
	v_or_b32_e32 v119, 1, v85
	v_lshl_or_b32 v4, v6, 10, v13
	v_or_b32_e32 v120, 2, v85
	v_add_u32_e32 v126, 0, v4
	v_add_u32_e32 v127, s57, v4
	v_lshl_or_b32 v4, v119, 7, v13
	v_or_b32_e32 v121, 3, v85
	v_add_u32_e32 v128, 0, v4
	v_add_u32_e32 v129, s57, v4
	v_lshl_or_b32 v4, v120, 7, v13
	v_or_b32_e32 v122, 4, v85
	v_add_u32_e32 v130, 0, v4
	v_add_u32_e32 v131, s57, v4
	v_lshl_or_b32 v4, v121, 7, v13
	v_or_b32_e32 v123, 5, v85
	v_add_u32_e32 v132, 0, v4
	v_add_u32_e32 v133, s57, v4
	v_lshl_or_b32 v4, v122, 7, v13
	v_or_b32_e32 v124, 6, v85
	v_add_u32_e32 v134, 0, v4
	v_add_u32_e32 v135, s57, v4
	v_lshl_or_b32 v4, v123, 7, v13
	v_ashrrev_i32_e32 v7, 2, v0
	v_lshlrev_b32_e32 v0, 2, v0
	v_or_b32_e32 v125, 7, v85
	v_add_u32_e32 v136, 0, v4
	v_add_u32_e32 v137, s57, v4
	v_lshl_or_b32 v4, v124, 7, v13
	v_add_u32_e32 v86, s58, v0
	v_add_u32_e32 v87, s59, v0
	v_lshlrev_b32_e32 v0, 9, v1
	v_add_u32_e32 v138, 0, v4
	v_add_u32_e32 v139, s57, v4
	v_lshl_or_b32 v4, v125, 7, v13
	v_lshl_add_u32 v3, v3, 1, 0
	v_mul_lo_u32 v9, v7, s54
	v_cmp_eq_u32_e64 s[20:21], 15, v6
	v_lshlrev_b32_e32 v1, 7, v10
	v_add3_u32 v0, v12, v13, v0
	v_cmp_lt_i32_e64 s[22:23], 0, v6
	v_cmp_lt_i32_e64 s[24:25], 1, v6
	v_cmp_lt_i32_e64 s[26:27], 2, v6
	v_cmp_lt_i32_e64 s[28:29], 3, v6
	v_cmp_lt_i32_e64 s[30:31], 4, v6
	v_cmp_lt_i32_e64 s[34:35], 5, v6
	v_cmp_lt_i32_e64 s[36:37], 6, v6
	v_cmp_lt_i32_e64 s[38:39], 7, v6
	v_cmp_lt_i32_e64 s[40:41], 8, v6
	v_cmp_lt_i32_e64 s[42:43], 9, v6
	v_cmp_lt_i32_e64 s[44:45], 10, v6
	v_cmp_lt_i32_e64 s[46:47], 11, v6
	v_cmp_lt_i32_e64 s[48:49], 12, v6
	v_cmp_lt_i32_e64 s[50:51], 13, v6
	v_cmp_lt_i32_e64 s[52:53], 14, v6
	v_add_u32_e32 v140, 0, v4
	v_add_u32_e32 v141, s57, v4
	v_mul_lo_u32 v4, v79, s54
	v_mul_lo_u32 v5, v80, s54
	v_mul_lo_u32 v6, v81, s54
	v_mul_lo_u32 v10, v82, s54
	v_mov_b32_e32 v12, 0x8800
	v_add_u32_e32 v88, s63, v13
	s_mov_b32 s65, 7
	v_add_u32_e32 v117, s59, v13
	v_add_u32_e32 v118, s58, v13
	v_lshlrev_b32_e32 v142, 7, v8
	v_lshl_add_u32 v143, v7, 7, v12
	v_lshl_add_u32 v144, v8, 6, v9
	v_add_u32_e32 v145, v3, v11
	v_add_u32_e32 v146, v0, v1
	v_mov_b32_e32 v147, 0x3c088889
	s_mov_b32 s3, 0xbe99999a
	v_add_u32_e32 v148, v2, v4
	v_add_u32_e32 v149, v2, v5
	v_add_u32_e32 v150, v2, v6
	v_add_u32_e32 v151, v2, v10
	s_waitcnt lgkmcnt(0)
	s_barrier
	s_branch .LBB0_1724

; #define RG_RAW_LOAD(tile_) do { _Pragma("unroll") for (int i = 0; i < 5; ++i) { const int q = tid + 512 * i, row = q >> 4, c16 = q & 15, tl = (tile_) * 128 - 3 + row; \
;         pre[i] = (q < 131 * 16 && tl >= 0) ? *(const u32x4*)(XR + ((size_t)b * SEQ + tl) * D + cb0 + c16 * 8) : (u32x4){0u, 0u, 0u, 0u}; } } while (0)
; #define RG_RAW_STORE() do { _Pragma("unroll") for (int i = 0; i < 5; ++i) { const int q = tid + 512 * i; if (q < 131 * 16) *(LAS u32x4*)(rawt + (q >> 4) * 136 + (q & 15) * 8) = pre[i]; } } while (0)
; __device__ __forceinline__ void rglru_task(const Params& P, LAS unsigned char* lds, int b, int n, int qd, int tid, int t0, int t1) {
;     ...
;     if (prompt) { RG_RAW_LOAD(t0); RG_RAW_STORE(); }
.LBB0_1879:
	v_add_u32_e32 v4, 0x37d, v83
	v_mov_b32_e32 v5, 0
	v_lshlrev_b64 v[4:5], 11, v[4:5]
	v_lshl_add_u64 v[4:5], v[74:75], 0, v[4:5]
	global_load_dwordx4 v[64:67], v[4:5], off
	s_or_b64 exec, exec, s[18:19]
	v_lshl_add_u32 v2, v2, 1, s62
	s_and_saveexec_b64 s[18:19], s[8:9]
	s_cbranch_execz .LBB0_1716

; __device__ __forceinline__ unsigned pk2(float lo, float hi) { f32x2_t v = {lo, hi}; bf16x2_t b = __builtin_convertvector(v, bf16x2_t); return __builtin_bit_cast(unsigned, b); }
;     __device__ __forceinline__ void operator()(const AccT& acc, const pg8::Unit& u, int wr, int wc, int fr, int fq) const {
; #pragma unroll
;         for (int ai = 0; ai < 2; ++ai)
; #pragma unroll
;             for (int m = 0; m < 4; ++m) { const int row = u.pm * 256 + ai * 128 + wr * 64 + m * 16 + fr; if (row >= M) continue;
; #pragma unroll
;                 for (int bj = 0; bj < 2; ++bj) { const size_t o = (size_t)row * D + u.pn * 256 + bj * 128 + wc * 32 + 8 * fq;
;                     const u32x4 b = *(const u32x4*)(mgb + o);
;                     const f32x4 v0 = acc[ai][bj][m][0], v1 = acc[ai][bj][m][1];
;                     u32x4 w; w.x = pk2(v0[0] * bflo(b.x), v0[1] * bfhi(b.x)); w.y = pk2(v0[2] * bflo(b.y), v0[3] * bfhi(b.y));
;                     w.z = pk2(v1[0] * bflo(b.z), v1[1] * bfhi(b.z)); w.w = pk2(v1[2] * bflo(b.w), v1[3] * bfhi(b.w));
;                     *(u32x4*)(G + o) = w; } }
;     }
.LBB0_1912:
	s_cmp_lg_u32 s7, 0
	s_cselect_b64 s[36:37], -1, 0
	s_lshl_b32 s27, s38, 8
	v_add_u32_e32 v2, s27, v164
	s_and_b64 vcc, exec, s[36:37]
	s_cbranch_vccz .LBB0_1936
	s_lshl_b32 s4, s6, 8
	s_ashr_i32 s5, s4, 31
	s_or_b64 s[4:5], s[4:5], s[82:83]
	v_lshl_add_u64 v[132:133], s[4:5], 0, v[152:153]
	v_cmp_gt_i32_e32 vcc, s50, v2
	s_and_saveexec_b64 s[4:5], vcc
	s_cbranch_execz .LBB0_1915
	v_ashrrev_i32_e32 v3, 31, v2
	v_lshlrev_b64 v[134:135], 10, v[2:3]
	v_lshl_add_u64 v[134:135], v[134:135], 0, v[132:133]
	v_lshlrev_b64 v[138:139], 1, v[134:135]
	v_lshl_add_u64 v[140:141], s[10:11], 0, v[138:139]
	global_load_dwordx4 v[196:199], v[140:141], off
	global_load_dwordx4 v[200:203], v[140:141], off offset:256
	v_lshl_add_u64 v[138:139], s[84:85], 0, v[138:139]
	s_waitcnt vmcnt(1)
	v_lshlrev_b32_e32 v142, 16, v196
	v_and_b32_e32 v143, 0xffff0000, v196
	v_lshlrev_b32_e32 v134, 16, v197
	v_and_b32_e32 v135, 0xffff0000, v197
	v_lshlrev_b32_e32 v176, 16, v198
	v_and_b32_e32 v177, 0xffff0000, v198
	v_lshlrev_b32_e32 v136, 16, v199
	v_and_b32_e32 v137, 0xffff0000, v199
	v_pk_mul_f32 v[142:143], v[128:129], v[142:143]
	v_pk_mul_f32 v[178:179], v[130:131], v[134:135]
	v_pk_mul_f32 v[176:177], v[124:125], v[176:177]
	v_pk_mul_f32 v[180:181], v[126:127], v[136:137]
	v_cvt_pk_bf16_f32 v134, v142, v143
	v_cvt_pk_bf16_f32 v135, v178, v179
	v_cvt_pk_bf16_f32 v136, v176, v177
	v_cvt_pk_bf16_f32 v137, v180, v181
	global_store_dwordx4 v[138:139], v[134:137], off
	s_waitcnt vmcnt(1)
	v_lshlrev_b32_e32 v140, 16, v200
	v_and_b32_e32 v141, 0xffff0000, v200
	v_lshlrev_b32_e32 v134, 16, v201
	v_and_b32_e32 v135, 0xffff0000, v201
	v_lshlrev_b32_e32 v142, 16, v202
	v_and_b32_e32 v143, 0xffff0000, v202
	v_lshlrev_b32_e32 v136, 16, v203
	v_and_b32_e32 v137, 0xffff0000, v203
	v_pk_mul_f32 v[140:141], v[96:97], v[140:141]
	v_pk_mul_f32 v[176:177], v[98:99], v[134:135]
	v_pk_mul_f32 v[142:143], v[92:93], v[142:143]
	v_pk_mul_f32 v[178:179], v[94:95], v[136:137]
	v_cvt_pk_bf16_f32 v134, v140, v141
	v_cvt_pk_bf16_f32 v135, v176, v177
	v_cvt_pk_bf16_f32 v136, v142, v143
	v_cvt_pk_bf16_f32 v137, v178, v179
	global_store_dwordx4 v[138:139], v[134:137], off offset:256
.LBB0_1915:
	s_or_b64 exec, exec, s[4:5]
	s_nop 0
	v_or_b32_e32 v134, 16, v2
	v_cmp_gt_i32_e32 vcc, s50, v134
	s_and_saveexec_b64 s[4:5], vcc
	s_cbranch_execz .LBB0_1917
	v_ashrrev_i32_e32 v135, 31, v134
	v_lshlrev_b64 v[134:135], 10, v[134:135]
	v_lshl_add_u64 v[134:135], v[134:135], 0, v[132:133]
	v_lshlrev_b64 v[138:139], 1, v[134:135]
	v_lshl_add_u64 v[140:141], s[10:11], 0, v[138:139]
	global_load_dwordx4 v[196:199], v[140:141], off
	global_load_dwordx4 v[200:203], v[140:141], off offset:256
	v_lshl_add_u64 v[138:139], s[84:85], 0, v[138:139]
	s_waitcnt vmcnt(1)
	v_lshlrev_b32_e32 v142, 16, v196
	v_and_b32_e32 v143, 0xffff0000, v196
	v_lshlrev_b32_e32 v134, 16, v197
	v_and_b32_e32 v135, 0xffff0000, v197
	v_lshlrev_b32_e32 v176, 16, v198
	v_and_b32_e32 v177, 0xffff0000, v198
	v_lshlrev_b32_e32 v136, 16, v199
	v_and_b32_e32 v137, 0xffff0000, v199
	v_pk_mul_f32 v[142:143], v[120:121], v[142:143]
	v_pk_mul_f32 v[178:179], v[122:123], v[134:135]
	v_pk_mul_f32 v[176:177], v[116:117], v[176:177]
	v_pk_mul_f32 v[180:181], v[118:119], v[136:137]
	v_cvt_pk_bf16_f32 v134, v142, v143
	v_cvt_pk_bf16_f32 v135, v178, v179
	v_cvt_pk_bf16_f32 v136, v176, v177
	v_cvt_pk_bf16_f32 v137, v180, v181
	global_store_dwordx4 v[138:139], v[134:137], off
	s_waitcnt vmcnt(1)
	v_lshlrev_b32_e32 v140, 16, v200
	v_and_b32_e32 v141, 0xffff0000, v200
	v_lshlrev_b32_e32 v134, 16, v201
	v_and_b32_e32 v135, 0xffff0000, v201
	v_lshlrev_b32_e32 v142, 16, v202
	v_and_b32_e32 v143, 0xffff0000, v202
	v_lshlrev_b32_e32 v136, 16, v203
	v_and_b32_e32 v137, 0xffff0000, v203
	v_pk_mul_f32 v[140:141], v[88:89], v[140:141]
	v_pk_mul_f32 v[176:177], v[90:91], v[134:135]
	v_pk_mul_f32 v[142:143], v[84:85], v[142:143]
	v_pk_mul_f32 v[178:179], v[86:87], v[136:137]
	v_cvt_pk_bf16_f32 v134, v140, v141
	v_cvt_pk_bf16_f32 v135, v176, v177
	v_cvt_pk_bf16_f32 v136, v142, v143
	v_cvt_pk_bf16_f32 v137, v178, v179
	global_store_dwordx4 v[138:139], v[134:137], off offset:256
.LBB0_1917:
	s_or_b64 exec, exec, s[4:5]
	s_nop 0
	v_or_b32_e32 v134, 32, v2
	v_cmp_gt_i32_e32 vcc, s50, v134
	s_and_saveexec_b64 s[4:5], vcc
	s_cbranch_execz .LBB0_1919
	v_ashrrev_i32_e32 v135, 31, v134
	v_lshlrev_b64 v[134:135], 10, v[134:135]
	v_lshl_add_u64 v[134:135], v[134:135], 0, v[132:133]
	v_lshlrev_b64 v[138:139], 1, v[134:135]
	v_lshl_add_u64 v[140:141], s[10:11], 0, v[138:139]
	global_load_dwordx4 v[196:199], v[140:141], off
	global_load_dwordx4 v[200:203], v[140:141], off offset:256
	v_lshl_add_u64 v[138:139], s[84:85], 0, v[138:139]
	s_waitcnt vmcnt(1)
	v_lshlrev_b32_e32 v142, 16, v196
	v_and_b32_e32 v143, 0xffff0000, v196
	v_lshlrev_b32_e32 v134, 16, v197
	v_and_b32_e32 v135, 0xffff0000, v197
	v_lshlrev_b32_e32 v176, 16, v198
	v_and_b32_e32 v177, 0xffff0000, v198
	v_lshlrev_b32_e32 v136, 16, v199
	v_and_b32_e32 v137, 0xffff0000, v199
	v_pk_mul_f32 v[142:143], v[112:113], v[142:143]
	v_pk_mul_f32 v[178:179], v[114:115], v[134:135]
	v_pk_mul_f32 v[176:177], v[108:109], v[176:177]
	v_pk_mul_f32 v[180:181], v[110:111], v[136:137]
	v_cvt_pk_bf16_f32 v134, v142, v143
	v_cvt_pk_bf16_f32 v135, v178, v179
	v_cvt_pk_bf16_f32 v136, v176, v177
	v_cvt_pk_bf16_f32 v137, v180, v181
	global_store_dwordx4 v[138:139], v[134:137], off
	s_waitcnt vmcnt(1)
	v_lshlrev_b32_e32 v140, 16, v200
	v_and_b32_e32 v141, 0xffff0000, v200
	v_lshlrev_b32_e32 v134, 16, v201
	v_and_b32_e32 v135, 0xffff0000, v201
	v_lshlrev_b32_e32 v142, 16, v202
	v_and_b32_e32 v143, 0xffff0000, v202
	v_lshlrev_b32_e32 v136, 16, v203
	v_and_b32_e32 v137, 0xffff0000, v203
	v_pk_mul_f32 v[140:141], v[80:81], v[140:141]
	v_pk_mul_f32 v[176:177], v[82:83], v[134:135]
	v_pk_mul_f32 v[142:143], v[76:77], v[142:143]
	v_pk_mul_f32 v[178:179], v[78:79], v[136:137]
	v_cvt_pk_bf16_f32 v134, v140, v141
	v_cvt_pk_bf16_f32 v135, v176, v177
	v_cvt_pk_bf16_f32 v136, v142, v143
	v_cvt_pk_bf16_f32 v137, v178, v179
	global_store_dwordx4 v[138:139], v[134:137], off offset:256
; __device__ __forceinline__ unsigned pk2(float lo, float hi) { f32x2_t v = {lo, hi}; bf16x2_t b = __builtin_convertvector(v, bf16x2_t); return __builtin_bit_cast(unsigned, b); }
;     __device__ __forceinline__ void operator()(const AccT& acc, const pg8::Unit& u, int wr, int wc, int fr, int fq) const {
; #pragma unroll
;         for (int ai = 0; ai < 2; ++ai)
; #pragma unroll
;             for (int m = 0; m < 4; ++m) { const int row = u.pm * 256 + ai * 128 + wr * 64 + m * 16 + fr; if (row >= M) continue;
; #pragma unroll
;                 for (int bj = 0; bj < 2; ++bj) { const size_t o = (size_t)row * D + u.pn * 256 + bj * 128 + wc * 32 + 8 * fq;
;                     const u32x4 b = *(const u32x4*)(mgb + o);
;                     const f32x4 v0 = acc[ai][bj][m][0], v1 = acc[ai][bj][m][1];
;                     u32x4 w; w.x = pk2(v0[0] * bflo(b.x), v0[1] * bfhi(b.x)); w.y = pk2(v0[2] * bflo(b.y), v0[3] * bfhi(b.y));
;                     w.z = pk2(v1[0] * bflo(b.z), v1[1] * bfhi(b.z)); w.w = pk2(v1[2] * bflo(b.w), v1[3] * bfhi(b.w));
;                     *(u32x4*)(G + o) = w; } }
;     }
.LBB0_1919:
	s_or_b64 exec, exec, s[4:5]
	s_nop 0
	v_or_b32_e32 v134, 48, v2
	v_cmp_gt_i32_e32 vcc, s50, v134
	s_and_saveexec_b64 s[4:5], vcc
	s_cbranch_execz .LBB0_1921
	v_ashrrev_i32_e32 v135, 31, v134
	v_lshlrev_b64 v[134:135], 10, v[134:135]
	v_lshl_add_u64 v[134:135], v[134:135], 0, v[132:133]
	v_lshlrev_b64 v[138:139], 1, v[134:135]
	v_lshl_add_u64 v[140:141], s[10:11], 0, v[138:139]
	global_load_dwordx4 v[196:199], v[140:141], off
	global_load_dwordx4 v[200:203], v[140:141], off offset:256
	v_lshl_add_u64 v[138:139], s[84:85], 0, v[138:139]
	s_waitcnt vmcnt(1)
	v_lshlrev_b32_e32 v142, 16, v196
	v_and_b32_e32 v143, 0xffff0000, v196
	v_lshlrev_b32_e32 v134, 16, v197
	v_and_b32_e32 v135, 0xffff0000, v197
	v_lshlrev_b32_e32 v176, 16, v198
	v_and_b32_e32 v177, 0xffff0000, v198
	v_lshlrev_b32_e32 v136, 16, v199
	v_and_b32_e32 v137, 0xffff0000, v199
	v_pk_mul_f32 v[142:143], v[104:105], v[142:143]
	v_pk_mul_f32 v[178:179], v[106:107], v[134:135]
	v_pk_mul_f32 v[176:177], v[100:101], v[176:177]
	v_pk_mul_f32 v[180:181], v[102:103], v[136:137]
	v_cvt_pk_bf16_f32 v134, v142, v143
	v_cvt_pk_bf16_f32 v135, v178, v179
	v_cvt_pk_bf16_f32 v136, v176, v177
	v_cvt_pk_bf16_f32 v137, v180, v181
	global_store_dwordx4 v[138:139], v[134:137], off
	s_waitcnt vmcnt(1)
	v_lshlrev_b32_e32 v140, 16, v200
	v_and_b32_e32 v141, 0xffff0000, v200
	v_lshlrev_b32_e32 v134, 16, v201
	v_and_b32_e32 v135, 0xffff0000, v201
	v_lshlrev_b32_e32 v142, 16, v202
	v_and_b32_e32 v143, 0xffff0000, v202
	v_lshlrev_b32_e32 v136, 16, v203
	v_and_b32_e32 v137, 0xffff0000, v203
	v_pk_mul_f32 v[140:141], v[72:73], v[140:141]
	v_pk_mul_f32 v[176:177], v[74:75], v[134:135]
	v_pk_mul_f32 v[142:143], v[68:69], v[142:143]
	v_pk_mul_f32 v[178:179], v[70:71], v[136:137]
	v_cvt_pk_bf16_f32 v134, v140, v141
	v_cvt_pk_bf16_f32 v135, v176, v177
	v_cvt_pk_bf16_f32 v136, v142, v143
	v_cvt_pk_bf16_f32 v137, v178, v179
	global_store_dwordx4 v[138:139], v[134:137], off offset:256
.LBB0_1921:
	s_or_b64 exec, exec, s[4:5]
	s_nop 0
	v_add_u32_e32 v134, 0x80, v2
	v_cmp_gt_i32_e32 vcc, s50, v134
	s_and_saveexec_b64 s[4:5], vcc
	s_cbranch_execz .LBB0_1923
	v_ashrrev_i32_e32 v135, 31, v134
	v_lshlrev_b64 v[134:135], 10, v[134:135]
	v_lshl_add_u64 v[134:135], v[134:135], 0, v[132:133]
	v_lshlrev_b64 v[138:139], 1, v[134:135]
	v_lshl_add_u64 v[140:141], s[10:11], 0, v[138:139]
	global_load_dwordx4 v[196:199], v[140:141], off
	global_load_dwordx4 v[200:203], v[140:141], off offset:256
	v_lshl_add_u64 v[138:139], s[84:85], 0, v[138:139]
	s_waitcnt vmcnt(1)
	v_lshlrev_b32_e32 v142, 16, v196
	v_and_b32_e32 v143, 0xffff0000, v196
	v_lshlrev_b32_e32 v134, 16, v197
	v_and_b32_e32 v135, 0xffff0000, v197
	v_lshlrev_b32_e32 v176, 16, v198
	v_and_b32_e32 v177, 0xffff0000, v198
	v_lshlrev_b32_e32 v136, 16, v199
	v_and_b32_e32 v137, 0xffff0000, v199
	v_pk_mul_f32 v[142:143], v[64:65], v[142:143]
	v_pk_mul_f32 v[178:179], v[66:67], v[134:135]
	v_pk_mul_f32 v[176:177], v[60:61], v[176:177]
	v_pk_mul_f32 v[180:181], v[62:63], v[136:137]
	v_cvt_pk_bf16_f32 v134, v142, v143
	v_cvt_pk_bf16_f32 v135, v178, v179
	v_cvt_pk_bf16_f32 v136, v176, v177
	v_cvt_pk_bf16_f32 v137, v180, v181
	global_store_dwordx4 v[138:139], v[134:137], off
	s_waitcnt vmcnt(1)
	v_lshlrev_b32_e32 v140, 16, v200
	v_and_b32_e32 v141, 0xffff0000, v200
	v_lshlrev_b32_e32 v134, 16, v201
	v_and_b32_e32 v135, 0xffff0000, v201
	v_lshlrev_b32_e32 v142, 16, v202
	v_and_b32_e32 v143, 0xffff0000, v202
	v_lshlrev_b32_e32 v136, 16, v203
	v_and_b32_e32 v137, 0xffff0000, v203
	v_pk_mul_f32 v[140:141], v[32:33], v[140:141]
	v_pk_mul_f32 v[176:177], v[34:35], v[134:135]
	v_pk_mul_f32 v[142:143], v[28:29], v[142:143]
	v_pk_mul_f32 v[178:179], v[30:31], v[136:137]
	v_cvt_pk_bf16_f32 v134, v140, v141
	v_cvt_pk_bf16_f32 v135, v176, v177
	v_cvt_pk_bf16_f32 v136, v142, v143
	v_cvt_pk_bf16_f32 v137, v178, v179
	global_store_dwordx4 v[138:139], v[134:137], off offset:256
; __device__ __forceinline__ unsigned pk2(float lo, float hi) { f32x2_t v = {lo, hi}; bf16x2_t b = __builtin_convertvector(v, bf16x2_t); return __builtin_bit_cast(unsigned, b); }
;     __device__ __forceinline__ void operator()(const AccT& acc, const pg8::Unit& u, int wr, int wc, int fr, int fq) const {
; #pragma unroll
;         for (int ai = 0; ai < 2; ++ai)
; #pragma unroll
;             for (int m = 0; m < 4; ++m) { const int row = u.pm * 256 + ai * 128 + wr * 64 + m * 16 + fr; if (row >= M) continue;
; #pragma unroll
;                 for (int bj = 0; bj < 2; ++bj) { const size_t o = (size_t)row * D + u.pn * 256 + bj * 128 + wc * 32 + 8 * fq;
;                     const u32x4 b = *(const u32x4*)(mgb + o);
;                     const f32x4 v0 = acc[ai][bj][m][0], v1 = acc[ai][bj][m][1];
;                     u32x4 w; w.x = pk2(v0[0] * bflo(b.x), v0[1] * bfhi(b.x)); w.y = pk2(v0[2] * bflo(b.y), v0[3] * bfhi(b.y));
;                     w.z = pk2(v1[0] * bflo(b.z), v1[1] * bfhi(b.z)); w.w = pk2(v1[2] * bflo(b.w), v1[3] * bfhi(b.w));
;                     *(u32x4*)(G + o) = w; } }
;     }
.LBB0_1923:
	s_or_b64 exec, exec, s[4:5]
	s_nop 0
	v_add_u32_e32 v134, 0x90, v2
	v_cmp_gt_i32_e32 vcc, s50, v134
	s_and_saveexec_b64 s[4:5], vcc
	s_cbranch_execz .LBB0_1925
	v_ashrrev_i32_e32 v135, 31, v134
	v_lshlrev_b64 v[134:135], 10, v[134:135]
	v_lshl_add_u64 v[134:135], v[134:135], 0, v[132:133]
	v_lshlrev_b64 v[138:139], 1, v[134:135]
	v_lshl_add_u64 v[140:141], s[10:11], 0, v[138:139]
	global_load_dwordx4 v[196:199], v[140:141], off
	global_load_dwordx4 v[200:203], v[140:141], off offset:256
	v_lshl_add_u64 v[138:139], s[84:85], 0, v[138:139]
	s_waitcnt vmcnt(1)
	v_lshlrev_b32_e32 v142, 16, v196
	v_and_b32_e32 v143, 0xffff0000, v196
	v_lshlrev_b32_e32 v134, 16, v197
	v_and_b32_e32 v135, 0xffff0000, v197
	v_lshlrev_b32_e32 v176, 16, v198
	v_and_b32_e32 v177, 0xffff0000, v198
	v_lshlrev_b32_e32 v136, 16, v199
	v_and_b32_e32 v137, 0xffff0000, v199
	v_pk_mul_f32 v[142:143], v[56:57], v[142:143]
	v_pk_mul_f32 v[178:179], v[58:59], v[134:135]
	v_pk_mul_f32 v[176:177], v[52:53], v[176:177]
	v_pk_mul_f32 v[180:181], v[54:55], v[136:137]
	v_cvt_pk_bf16_f32 v134, v142, v143
	v_cvt_pk_bf16_f32 v135, v178, v179
	v_cvt_pk_bf16_f32 v136, v176, v177
	v_cvt_pk_bf16_f32 v137, v180, v181
	global_store_dwordx4 v[138:139], v[134:137], off
	s_waitcnt vmcnt(1)
	v_lshlrev_b32_e32 v140, 16, v200
	v_and_b32_e32 v141, 0xffff0000, v200
	v_lshlrev_b32_e32 v134, 16, v201
	v_and_b32_e32 v135, 0xffff0000, v201
	v_lshlrev_b32_e32 v142, 16, v202
	v_and_b32_e32 v143, 0xffff0000, v202
	v_lshlrev_b32_e32 v136, 16, v203
	v_and_b32_e32 v137, 0xffff0000, v203
	v_pk_mul_f32 v[140:141], v[24:25], v[140:141]
	v_pk_mul_f32 v[176:177], v[26:27], v[134:135]
	v_pk_mul_f32 v[142:143], v[20:21], v[142:143]
	v_pk_mul_f32 v[178:179], v[22:23], v[136:137]
	v_cvt_pk_bf16_f32 v134, v140, v141
	v_cvt_pk_bf16_f32 v135, v176, v177
	v_cvt_pk_bf16_f32 v136, v142, v143
	v_cvt_pk_bf16_f32 v137, v178, v179
	global_store_dwordx4 v[138:139], v[134:137], off offset:256
.LBB0_1925:
	s_or_b64 exec, exec, s[4:5]
	s_nop 0
	v_add_u32_e32 v134, 0xa0, v2
	v_cmp_gt_i32_e32 vcc, s50, v134
	s_and_saveexec_b64 s[4:5], vcc
	s_cbranch_execz .LBB0_1927
	v_ashrrev_i32_e32 v135, 31, v134
	v_lshlrev_b64 v[134:135], 10, v[134:135]
	v_lshl_add_u64 v[134:135], v[134:135], 0, v[132:133]
	v_lshlrev_b64 v[138:139], 1, v[134:135]
	v_lshl_add_u64 v[140:141], s[10:11], 0, v[138:139]
	global_load_dwordx4 v[196:199], v[140:141], off
	global_load_dwordx4 v[200:203], v[140:141], off offset:256
	v_lshl_add_u64 v[138:139], s[84:85], 0, v[138:139]
	s_waitcnt vmcnt(1)
	v_lshlrev_b32_e32 v142, 16, v196
	v_and_b32_e32 v143, 0xffff0000, v196
	v_lshlrev_b32_e32 v134, 16, v197
	v_and_b32_e32 v135, 0xffff0000, v197
	v_lshlrev_b32_e32 v176, 16, v198
	v_and_b32_e32 v177, 0xffff0000, v198
	v_lshlrev_b32_e32 v136, 16, v199
	v_and_b32_e32 v137, 0xffff0000, v199
	v_pk_mul_f32 v[142:143], v[48:49], v[142:143]
	v_pk_mul_f32 v[178:179], v[50:51], v[134:135]
	v_pk_mul_f32 v[176:177], v[44:45], v[176:177]
	v_pk_mul_f32 v[180:181], v[46:47], v[136:137]
	v_cvt_pk_bf16_f32 v134, v142, v143
	v_cvt_pk_bf16_f32 v135, v178, v179
	v_cvt_pk_bf16_f32 v136, v176, v177
	v_cvt_pk_bf16_f32 v137, v180, v181
	global_store_dwordx4 v[138:139], v[134:137], off
	s_waitcnt vmcnt(1)
	v_lshlrev_b32_e32 v140, 16, v200
	v_and_b32_e32 v141, 0xffff0000, v200
	v_lshlrev_b32_e32 v134, 16, v201
	v_and_b32_e32 v135, 0xffff0000, v201
	v_lshlrev_b32_e32 v142, 16, v202
	v_and_b32_e32 v143, 0xffff0000, v202
	v_lshlrev_b32_e32 v136, 16, v203
	v_and_b32_e32 v137, 0xffff0000, v203
	v_pk_mul_f32 v[140:141], v[16:17], v[140:141]
	v_pk_mul_f32 v[176:177], v[18:19], v[134:135]
	v_pk_mul_f32 v[142:143], v[12:13], v[142:143]
	v_pk_mul_f32 v[178:179], v[14:15], v[136:137]
	v_cvt_pk_bf16_f32 v134, v140, v141
	v_cvt_pk_bf16_f32 v135, v176, v177
	v_cvt_pk_bf16_f32 v136, v142, v143
	v_cvt_pk_bf16_f32 v137, v178, v179
	global_store_dwordx4 v[138:139], v[134:137], off offset:256
.LBB0_1927:
	s_or_b64 exec, exec, s[4:5]
	s_nop 0
	v_add_u32_e32 v134, 0xb0, v2
	v_cmp_gt_i32_e32 vcc, s50, v134
	s_and_saveexec_b64 s[4:5], vcc
	s_cbranch_execz .LBB0_1929
	v_ashrrev_i32_e32 v135, 31, v134
	v_lshlrev_b64 v[134:135], 10, v[134:135]
	v_lshl_add_u64 v[132:133], v[134:135], 0, v[132:133]
	v_lshlrev_b64 v[136:137], 1, v[132:133]
	v_lshl_add_u64 v[138:139], s[10:11], 0, v[136:137]
	global_load_dwordx4 v[196:199], v[138:139], off
	global_load_dwordx4 v[200:203], v[138:139], off offset:256
	v_lshl_add_u64 v[136:137], s[84:85], 0, v[136:137]
	s_waitcnt vmcnt(1)
	v_lshlrev_b32_e32 v140, 16, v196
	v_and_b32_e32 v141, 0xffff0000, v196
	v_lshlrev_b32_e32 v132, 16, v197
	v_and_b32_e32 v133, 0xffff0000, v197
	v_lshlrev_b32_e32 v142, 16, v198
	v_and_b32_e32 v143, 0xffff0000, v198
	v_lshlrev_b32_e32 v134, 16, v199
	v_and_b32_e32 v135, 0xffff0000, v199
	v_pk_mul_f32 v[140:141], v[40:41], v[140:141]
	v_pk_mul_f32 v[176:177], v[42:43], v[132:133]
	v_pk_mul_f32 v[142:143], v[36:37], v[142:143]
	v_pk_mul_f32 v[178:179], v[38:39], v[134:135]
	v_cvt_pk_bf16_f32 v132, v140, v141
	v_cvt_pk_bf16_f32 v133, v176, v177
	v_cvt_pk_bf16_f32 v134, v142, v143
	v_cvt_pk_bf16_f32 v135, v178, v179
	global_store_dwordx4 v[136:137], v[132:135], off
	s_waitcnt vmcnt(1)
	v_lshlrev_b32_e32 v138, 16, v200
	v_and_b32_e32 v139, 0xffff0000, v200
	v_lshlrev_b32_e32 v132, 16, v201
	v_and_b32_e32 v133, 0xffff0000, v201
	v_lshlrev_b32_e32 v140, 16, v202
	v_and_b32_e32 v141, 0xffff0000, v202
	v_lshlrev_b32_e32 v134, 16, v203
	v_and_b32_e32 v135, 0xffff0000, v203
	v_pk_mul_f32 v[138:139], v[8:9], v[138:139]
	v_pk_mul_f32 v[142:143], v[10:11], v[132:133]
	v_pk_mul_f32 v[140:141], v[4:5], v[140:141]
	v_pk_mul_f32 v[176:177], v[6:7], v[134:135]
	v_cvt_pk_bf16_f32 v132, v138, v139
	v_cvt_pk_bf16_f32 v133, v142, v143
	v_cvt_pk_bf16_f32 v134, v140, v141
	v_cvt_pk_bf16_f32 v135, v176, v177
	global_store_dwordx4 v[136:137], v[132:135], off offset:256

; __device__ __forceinline__ float shfl_xor_l(float v, int o) { const int idx = (opq(lane_now()) ^ o) << 2; return __builtin_bit_cast(float, __builtin_amdgcn_ds_bpermute(idx, __builtin_bit_cast(int, v))); }
;     __device__ __forceinline__ void operator()(AccT& acc, const pg8::Unit& u, int wr, int wc, int fr_, int fq_) const {
;     ...
;             for (int m = 0; m < 4; ++m) { const int row = u.pm * 256 + ai * 128 + wr * 64 + m * 16 + fr + zoff;
;                 const float* xin = xp ? xp + (size_t)row * D : X + (size_t)row * D; float sacc = 0.f;
; #pragma unroll
;                 for (int bj = 0; bj < 2; ++bj)
; #pragma unroll
;                     for (int n = 0; n < 2; ++n) { const int col = u.pn * 256 + bj * 128 + wc * 32 + 8 * fq + 4 * n;
;                         const f32x4 xv = *(const f32x4*)(xin + col), gv = *(const f32x4*)(gt + col);
;                         const f32x4 xn = xv + (gv * coef) * acc[ai][bj][m][n]; acc[ai][bj][m][n] = xn;
;                         if (MODE == 0) *(f32x4*)(X + (size_t)row * D + col) = xn;
;                         sacc += (xn[0] * xn[0] + xn[1] * xn[1]) + (xn[2] * xn[2] + xn[3] * xn[3]); }
;                 asm volatile("" : "+v"(zoff) : "v"(sacc));
;                 sacc += shfl_xor_l(sacc, 16); sacc += shfl_xor_l(sacc, 32);
;                 ss[ai][m] = sacc; __builtin_amdgcn_sched_barrier(0); }
.LBB0_2017:
	s_ashr_i32 s4, s38, 3
	s_mul_hi_i32 s5, s4, 0x2400
	s_mulk_i32 s4, 0x2400
	s_lshl_b64 s[6:7], s[4:5], 2
	v_mov_b32_e32 v134, v165
	s_add_u32 s4, s12, s6
	s_addc_u32 s5, s13, s7
	v_add_u32_e32 v152, s80, v134
	s_lshl_b32 s10, s40, 8
	v_mov_b32_e32 v135, v164
	v_lshl_add_u32 v132, s38, 8, v152
	s_or_b32 s10, s10, s81
	v_ashrrev_i32_e32 v133, 31, v132
	v_lshl_add_u32 v154, v135, 3, s10
	v_lshlrev_b64 v[128:129], 12, v[132:133]
	v_ashrrev_i32_e32 v155, 31, v154
	v_lshl_add_u64 v[130:131], s[14:15], 0, v[128:129]
	v_lshlrev_b64 v[128:129], 2, v[154:155]
	v_lshl_add_u64 v[178:179], v[130:131], 0, v[128:129]
	v_lshl_add_u64 v[130:131], s[4:5], 0, v[128:129]
	global_load_dwordx4 v[196:199], v[130:131], off
	global_load_dwordx4 v[200:203], v[130:131], off offset:16
	global_load_dwordx4 v[204:207], v[130:131], off offset:512
	global_load_dwordx4 v[208:211], v[130:131], off offset:528
	global_load_dwordx4 v[212:215], v[178:179], off
	global_load_dwordx4 v[216:219], v[178:179], off offset:16
	global_load_dwordx4 v[220:223], v[178:179], off offset:512
	global_load_dwordx4 v[224:227], v[178:179], off offset:528
	v_mov_b32_e32 v133, 0
	v_mov_b32_e32 v153, v166
	s_waitcnt vmcnt(3)
	v_pk_fma_f32 v[58:59], v[58:59], v[198:199], v[214:215]
	v_pk_fma_f32 v[56:57], v[56:57], v[196:197], v[212:213]
	global_store_dwordx4 v[178:179], v[56:59], off
	s_waitcnt vmcnt(3)
	v_pk_fma_f32 v[66:67], v[66:67], v[202:203], v[218:219]
	v_pk_fma_f32 v[64:65], v[64:65], v[200:201], v[216:217]
	global_store_dwordx4 v[178:179], v[64:67], off offset:16
	s_waitcnt vmcnt(3)
	v_pk_fma_f32 v[22:23], v[22:23], v[206:207], v[222:223]
	v_pk_fma_f32 v[20:21], v[20:21], v[204:205], v[220:221]
	global_store_dwordx4 v[178:179], v[20:23], off offset:512
	v_pk_mul_f32 v[160:161], v[58:59], v[58:59]
	v_pk_mul_f32 v[162:163], v[56:57], v[56:57]
	s_waitcnt vmcnt(3)
	v_pk_fma_f32 v[30:31], v[30:31], v[210:211], v[226:227]
	v_pk_mov_b32 v[180:181], v[162:163], v[160:161] op_sel:[1,0]
	v_mov_b32_e32 v163, v161
	v_pk_add_f32 v[160:161], v[180:181], v[162:163]
	v_pk_mul_f32 v[162:163], v[66:67], v[66:67]
	v_pk_mul_f32 v[180:181], v[64:65], v[64:65]
	v_pk_add_f32 v[160:161], v[160:161], v[160:161] op_sel:[0,1] op_sel_hi:[1,0]
	v_pk_mov_b32 v[182:183], v[180:181], v[162:163] op_sel:[1,0]
	v_mov_b32_e32 v181, v163
	v_pk_add_f32 v[162:163], v[182:183], v[180:181]
	v_mul_f32_e32 v180, v21, v21
	v_mul_f32_e32 v182, v23, v23
	v_pk_add_f32 v[162:163], v[162:163], v[162:163] op_sel:[0,1] op_sel_hi:[1,0]
	v_pk_fma_f32 v[180:181], v[20:21], v[20:21], v[180:181] op_sel_hi:[1,1,0]
	v_pk_fma_f32 v[182:183], v[22:23], v[22:23], v[182:183] op_sel_hi:[1,1,0]
	v_pk_fma_f32 v[28:29], v[28:29], v[208:209], v[224:225]
	v_mul_f32_e32 v181, v30, v30
	v_mul_f32_e32 v161, v28, v28
	v_mul_f32_e32 v163, v29, v29
	v_mul_f32_e32 v183, v31, v31
	v_pk_add_f32 v[156:157], v[160:161], v[162:163]
	v_pk_add_f32 v[158:159], v[180:181], v[182:183]
	global_store_dwordx4 v[178:179], v[28:31], off offset:528
	v_pk_add_f32 v[156:157], v[156:157], v[158:159]
	s_nop 0
	v_add_f32_e32 v156, v156, v157
	v_mov_b32_e32 v157, v166
	v_lshlrev_b32_e32 v153, 2, v153
	v_xor_b32_e32 v153, 64, v153
	ds_bpermute_b32 v153, v153, v156
	s_waitcnt lgkmcnt(0)
	v_add_f32_e32 v153, v156, v153
	v_lshlrev_b32_e32 v157, 2, v157
	v_xor_b32_e32 v156, 0x80, v157
	ds_bpermute_b32 v156, v156, v153
	v_add3_u32 v158, v132, v133, 16
	v_ashrrev_i32_e32 v159, 31, v158
	v_lshlrev_b64 v[158:159], 12, v[158:159]
	v_lshl_add_u64 v[158:159], s[14:15], 0, v[158:159]
	v_lshl_add_u64 v[162:163], v[158:159], 0, v[128:129]
	global_load_dwordx4 v[212:215], v[162:163], off
	global_load_dwordx4 v[216:219], v[162:163], off offset:16
	global_load_dwordx4 v[220:223], v[162:163], off offset:512
	global_load_dwordx4 v[224:227], v[162:163], off offset:528
	v_mov_b32_e32 v157, v166
	s_waitcnt vmcnt(3)
	v_pk_fma_f32 v[86:87], v[86:87], v[198:199], v[214:215]
	v_pk_fma_f32 v[84:85], v[84:85], v[196:197], v[212:213]
	global_store_dwordx4 v[162:163], v[84:87], off
	s_waitcnt vmcnt(3)
	v_pk_fma_f32 v[94:95], v[94:95], v[202:203], v[218:219]
	v_pk_fma_f32 v[92:93], v[92:93], v[200:201], v[216:217]
	global_store_dwordx4 v[162:163], v[92:95], off offset:16
	s_waitcnt vmcnt(3)
	v_pk_fma_f32 v[38:39], v[38:39], v[206:207], v[222:223]
	v_pk_fma_f32 v[36:37], v[36:37], v[204:205], v[220:221]
	global_store_dwordx4 v[162:163], v[36:39], off offset:512
	v_pk_mul_f32 v[174:175], v[86:87], v[86:87]
	v_pk_mul_f32 v[176:177], v[84:85], v[84:85]
	s_waitcnt vmcnt(3)
	v_pk_fma_f32 v[50:51], v[50:51], v[210:211], v[226:227]
	v_pk_mov_b32 v[182:183], v[176:177], v[174:175] op_sel:[1,0]
	v_mov_b32_e32 v177, v175
	v_pk_add_f32 v[174:175], v[182:183], v[176:177]
	v_pk_mul_f32 v[176:177], v[94:95], v[94:95]
	v_pk_mul_f32 v[182:183], v[92:93], v[92:93]
	v_pk_add_f32 v[174:175], v[174:175], v[174:175] op_sel:[0,1] op_sel_hi:[1,0]
	v_pk_mov_b32 v[184:185], v[182:183], v[176:177] op_sel:[1,0]
	v_mov_b32_e32 v183, v177
	v_pk_add_f32 v[176:177], v[184:185], v[182:183]
	v_mul_f32_e32 v182, v37, v37
	v_mul_f32_e32 v184, v39, v39
	v_pk_add_f32 v[176:177], v[176:177], v[176:177] op_sel:[0,1] op_sel_hi:[1,0]
	v_pk_fma_f32 v[182:183], v[36:37], v[36:37], v[182:183] op_sel_hi:[1,1,0]
	v_pk_fma_f32 v[184:185], v[38:39], v[38:39], v[184:185] op_sel_hi:[1,1,0]
	v_pk_fma_f32 v[48:49], v[48:49], v[208:209], v[224:225]
	v_mul_f32_e32 v183, v50, v50
	v_mul_f32_e32 v175, v48, v48
	v_mul_f32_e32 v177, v49, v49
	v_mul_f32_e32 v185, v51, v51
	v_pk_add_f32 v[158:159], v[174:175], v[176:177]
	v_pk_add_f32 v[160:161], v[182:183], v[184:185]
	global_store_dwordx4 v[162:163], v[48:51], off offset:528
	v_pk_add_f32 v[158:159], v[158:159], v[160:161]
	s_nop 0
	v_add_f32_e32 v158, v158, v159
	v_mov_b32_e32 v159, v166
	v_lshlrev_b32_e32 v157, 2, v157
	v_xor_b32_e32 v157, 64, v157
	ds_bpermute_b32 v157, v157, v158
	s_waitcnt lgkmcnt(0)
; __device__ __forceinline__ float shfl_xor_l(float v, int o) { const int idx = (opq(lane_now()) ^ o) << 2; return __builtin_bit_cast(float, __builtin_amdgcn_ds_bpermute(idx, __builtin_bit_cast(int, v))); }
;     __device__ __forceinline__ void operator()(AccT& acc, const pg8::Unit& u, int wr, int wc, int fr_, int fq_) const {
;     ...
;             for (int m = 0; m < 4; ++m) { const int row = u.pm * 256 + ai * 128 + wr * 64 + m * 16 + fr + zoff;
;                 const float* xin = xp ? xp + (size_t)row * D : X + (size_t)row * D; float sacc = 0.f;
; #pragma unroll
;                 for (int bj = 0; bj < 2; ++bj)
; #pragma unroll
;                     for (int n = 0; n < 2; ++n) { const int col = u.pn * 256 + bj * 128 + wc * 32 + 8 * fq + 4 * n;
;                         const f32x4 xv = *(const f32x4*)(xin + col), gv = *(const f32x4*)(gt + col);
;                         const f32x4 xn = xv + (gv * coef) * acc[ai][bj][m][n]; acc[ai][bj][m][n] = xn;
;                         if (MODE == 0) *(f32x4*)(X + (size_t)row * D + col) = xn;
;                         sacc += (xn[0] * xn[0] + xn[1] * xn[1]) + (xn[2] * xn[2] + xn[3] * xn[3]); }
;                 asm volatile("" : "+v"(zoff) : "v"(sacc));
;                 sacc += shfl_xor_l(sacc, 16); sacc += shfl_xor_l(sacc, 32);
;                 ss[ai][m] = sacc; __builtin_amdgcn_sched_barrier(0); }
	v_add_f32_e32 v157, v158, v157
	v_lshlrev_b32_e32 v159, 2, v159
	v_xor_b32_e32 v158, 0x80, v159
	ds_bpermute_b32 v158, v158, v157
	v_add3_u32 v160, v132, v133, 32
	v_ashrrev_i32_e32 v161, 31, v160
	v_lshlrev_b64 v[160:161], 12, v[160:161]
	v_lshl_add_u64 v[160:161], s[14:15], 0, v[160:161]
	v_lshl_add_u64 v[182:183], v[160:161], 0, v[128:129]
	global_load_dwordx4 v[212:215], v[182:183], off
	global_load_dwordx4 v[216:219], v[182:183], off offset:16
	global_load_dwordx4 v[220:223], v[182:183], off offset:512
	global_load_dwordx4 v[224:227], v[182:183], off offset:528
	v_mov_b32_e32 v159, v166
	s_waitcnt vmcnt(3)
	v_pk_fma_f32 v[114:115], v[114:115], v[198:199], v[214:215]
	v_pk_fma_f32 v[112:113], v[112:113], v[196:197], v[212:213]
	global_store_dwordx4 v[182:183], v[112:115], off
	s_waitcnt vmcnt(3)
	v_pk_fma_f32 v[118:119], v[118:119], v[202:203], v[218:219]
	v_pk_fma_f32 v[116:117], v[116:117], v[200:201], v[216:217]
	global_store_dwordx4 v[182:183], v[116:119], off offset:16
	s_waitcnt vmcnt(3)
	v_pk_fma_f32 v[62:63], v[62:63], v[206:207], v[222:223]
	v_pk_fma_f32 v[60:61], v[60:61], v[204:205], v[220:221]
	global_store_dwordx4 v[182:183], v[60:63], off offset:512
	v_pk_mul_f32 v[174:175], v[114:115], v[114:115]
	v_pk_mul_f32 v[176:177], v[112:113], v[112:113]
	s_waitcnt vmcnt(3)
	v_pk_fma_f32 v[82:83], v[82:83], v[210:211], v[226:227]
	v_pk_mov_b32 v[184:185], v[176:177], v[174:175] op_sel:[1,0]
	v_mov_b32_e32 v177, v175
	v_pk_add_f32 v[174:175], v[184:185], v[176:177]
	v_pk_mul_f32 v[176:177], v[118:119], v[118:119]
	v_pk_mul_f32 v[184:185], v[116:117], v[116:117]
	v_pk_add_f32 v[174:175], v[174:175], v[174:175] op_sel:[0,1] op_sel_hi:[1,0]
	v_pk_mov_b32 v[186:187], v[184:185], v[176:177] op_sel:[1,0]
	v_mov_b32_e32 v185, v177
	v_pk_add_f32 v[176:177], v[186:187], v[184:185]
	v_mul_f32_e32 v184, v61, v61
	v_mul_f32_e32 v186, v63, v63
	v_pk_add_f32 v[176:177], v[176:177], v[176:177] op_sel:[0,1] op_sel_hi:[1,0]
	v_pk_fma_f32 v[184:185], v[60:61], v[60:61], v[184:185] op_sel_hi:[1,1,0]
	v_pk_fma_f32 v[186:187], v[62:63], v[62:63], v[186:187] op_sel_hi:[1,1,0]
	v_pk_fma_f32 v[80:81], v[80:81], v[208:209], v[224:225]
	v_mul_f32_e32 v185, v82, v82
	v_mul_f32_e32 v175, v80, v80
	v_mul_f32_e32 v177, v81, v81
	v_mul_f32_e32 v187, v83, v83
	v_pk_add_f32 v[160:161], v[174:175], v[176:177]
	v_pk_add_f32 v[162:163], v[184:185], v[186:187]
	global_store_dwordx4 v[182:183], v[80:83], off offset:528
	v_pk_add_f32 v[160:161], v[160:161], v[162:163]
	s_nop 0
	v_add_f32_e32 v160, v160, v161
	v_mov_b32_e32 v161, v166
	v_lshlrev_b32_e32 v159, 2, v159
	v_xor_b32_e32 v159, 64, v159
	ds_bpermute_b32 v159, v159, v160
	s_waitcnt lgkmcnt(0)
	v_add_f32_e32 v159, v160, v159
	v_lshlrev_b32_e32 v161, 2, v161
	v_xor_b32_e32 v160, 0x80, v161
	ds_bpermute_b32 v160, v160, v159
	v_add3_u32 v162, v132, v133, 48
	v_ashrrev_i32_e32 v163, 31, v162
	v_lshlrev_b64 v[162:163], 12, v[162:163]
	v_lshl_add_u64 v[162:163], s[14:15], 0, v[162:163]
	v_lshl_add_u64 v[162:163], v[162:163], 0, v[128:129]
	global_load_dwordx4 v[212:215], v[162:163], off
	global_load_dwordx4 v[216:219], v[162:163], off offset:16
	global_load_dwordx4 v[220:223], v[162:163], off offset:512
	global_load_dwordx4 v[224:227], v[162:163], off offset:528
	v_mov_b32_e32 v161, v166
	s_waitcnt vmcnt(3)
	v_pk_fma_f32 v[122:123], v[122:123], v[198:199], v[214:215]
	v_pk_fma_f32 v[120:121], v[120:121], v[196:197], v[212:213]
	global_store_dwordx4 v[162:163], v[120:123], off
	s_waitcnt vmcnt(3)
	v_pk_fma_f32 v[126:127], v[126:127], v[202:203], v[218:219]
	v_pk_fma_f32 v[124:125], v[124:125], v[200:201], v[216:217]
	global_store_dwordx4 v[162:163], v[124:127], off offset:16
	s_waitcnt vmcnt(3)
	v_pk_fma_f32 v[98:99], v[98:99], v[206:207], v[222:223]
	v_pk_fma_f32 v[96:97], v[96:97], v[204:205], v[220:221]
	global_store_dwordx4 v[162:163], v[96:99], off offset:512
	v_pk_mul_f32 v[178:179], v[122:123], v[122:123]
	v_pk_mul_f32 v[180:181], v[120:121], v[120:121]
	s_waitcnt vmcnt(3)
	v_pk_fma_f32 v[106:107], v[106:107], v[210:211], v[226:227]
	v_pk_mov_b32 v[186:187], v[180:181], v[178:179] op_sel:[1,0]
	v_mov_b32_e32 v181, v179
	v_pk_add_f32 v[178:179], v[186:187], v[180:181]
	v_pk_mul_f32 v[180:181], v[126:127], v[126:127]
	v_pk_mul_f32 v[186:187], v[124:125], v[124:125]
	v_pk_add_f32 v[178:179], v[178:179], v[178:179] op_sel:[0,1] op_sel_hi:[1,0]
	v_pk_mov_b32 v[188:189], v[186:187], v[180:181] op_sel:[1,0]
	v_mov_b32_e32 v187, v181
	v_pk_add_f32 v[180:181], v[188:189], v[186:187]
	v_mul_f32_e32 v186, v97, v97
	v_mul_f32_e32 v188, v99, v99
	v_pk_add_f32 v[180:181], v[180:181], v[180:181] op_sel:[0,1] op_sel_hi:[1,0]
	v_pk_fma_f32 v[186:187], v[96:97], v[96:97], v[186:187] op_sel_hi:[1,1,0]
	v_pk_fma_f32 v[188:189], v[98:99], v[98:99], v[188:189] op_sel_hi:[1,1,0]
	v_pk_fma_f32 v[104:105], v[104:105], v[208:209], v[224:225]
	v_mul_f32_e32 v187, v106, v106
	v_mul_f32_e32 v179, v104, v104
	v_mul_f32_e32 v181, v105, v105
	v_mul_f32_e32 v189, v107, v107
	global_store_dwordx4 v[162:163], v[104:107], off offset:528
	v_pk_add_f32 v[162:163], v[178:179], v[180:181]
	v_pk_add_f32 v[174:175], v[186:187], v[188:189]
	s_nop 0
	v_pk_add_f32 v[162:163], v[162:163], v[174:175]
	s_nop 0
	v_add_f32_e32 v162, v162, v163
	v_mov_b32_e32 v163, v166
	v_lshlrev_b32_e32 v161, 2, v161
	v_xor_b32_e32 v161, 64, v161
	ds_bpermute_b32 v161, v161, v162
	s_waitcnt lgkmcnt(0)
; __device__ __forceinline__ float shfl_xor_l(float v, int o) { const int idx = (opq(lane_now()) ^ o) << 2; return __builtin_bit_cast(float, __builtin_amdgcn_ds_bpermute(idx, __builtin_bit_cast(int, v))); }
;     __device__ __forceinline__ void operator()(AccT& acc, const pg8::Unit& u, int wr, int wc, int fr_, int fq_) const {
;     ...
;             for (int m = 0; m < 4; ++m) { const int row = u.pm * 256 + ai * 128 + wr * 64 + m * 16 + fr + zoff;
;                 const float* xin = xp ? xp + (size_t)row * D : X + (size_t)row * D; float sacc = 0.f;
; #pragma unroll
;                 for (int bj = 0; bj < 2; ++bj)
; #pragma unroll
;                     for (int n = 0; n < 2; ++n) { const int col = u.pn * 256 + bj * 128 + wc * 32 + 8 * fq + 4 * n;
;                         const f32x4 xv = *(const f32x4*)(xin + col), gv = *(const f32x4*)(gt + col);
;                         const f32x4 xn = xv + (gv * coef) * acc[ai][bj][m][n]; acc[ai][bj][m][n] = xn;
;                         if (MODE == 0) *(f32x4*)(X + (size_t)row * D + col) = xn;
;                         sacc += (xn[0] * xn[0] + xn[1] * xn[1]) + (xn[2] * xn[2] + xn[3] * xn[3]); }
;                 asm volatile("" : "+v"(zoff) : "v"(sacc));
;                 sacc += shfl_xor_l(sacc, 16); sacc += shfl_xor_l(sacc, 32);
;                 ss[ai][m] = sacc; __builtin_amdgcn_sched_barrier(0); }
	v_add_f32_e32 v161, v162, v161
	v_lshlrev_b32_e32 v163, 2, v163
	v_xor_b32_e32 v162, 0x80, v163
	ds_bpermute_b32 v162, v162, v161
	v_add3_u32 v174, v132, v133, s64
	v_ashrrev_i32_e32 v175, 31, v174
	v_lshlrev_b64 v[174:175], 12, v[174:175]
	v_lshl_add_u64 v[174:175], s[14:15], 0, v[174:175]
	v_lshl_add_u64 v[186:187], v[174:175], 0, v[128:129]
	global_load_dwordx4 v[212:215], v[186:187], off
	global_load_dwordx4 v[216:219], v[186:187], off offset:16
	global_load_dwordx4 v[220:223], v[186:187], off offset:512
	global_load_dwordx4 v[224:227], v[186:187], off offset:528
	v_mov_b32_e32 v163, v166
	s_waitcnt vmcnt(3)
	v_pk_fma_f32 v[110:111], v[110:111], v[198:199], v[214:215]
	v_pk_fma_f32 v[108:109], v[108:109], v[196:197], v[212:213]
	global_store_dwordx4 v[186:187], v[108:111], off
	s_waitcnt vmcnt(3)
	v_pk_fma_f32 v[102:103], v[102:103], v[202:203], v[218:219]
	v_pk_fma_f32 v[100:101], v[100:101], v[200:201], v[216:217]
	global_store_dwordx4 v[186:187], v[100:103], off offset:16
	s_waitcnt vmcnt(3)
	v_pk_fma_f32 v[90:91], v[90:91], v[206:207], v[222:223]
	v_pk_fma_f32 v[88:89], v[88:89], v[204:205], v[220:221]
	global_store_dwordx4 v[186:187], v[88:91], off offset:512
	v_pk_mul_f32 v[178:179], v[110:111], v[110:111]
	v_pk_mul_f32 v[180:181], v[108:109], v[108:109]
	s_waitcnt vmcnt(3)
	v_pk_fma_f32 v[78:79], v[78:79], v[210:211], v[226:227]
	v_pk_mov_b32 v[188:189], v[180:181], v[178:179] op_sel:[1,0]
	v_mov_b32_e32 v181, v179
	v_pk_add_f32 v[178:179], v[188:189], v[180:181]
	v_pk_mul_f32 v[180:181], v[102:103], v[102:103]
	v_pk_mul_f32 v[188:189], v[100:101], v[100:101]
	v_pk_add_f32 v[178:179], v[178:179], v[178:179] op_sel:[0,1] op_sel_hi:[1,0]
	v_pk_mov_b32 v[190:191], v[188:189], v[180:181] op_sel:[1,0]
	v_mov_b32_e32 v189, v181
	v_pk_add_f32 v[180:181], v[190:191], v[188:189]
	v_mul_f32_e32 v188, v89, v89
	v_mul_f32_e32 v190, v91, v91
	v_pk_add_f32 v[180:181], v[180:181], v[180:181] op_sel:[0,1] op_sel_hi:[1,0]
	v_pk_fma_f32 v[188:189], v[88:89], v[88:89], v[188:189] op_sel_hi:[1,1,0]
	v_pk_fma_f32 v[190:191], v[90:91], v[90:91], v[190:191] op_sel_hi:[1,1,0]
	v_pk_fma_f32 v[76:77], v[76:77], v[208:209], v[224:225]
	v_mul_f32_e32 v189, v78, v78
	v_mul_f32_e32 v179, v76, v76
	v_mul_f32_e32 v181, v77, v77
	v_mul_f32_e32 v191, v79, v79
	v_pk_add_f32 v[174:175], v[178:179], v[180:181]
	v_pk_add_f32 v[176:177], v[188:189], v[190:191]
	global_store_dwordx4 v[186:187], v[76:79], off offset:528
	v_pk_add_f32 v[174:175], v[174:175], v[176:177]
	s_nop 0
	v_add_f32_e32 v173, v174, v175
	v_mov_b32_e32 v174, v166
	v_lshlrev_b32_e32 v163, 2, v163
	v_xor_b32_e32 v163, 64, v163
	ds_bpermute_b32 v163, v163, v173
	s_waitcnt lgkmcnt(0)
	v_add_f32_e32 v163, v173, v163
	v_lshlrev_b32_e32 v174, 2, v174
	v_xor_b32_e32 v173, 0x80, v174
	ds_bpermute_b32 v173, v173, v163
	v_add3_u32 v174, v132, v133, s65
	v_ashrrev_i32_e32 v175, 31, v174
	v_lshlrev_b64 v[174:175], 12, v[174:175]
	v_lshl_add_u64 v[174:175], s[14:15], 0, v[174:175]
	v_lshl_add_u64 v[186:187], v[174:175], 0, v[128:129]
	global_load_dwordx4 v[212:215], v[186:187], off
	global_load_dwordx4 v[216:219], v[186:187], off offset:16
	global_load_dwordx4 v[220:223], v[186:187], off offset:512
	global_load_dwordx4 v[224:227], v[186:187], off offset:528
	v_mov_b32_e32 v192, v166
	s_waitcnt vmcnt(3)
	v_pk_fma_f32 v[74:75], v[74:75], v[198:199], v[214:215]
	v_pk_fma_f32 v[72:73], v[72:73], v[196:197], v[212:213]
	global_store_dwordx4 v[186:187], v[72:75], off
	s_waitcnt vmcnt(3)
	v_pk_fma_f32 v[70:71], v[70:71], v[202:203], v[218:219]
	v_pk_fma_f32 v[68:69], v[68:69], v[200:201], v[216:217]
	global_store_dwordx4 v[186:187], v[68:71], off offset:16
	s_waitcnt vmcnt(3)
	v_pk_fma_f32 v[54:55], v[54:55], v[206:207], v[222:223]
	v_pk_fma_f32 v[52:53], v[52:53], v[204:205], v[220:221]
	global_store_dwordx4 v[186:187], v[52:55], off offset:512
	v_pk_mul_f32 v[178:179], v[74:75], v[74:75]
	v_pk_mul_f32 v[180:181], v[72:73], v[72:73]
	s_waitcnt vmcnt(3)
	v_pk_fma_f32 v[46:47], v[46:47], v[210:211], v[226:227]
	v_pk_mov_b32 v[188:189], v[180:181], v[178:179] op_sel:[1,0]
	v_mov_b32_e32 v181, v179
	v_pk_add_f32 v[178:179], v[188:189], v[180:181]
	v_pk_mul_f32 v[180:181], v[70:71], v[70:71]
	v_pk_mul_f32 v[188:189], v[68:69], v[68:69]
	v_pk_add_f32 v[178:179], v[178:179], v[178:179] op_sel:[0,1] op_sel_hi:[1,0]
	v_pk_mov_b32 v[190:191], v[188:189], v[180:181] op_sel:[1,0]
	v_mov_b32_e32 v189, v181
	v_pk_add_f32 v[180:181], v[190:191], v[188:189]
	v_mul_f32_e32 v188, v53, v53
	v_mul_f32_e32 v190, v55, v55
	v_pk_add_f32 v[180:181], v[180:181], v[180:181] op_sel:[0,1] op_sel_hi:[1,0]
	v_pk_fma_f32 v[188:189], v[52:53], v[52:53], v[188:189] op_sel_hi:[1,1,0]
	v_pk_fma_f32 v[190:191], v[54:55], v[54:55], v[190:191] op_sel_hi:[1,1,0]
	v_pk_fma_f32 v[44:45], v[44:45], v[208:209], v[224:225]
	v_mul_f32_e32 v189, v46, v46
	v_mul_f32_e32 v179, v44, v44
	v_mul_f32_e32 v181, v45, v45
	v_mul_f32_e32 v191, v47, v47
	v_pk_add_f32 v[174:175], v[178:179], v[180:181]
	v_pk_add_f32 v[176:177], v[188:189], v[190:191]
	global_store_dwordx4 v[186:187], v[44:47], off offset:528
	v_pk_add_f32 v[174:175], v[174:175], v[176:177]
	v_mov_b32_e32 v176, v166
	v_add_f32_e32 v174, v174, v175
	s_nop 0
	v_lshlrev_b32_e32 v175, 2, v192
	v_xor_b32_e32 v175, 64, v175
	ds_bpermute_b32 v175, v175, v174
	v_lshlrev_b32_e32 v176, 2, v176
	s_waitcnt lgkmcnt(0)
	v_add_f32_e32 v174, v174, v175
	v_xor_b32_e32 v175, 0x80, v176
	ds_bpermute_b32 v175, v175, v174
	v_add3_u32 v176, v132, v133, s66
	v_ashrrev_i32_e32 v177, 31, v176
	v_lshlrev_b64 v[176:177], 12, v[176:177]
	v_lshl_add_u64 v[176:177], s[14:15], 0, v[176:177]
	v_lshl_add_u64 v[188:189], v[176:177], 0, v[128:129]
	global_load_dwordx4 v[212:215], v[188:189], off
	global_load_dwordx4 v[216:219], v[188:189], off offset:16
	global_load_dwordx4 v[220:223], v[188:189], off offset:512
	global_load_dwordx4 v[224:227], v[188:189], off offset:528
	v_mov_b32_e32 v194, v166
	s_waitcnt vmcnt(3)
; __device__ __forceinline__ float shfl_xor_l(float v, int o) { const int idx = (opq(lane_now()) ^ o) << 2; return __builtin_bit_cast(float, __builtin_amdgcn_ds_bpermute(idx, __builtin_bit_cast(int, v))); }
;     __device__ __forceinline__ void operator()(AccT& acc, const pg8::Unit& u, int wr, int wc, int fr_, int fq_) const {
;     ...
;             for (int m = 0; m < 4; ++m) { const int row = u.pm * 256 + ai * 128 + wr * 64 + m * 16 + fr + zoff;
;                 const float* xin = xp ? xp + (size_t)row * D : X + (size_t)row * D; float sacc = 0.f;
; #pragma unroll
;                 for (int bj = 0; bj < 2; ++bj)
; #pragma unroll
;                     for (int n = 0; n < 2; ++n) { const int col = u.pn * 256 + bj * 128 + wc * 32 + 8 * fq + 4 * n;
;                         const f32x4 xv = *(const f32x4*)(xin + col), gv = *(const f32x4*)(gt + col);
;                         const f32x4 xn = xv + (gv * coef) * acc[ai][bj][m][n]; acc[ai][bj][m][n] = xn;
;                         if (MODE == 0) *(f32x4*)(X + (size_t)row * D + col) = xn;
;                         sacc += (xn[0] * xn[0] + xn[1] * xn[1]) + (xn[2] * xn[2] + xn[3] * xn[3]); }
;                 asm volatile("" : "+v"(zoff) : "v"(sacc));
;                 sacc += shfl_xor_l(sacc, 16); sacc += shfl_xor_l(sacc, 32);
;                 ss[ai][m] = sacc; __builtin_amdgcn_sched_barrier(0); }
;         if (fq == 0) {
; #pragma unroll
;             for (int ai = 0; ai < 2; ++ai)
; #pragma unroll
;                 for (int m = 0; m < 4; ++m) sred[wc * 256 + ai * 128 + wr * 64 + m * 16 + fr] = ss[ai][m]; }
	v_pk_fma_f32 v[42:43], v[42:43], v[198:199], v[214:215]
	v_pk_fma_f32 v[40:41], v[40:41], v[196:197], v[212:213]
	global_store_dwordx4 v[188:189], v[40:43], off
	s_waitcnt vmcnt(3)
	v_pk_fma_f32 v[34:35], v[34:35], v[202:203], v[218:219]
	v_pk_fma_f32 v[32:33], v[32:33], v[200:201], v[216:217]
	global_store_dwordx4 v[188:189], v[32:35], off offset:16
	s_waitcnt vmcnt(3)
	v_pk_fma_f32 v[26:27], v[26:27], v[206:207], v[222:223]
	v_pk_fma_f32 v[24:25], v[24:25], v[204:205], v[220:221]
	global_store_dwordx4 v[188:189], v[24:27], off offset:512
	v_pk_mul_f32 v[180:181], v[42:43], v[42:43]
	v_pk_mul_f32 v[182:183], v[40:41], v[40:41]
	s_waitcnt vmcnt(3)
	v_pk_fma_f32 v[18:19], v[18:19], v[210:211], v[226:227]
	v_pk_mov_b32 v[190:191], v[182:183], v[180:181] op_sel:[1,0]
	v_mov_b32_e32 v183, v181
	v_pk_add_f32 v[180:181], v[190:191], v[182:183]
	v_pk_mul_f32 v[182:183], v[34:35], v[34:35]
	v_pk_mul_f32 v[190:191], v[32:33], v[32:33]
	v_pk_add_f32 v[180:181], v[180:181], v[180:181] op_sel:[0,1] op_sel_hi:[1,0]
	v_pk_mov_b32 v[192:193], v[190:191], v[182:183] op_sel:[1,0]
	v_mov_b32_e32 v191, v183
	v_pk_add_f32 v[182:183], v[192:193], v[190:191]
	v_mul_f32_e32 v190, v25, v25
	v_mul_f32_e32 v192, v27, v27
	v_pk_add_f32 v[182:183], v[182:183], v[182:183] op_sel:[0,1] op_sel_hi:[1,0]
	v_pk_fma_f32 v[190:191], v[24:25], v[24:25], v[190:191] op_sel_hi:[1,1,0]
	v_pk_fma_f32 v[192:193], v[26:27], v[26:27], v[192:193] op_sel_hi:[1,1,0]
	v_pk_fma_f32 v[16:17], v[16:17], v[208:209], v[224:225]
	v_mul_f32_e32 v191, v18, v18
	v_mul_f32_e32 v181, v16, v16
	v_mul_f32_e32 v183, v17, v17
	v_mul_f32_e32 v193, v19, v19
	v_pk_add_f32 v[176:177], v[180:181], v[182:183]
	v_pk_add_f32 v[178:179], v[190:191], v[192:193]
	global_store_dwordx4 v[188:189], v[16:19], off offset:528
	v_pk_add_f32 v[176:177], v[176:177], v[178:179]
	v_mov_b32_e32 v178, v166
	v_add_f32_e32 v176, v176, v177
	s_nop 0
	v_lshlrev_b32_e32 v177, 2, v194
	v_xor_b32_e32 v177, 64, v177
	ds_bpermute_b32 v177, v177, v176
	v_lshlrev_b32_e32 v178, 2, v178
	s_waitcnt lgkmcnt(0)
	v_add_f32_e32 v176, v176, v177
	v_xor_b32_e32 v177, 0x80, v178
	ds_bpermute_b32 v177, v177, v176
	v_add3_u32 v178, v132, v133, s67
	v_ashrrev_i32_e32 v179, 31, v178
	v_lshlrev_b64 v[178:179], 12, v[178:179]
	v_lshl_add_u64 v[178:179], s[14:15], 0, v[178:179]
	v_lshl_add_u64 v[190:191], v[178:179], 0, v[128:129]
	global_load_dwordx4 v[212:215], v[190:191], off
	global_load_dwordx4 v[216:219], v[190:191], off offset:16
	global_load_dwordx4 v[220:223], v[190:191], off offset:512
	global_load_dwordx4 v[224:227], v[190:191], off offset:528
	v_mov_b32_e32 v194, v166
	s_waitcnt vmcnt(3)
	v_pk_fma_f32 v[14:15], v[14:15], v[198:199], v[214:215]
	v_pk_fma_f32 v[12:13], v[12:13], v[196:197], v[212:213]
	global_store_dwordx4 v[190:191], v[12:15], off
	s_waitcnt vmcnt(3)
	v_pk_fma_f32 v[10:11], v[10:11], v[202:203], v[218:219]
	v_pk_fma_f32 v[8:9], v[8:9], v[200:201], v[216:217]
	global_store_dwordx4 v[190:191], v[8:11], off offset:16
	s_waitcnt vmcnt(3)
	v_pk_fma_f32 v[6:7], v[6:7], v[206:207], v[222:223]
	v_pk_fma_f32 v[4:5], v[4:5], v[204:205], v[220:221]
	global_store_dwordx4 v[190:191], v[4:7], off offset:512
	v_pk_mul_f32 v[130:131], v[14:15], v[14:15]
	v_pk_mul_f32 v[182:183], v[12:13], v[12:13]
	v_mul_f32_e32 v132, v5, v5
	v_pk_mov_b32 v[184:185], v[182:183], v[130:131] op_sel:[1,0]
	v_mov_b32_e32 v183, v131
	v_pk_add_f32 v[130:131], v[184:185], v[182:183]
	v_pk_mul_f32 v[182:183], v[10:11], v[10:11]
	v_pk_mul_f32 v[184:185], v[8:9], v[8:9]
	v_pk_add_f32 v[130:131], v[130:131], v[130:131] op_sel:[0,1] op_sel_hi:[1,0]
	v_pk_mov_b32 v[192:193], v[184:185], v[182:183] op_sel:[1,0]
	v_mov_b32_e32 v185, v183
	v_pk_add_f32 v[182:183], v[192:193], v[184:185]
	v_mul_f32_e32 v184, v7, v7
	v_pk_add_f32 v[182:183], v[182:183], v[182:183] op_sel:[0,1] op_sel_hi:[1,0]
	v_pk_fma_f32 v[192:193], v[4:5], v[4:5], v[132:133] op_sel_hi:[1,1,0]
	v_pk_fma_f32 v[184:185], v[6:7], v[6:7], v[184:185] op_sel_hi:[1,1,0]
	v_mov_b32_e32 v132, v166
	s_waitcnt vmcnt(3)
	v_pk_fma_f32 v[2:3], v[2:3], v[210:211], v[226:227]
	v_pk_fma_f32 v[0:1], v[0:1], v[208:209], v[224:225]
	v_mul_f32_e32 v193, v2, v2
	v_mul_f32_e32 v131, v0, v0
	v_mul_f32_e32 v183, v1, v1
	v_mul_f32_e32 v185, v3, v3
	v_pk_add_f32 v[130:131], v[130:131], v[182:183]
	v_pk_add_f32 v[178:179], v[192:193], v[184:185]
	global_store_dwordx4 v[190:191], v[0:3], off offset:528
	v_pk_add_f32 v[130:131], v[130:131], v[178:179]
	s_nop 0
	v_add_f32_e32 v130, v130, v131
	s_nop 0
	v_lshlrev_b32_e32 v131, 2, v194
	v_xor_b32_e32 v131, 64, v131
	ds_bpermute_b32 v131, v131, v130
	v_lshlrev_b32_e32 v132, 2, v132
	s_waitcnt lgkmcnt(0)
	v_add_f32_e32 v130, v130, v131
	v_xor_b32_e32 v131, 0x80, v132
	ds_bpermute_b32 v131, v131, v130
	v_cmp_eq_u32_e32 vcc, 0, v135
	s_and_saveexec_b64 s[4:5], vcc
	s_cbranch_execz .LBB0_2019
	v_add_f32_e32 v157, v157, v158
	v_add_f32_e32 v153, v153, v156
	s_waitcnt lgkmcnt(0)
	v_add_f32_e32 v130, v130, v131
	v_lshl_add_u32 v131, v134, 2, s61
	v_add_f32_e32 v132, v176, v177
	v_add_f32_e32 v133, v174, v175
	v_add_f32_e32 v163, v163, v173
	v_add_f32_e32 v161, v161, v162
	v_add_f32_e32 v159, v159, v160
	ds_write2_b32 v131, v153, v157 offset1:16
	ds_write2_b32 v131, v159, v161 offset0:32 offset1:48
	ds_write2_b32 v131, v163, v133 offset0:128 offset1:144
	ds_write2_b32 v131, v132, v130 offset0:160 offset1:176

; __device__ __forceinline__ float shfl_xor_l(float v, int o) { const int idx = (opq(lane_now()) ^ o) << 2; return __builtin_bit_cast(float, __builtin_amdgcn_ds_bpermute(idx, __builtin_bit_cast(int, v))); }
;     __device__ __forceinline__ void operator()(AccT& acc, const pg8::Unit& u, int wr, int wc, int fr_, int fq_) const {
;     ...
;             for (int m = 0; m < 4; ++m) { const int row = u.pm * 256 + ai * 128 + wr * 64 + m * 16 + fr + zoff;
;                 const float* xin = xp ? xp + (size_t)row * D : X + (size_t)row * D; float sacc = 0.f;
; #pragma unroll
;                 for (int bj = 0; bj < 2; ++bj)
; #pragma unroll
;                     for (int n = 0; n < 2; ++n) { const int col = u.pn * 256 + bj * 128 + wc * 32 + 8 * fq + 4 * n;
;                         const f32x4 xv = *(const f32x4*)(xin + col), gv = *(const f32x4*)(gt + col);
;                         const f32x4 xn = xv + (gv * coef) * acc[ai][bj][m][n]; acc[ai][bj][m][n] = xn;
;                         if (MODE == 0) *(f32x4*)(X + (size_t)row * D + col) = xn;
;                         sacc += (xn[0] * xn[0] + xn[1] * xn[1]) + (xn[2] * xn[2] + xn[3] * xn[3]); }
;                 asm volatile("" : "+v"(zoff) : "v"(sacc));
;                 sacc += shfl_xor_l(sacc, 16); sacc += shfl_xor_l(sacc, 32);
;                 ss[ai][m] = sacc; __builtin_amdgcn_sched_barrier(0); }
.LBB0_2326:
	s_ashr_i32 s4, s30, 3
	s_mul_hi_i32 s5, s4, 0x9000
	s_mul_i32 s4, s4, 0x9000
	s_add_u32 s4, s12, s4
	s_addc_u32 s5, s13, s5
	s_lshl_b32 s10, s34, 8
	v_mov_b32_e32 v147, v160
	v_mov_b32_e32 v156, v161
	s_or_b32 s10, s10, s81
	v_mov_b32_e32 v157, 0
	v_lshl_add_u32 v144, v156, 3, s10
	v_add_u32_e32 v146, s80, v147
	v_ashrrev_i32_e32 v145, 31, v144
	v_lshlrev_b64 v[144:145], 2, v[144:145]
	v_lshl_add_u32 v150, s30, 8, v146
	v_lshl_add_u64 v[148:149], s[4:5], 0, v[144:145]
	v_ashrrev_i32_e32 v151, 31, v150
	global_load_dwordx4 v[218:221], v[148:149], off offset:16
	global_load_dwordx4 v[222:225], v[148:149], off
	global_load_dwordx4 v[226:229], v[148:149], off offset:528
	global_load_dwordx4 v[230:233], v[148:149], off offset:512
	v_lshlrev_b64 v[158:159], 12, v[150:151]
	v_lshl_add_u64 v[158:159], s[14:15], 0, v[158:159]
	v_lshl_add_u64 v[158:159], v[158:159], 0, v[144:145]
	global_load_dwordx4 v[234:237], v[158:159], off
	global_load_dwordx4 v[240:243], v[158:159], off offset:16
	global_load_dwordx4 v[244:247], v[158:159], off offset:512
	global_load_dwordx4 v[248:251], v[158:159], off offset:528
	v_mov_b32_e32 v151, v166
	s_waitcnt vmcnt(7)
	v_pk_mul_f32 v[154:155], v[220:221], 0.5 op_sel_hi:[1,0]
	s_waitcnt vmcnt(6)
	v_pk_mul_f32 v[158:159], v[224:225], 0.5 op_sel_hi:[1,0]
	v_pk_mul_f32 v[170:171], v[222:223], 0.5 op_sel_hi:[1,0]
	v_pk_mul_f32 v[152:153], v[218:219], 0.5 op_sel_hi:[1,0]
	s_waitcnt vmcnt(3)
	v_pk_fma_f32 v[126:127], v[126:127], v[158:159], v[236:237]
	v_pk_fma_f32 v[124:125], v[124:125], v[170:171], v[234:235]
	s_waitcnt vmcnt(2)
	v_pk_fma_f32 v[122:123], v[122:123], v[154:155], v[242:243]
	v_pk_fma_f32 v[120:121], v[120:121], v[152:153], v[240:241]
	v_pk_mul_f32 v[172:173], v[232:233], 0.5 op_sel_hi:[1,0]
	v_pk_mul_f32 v[178:179], v[230:231], 0.5 op_sel_hi:[1,0]
	v_pk_mul_f32 v[176:177], v[228:229], 0.5 op_sel_hi:[1,0]
	v_pk_mul_f32 v[174:175], v[226:227], 0.5 op_sel_hi:[1,0]
	v_pk_mul_f32 v[152:153], v[126:127], v[126:127]
	v_pk_mul_f32 v[154:155], v[124:125], v[124:125]
	v_pk_mul_f32 v[158:159], v[122:123], v[122:123]
	v_pk_mul_f32 v[170:171], v[120:121], v[120:121]
	s_waitcnt vmcnt(1)
	v_pk_fma_f32 v[118:119], v[118:119], v[172:173], v[246:247]
	v_pk_fma_f32 v[116:117], v[116:117], v[178:179], v[244:245]
	s_waitcnt vmcnt(0)
	v_pk_fma_f32 v[114:115], v[114:115], v[176:177], v[250:251]
	v_pk_fma_f32 v[112:113], v[112:113], v[174:175], v[248:249]
	v_pk_mov_b32 v[176:177], v[154:155], v[152:153] op_sel:[1,0]
	v_mov_b32_e32 v155, v153
	v_pk_mov_b32 v[152:153], v[170:171], v[158:159] op_sel:[1,0]
	v_mov_b32_e32 v171, v159
	v_mul_f32_e32 v175, v113, v113
	v_mul_f32_e32 v172, v117, v117
	v_mul_f32_e32 v174, v119, v119
	v_pk_add_f32 v[154:155], v[176:177], v[154:155]
	v_pk_add_f32 v[152:153], v[152:153], v[170:171]
	v_mul_f32_e32 v169, v112, v112
	v_mul_f32_e32 v178, v114, v114
	v_mul_f32_e32 v179, v115, v115
	v_pk_fma_f32 v[158:159], v[116:117], v[116:117], v[172:173] op_sel_hi:[1,1,0]
	v_pk_fma_f32 v[172:173], v[118:119], v[118:119], v[174:175] op_sel_hi:[1,1,0]
	v_pk_add_f32 v[154:155], v[154:155], v[154:155] op_sel:[0,1] op_sel_hi:[1,0]
	v_pk_add_f32 v[152:153], v[152:153], v[152:153] op_sel:[0,1] op_sel_hi:[1,0]
	v_mov_b32_e32 v159, v178
	v_mov_b32_e32 v173, v179
	v_mov_b32_e32 v155, v169
	v_mov_b32_e32 v153, v175
	v_pk_add_f32 v[158:159], v[158:159], v[172:173]
	v_pk_add_f32 v[152:153], v[154:155], v[152:153]
	s_nop 0
	v_pk_add_f32 v[152:153], v[152:153], v[158:159]
	s_nop 0
	v_add_f32_e32 v152, v152, v153
	v_mov_b32_e32 v153, v166
	v_lshlrev_b32_e32 v151, 2, v151
	v_xor_b32_e32 v151, 64, v151
	ds_bpermute_b32 v151, v151, v152
	s_waitcnt lgkmcnt(0)
	v_add_f32_e32 v158, v152, v151
	v_lshlrev_b32_e32 v153, 2, v153
	v_xor_b32_e32 v151, 0x80, v153
	ds_bpermute_b32 v159, v151, v158
	v_add3_u32 v182, v150, v157, 16
	v_ashrrev_i32_e32 v183, 31, v182
	v_lshlrev_b64 v[182:183], 12, v[182:183]
	v_lshl_add_u64 v[182:183], s[14:15], 0, v[182:183]
	v_lshl_add_u64 v[194:195], v[182:183], 0, v[144:145]
	global_load_dwordx4 v[234:237], v[194:195], off
	global_load_dwordx4 v[240:243], v[194:195], off offset:16
	global_load_dwordx4 v[244:247], v[194:195], off offset:512
	global_load_dwordx4 v[248:251], v[194:195], off offset:528
	s_nop 0
	v_mov_b32_e32 v151, v166
	v_pk_mul_f32 v[154:155], v[220:221], 0.5 op_sel_hi:[1,0]
	v_pk_mul_f32 v[172:173], v[224:225], 0.5 op_sel_hi:[1,0]
	v_pk_mul_f32 v[170:171], v[222:223], 0.5 op_sel_hi:[1,0]
	v_pk_mul_f32 v[152:153], v[218:219], 0.5 op_sel_hi:[1,0]
	s_waitcnt vmcnt(3)
	v_pk_fma_f32 v[110:111], v[110:111], v[172:173], v[236:237]
	v_pk_fma_f32 v[108:109], v[108:109], v[170:171], v[234:235]
	s_waitcnt vmcnt(2)
	v_pk_fma_f32 v[106:107], v[106:107], v[154:155], v[242:243]
	v_pk_fma_f32 v[104:105], v[104:105], v[152:153], v[240:241]
	v_pk_mul_f32 v[180:181], v[232:233], 0.5 op_sel_hi:[1,0]
	v_pk_mul_f32 v[178:179], v[230:231], 0.5 op_sel_hi:[1,0]
	v_pk_mul_f32 v[174:175], v[226:227], 0.5 op_sel_hi:[1,0]
	v_pk_mul_f32 v[152:153], v[110:111], v[110:111]
	v_pk_mul_f32 v[154:155], v[108:109], v[108:109]
	v_pk_mul_f32 v[170:171], v[106:107], v[106:107]
	v_pk_mul_f32 v[172:173], v[104:105], v[104:105]
	v_pk_mul_f32 v[176:177], v[228:229], 0.5 op_sel_hi:[1,0]
	s_waitcnt vmcnt(1)
	v_pk_fma_f32 v[102:103], v[102:103], v[180:181], v[246:247]
	v_pk_fma_f32 v[100:101], v[100:101], v[178:179], v[244:245]
	s_waitcnt vmcnt(0)
; __device__ __forceinline__ float shfl_xor_l(float v, int o) { const int idx = (opq(lane_now()) ^ o) << 2; return __builtin_bit_cast(float, __builtin_amdgcn_ds_bpermute(idx, __builtin_bit_cast(int, v))); }
;     __device__ __forceinline__ void operator()(AccT& acc, const pg8::Unit& u, int wr, int wc, int fr_, int fq_) const {
;     ...
;         for (int ai = 0; ai < 2; ++ai)
; #pragma unroll
;             for (int m = 0; m < 4; ++m) { const int row = u.pm * 256 + ai * 128 + wr * 64 + m * 16 + fr + zoff;
;                 const float* xin = xp ? xp + (size_t)row * D : X + (size_t)row * D; float sacc = 0.f;
; #pragma unroll
;                 for (int bj = 0; bj < 2; ++bj)
; #pragma unroll
;                     for (int n = 0; n < 2; ++n) { const int col = u.pn * 256 + bj * 128 + wc * 32 + 8 * fq + 4 * n;
;                         const f32x4 xv = *(const f32x4*)(xin + col), gv = *(const f32x4*)(gt + col);
;                         const f32x4 xn = xv + (gv * coef) * acc[ai][bj][m][n]; acc[ai][bj][m][n] = xn;
;                         if (MODE == 0) *(f32x4*)(X + (size_t)row * D + col) = xn;
;                         sacc += (xn[0] * xn[0] + xn[1] * xn[1]) + (xn[2] * xn[2] + xn[3] * xn[3]); }
;                 asm volatile("" : "+v"(zoff) : "v"(sacc));
;                 sacc += shfl_xor_l(sacc, 16); sacc += shfl_xor_l(sacc, 32);
;                 ss[ai][m] = sacc; __builtin_amdgcn_sched_barrier(0); }
	v_pk_fma_f32 v[96:97], v[96:97], v[174:175], v[248:249]
	v_pk_mov_b32 v[178:179], v[154:155], v[152:153] op_sel:[1,0]
	v_mov_b32_e32 v155, v153
	v_pk_mov_b32 v[152:153], v[172:173], v[170:171] op_sel:[1,0]
	v_mov_b32_e32 v173, v171
	v_pk_fma_f32 v[98:99], v[98:99], v[176:177], v[250:251]
	v_mul_f32_e32 v177, v97, v97
	v_mul_f32_e32 v174, v101, v101
	v_mul_f32_e32 v176, v103, v103
	v_pk_add_f32 v[154:155], v[178:179], v[154:155]
	v_pk_add_f32 v[152:153], v[152:153], v[172:173]
	v_mul_f32_e32 v169, v96, v96
	v_mul_f32_e32 v180, v98, v98
	v_mul_f32_e32 v181, v99, v99
	v_pk_fma_f32 v[170:171], v[100:101], v[100:101], v[174:175] op_sel_hi:[1,1,0]
	v_pk_fma_f32 v[174:175], v[102:103], v[102:103], v[176:177] op_sel_hi:[1,1,0]
	v_pk_add_f32 v[154:155], v[154:155], v[154:155] op_sel:[0,1] op_sel_hi:[1,0]
	v_pk_add_f32 v[152:153], v[152:153], v[152:153] op_sel:[0,1] op_sel_hi:[1,0]
	v_mov_b32_e32 v171, v180
	v_mov_b32_e32 v175, v181
	v_mov_b32_e32 v155, v169
	v_mov_b32_e32 v153, v177
	v_pk_add_f32 v[170:171], v[170:171], v[174:175]
	v_pk_add_f32 v[152:153], v[154:155], v[152:153]
	s_nop 0
	v_pk_add_f32 v[152:153], v[152:153], v[170:171]
	s_nop 0
	v_add_f32_e32 v152, v152, v153
	v_mov_b32_e32 v153, v166
	v_lshlrev_b32_e32 v151, 2, v151
	v_xor_b32_e32 v151, 64, v151
	ds_bpermute_b32 v151, v151, v152
	s_waitcnt lgkmcnt(0)
	v_add_f32_e32 v169, v152, v151
	v_lshlrev_b32_e32 v153, 2, v153
	v_xor_b32_e32 v151, 0x80, v153
	ds_bpermute_b32 v170, v151, v169
	v_add3_u32 v184, v150, v157, 32
	v_ashrrev_i32_e32 v185, 31, v184
	v_lshlrev_b64 v[184:185], 12, v[184:185]
	v_lshl_add_u64 v[184:185], s[14:15], 0, v[184:185]
	v_lshl_add_u64 v[196:197], v[184:185], 0, v[144:145]
	global_load_dwordx4 v[234:237], v[196:197], off
	global_load_dwordx4 v[240:243], v[196:197], off offset:16
	global_load_dwordx4 v[244:247], v[196:197], off offset:512
	global_load_dwordx4 v[248:251], v[196:197], off offset:528
	s_nop 0
	v_mov_b32_e32 v151, v166
	v_pk_mul_f32 v[154:155], v[220:221], 0.5 op_sel_hi:[1,0]
	v_pk_mul_f32 v[174:175], v[224:225], 0.5 op_sel_hi:[1,0]
	v_pk_mul_f32 v[172:173], v[222:223], 0.5 op_sel_hi:[1,0]
	v_pk_mul_f32 v[152:153], v[218:219], 0.5 op_sel_hi:[1,0]
	s_waitcnt vmcnt(3)
	v_pk_fma_f32 v[94:95], v[94:95], v[174:175], v[236:237]
	v_pk_fma_f32 v[92:93], v[92:93], v[172:173], v[234:235]
	s_waitcnt vmcnt(2)
	v_pk_fma_f32 v[90:91], v[90:91], v[154:155], v[242:243]
	v_pk_fma_f32 v[88:89], v[88:89], v[152:153], v[240:241]
	v_pk_mul_f32 v[182:183], v[232:233], 0.5 op_sel_hi:[1,0]
	v_pk_mul_f32 v[180:181], v[230:231], 0.5 op_sel_hi:[1,0]
	v_pk_mul_f32 v[176:177], v[226:227], 0.5 op_sel_hi:[1,0]
	v_pk_mul_f32 v[152:153], v[94:95], v[94:95]
	v_pk_mul_f32 v[154:155], v[92:93], v[92:93]
	v_pk_mul_f32 v[172:173], v[90:91], v[90:91]
	v_pk_mul_f32 v[174:175], v[88:89], v[88:89]
	v_pk_mul_f32 v[178:179], v[228:229], 0.5 op_sel_hi:[1,0]
	s_waitcnt vmcnt(1)
	v_pk_fma_f32 v[86:87], v[86:87], v[182:183], v[246:247]
	v_pk_fma_f32 v[84:85], v[84:85], v[180:181], v[244:245]
	s_waitcnt vmcnt(0)
	v_pk_fma_f32 v[80:81], v[80:81], v[176:177], v[248:249]
	v_pk_mov_b32 v[180:181], v[154:155], v[152:153] op_sel:[1,0]
	v_mov_b32_e32 v155, v153
	v_pk_mov_b32 v[152:153], v[174:175], v[172:173] op_sel:[1,0]
	v_mov_b32_e32 v175, v173
	v_pk_fma_f32 v[82:83], v[82:83], v[178:179], v[250:251]
	v_mul_f32_e32 v179, v81, v81
	v_mul_f32_e32 v176, v85, v85
	v_mul_f32_e32 v178, v87, v87
	v_pk_add_f32 v[154:155], v[180:181], v[154:155]
	v_pk_add_f32 v[152:153], v[152:153], v[174:175]
	v_mul_f32_e32 v171, v80, v80
	v_mul_f32_e32 v182, v82, v82
	v_mul_f32_e32 v183, v83, v83
	v_pk_fma_f32 v[172:173], v[84:85], v[84:85], v[176:177] op_sel_hi:[1,1,0]
	v_pk_fma_f32 v[176:177], v[86:87], v[86:87], v[178:179] op_sel_hi:[1,1,0]
	v_pk_add_f32 v[154:155], v[154:155], v[154:155] op_sel:[0,1] op_sel_hi:[1,0]
	v_pk_add_f32 v[152:153], v[152:153], v[152:153] op_sel:[0,1] op_sel_hi:[1,0]
	v_mov_b32_e32 v173, v182
	v_mov_b32_e32 v177, v183
	v_mov_b32_e32 v155, v171
	v_mov_b32_e32 v153, v179
	v_pk_add_f32 v[172:173], v[172:173], v[176:177]
	v_pk_add_f32 v[152:153], v[154:155], v[152:153]
	s_nop 0
	v_pk_add_f32 v[152:153], v[152:153], v[172:173]
	s_nop 0
	v_add_f32_e32 v152, v152, v153
	v_mov_b32_e32 v153, v166
	v_lshlrev_b32_e32 v151, 2, v151
	v_xor_b32_e32 v151, 64, v151
	ds_bpermute_b32 v151, v151, v152
	s_waitcnt lgkmcnt(0)
	v_add_f32_e32 v171, v152, v151
	v_lshlrev_b32_e32 v153, 2, v153
	v_xor_b32_e32 v151, 0x80, v153
	ds_bpermute_b32 v172, v151, v171
	v_add3_u32 v186, v150, v157, 48
	v_ashrrev_i32_e32 v187, 31, v186
	v_lshlrev_b64 v[186:187], 12, v[186:187]
	v_lshl_add_u64 v[186:187], s[14:15], 0, v[186:187]
	v_lshl_add_u64 v[198:199], v[186:187], 0, v[144:145]
	global_load_dwordx4 v[234:237], v[198:199], off
	global_load_dwordx4 v[240:243], v[198:199], off offset:16
	global_load_dwordx4 v[244:247], v[198:199], off offset:512
	global_load_dwordx4 v[248:251], v[198:199], off offset:528
	s_nop 0
	v_mov_b32_e32 v151, v166
	v_pk_mul_f32 v[154:155], v[220:221], 0.5 op_sel_hi:[1,0]
	v_pk_mul_f32 v[176:177], v[224:225], 0.5 op_sel_hi:[1,0]
	v_pk_mul_f32 v[174:175], v[222:223], 0.5 op_sel_hi:[1,0]
	v_pk_mul_f32 v[152:153], v[218:219], 0.5 op_sel_hi:[1,0]
	s_waitcnt vmcnt(3)
	v_pk_fma_f32 v[78:79], v[78:79], v[176:177], v[236:237]
	v_pk_fma_f32 v[76:77], v[76:77], v[174:175], v[234:235]
	s_waitcnt vmcnt(2)
	v_pk_fma_f32 v[74:75], v[74:75], v[154:155], v[242:243]
	v_pk_fma_f32 v[72:73], v[72:73], v[152:153], v[240:241]
	v_pk_mul_f32 v[184:185], v[232:233], 0.5 op_sel_hi:[1,0]
	v_pk_mul_f32 v[182:183], v[230:231], 0.5 op_sel_hi:[1,0]
	v_pk_mul_f32 v[178:179], v[226:227], 0.5 op_sel_hi:[1,0]
	v_pk_mul_f32 v[152:153], v[78:79], v[78:79]
	v_pk_mul_f32 v[154:155], v[76:77], v[76:77]
	v_pk_mul_f32 v[174:175], v[74:75], v[74:75]
	v_pk_mul_f32 v[176:177], v[72:73], v[72:73]
	v_pk_mul_f32 v[180:181], v[228:229], 0.5 op_sel_hi:[1,0]
	s_waitcnt vmcnt(1)
; __device__ __forceinline__ float shfl_xor_l(float v, int o) { const int idx = (opq(lane_now()) ^ o) << 2; return __builtin_bit_cast(float, __builtin_amdgcn_ds_bpermute(idx, __builtin_bit_cast(int, v))); }
;     __device__ __forceinline__ void operator()(AccT& acc, const pg8::Unit& u, int wr, int wc, int fr_, int fq_) const {
;     ...
;         for (int ai = 0; ai < 2; ++ai)
; #pragma unroll
;             for (int m = 0; m < 4; ++m) { const int row = u.pm * 256 + ai * 128 + wr * 64 + m * 16 + fr + zoff;
;                 const float* xin = xp ? xp + (size_t)row * D : X + (size_t)row * D; float sacc = 0.f;
; #pragma unroll
;                 for (int bj = 0; bj < 2; ++bj)
; #pragma unroll
;                     for (int n = 0; n < 2; ++n) { const int col = u.pn * 256 + bj * 128 + wc * 32 + 8 * fq + 4 * n;
;                         const f32x4 xv = *(const f32x4*)(xin + col), gv = *(const f32x4*)(gt + col);
;                         const f32x4 xn = xv + (gv * coef) * acc[ai][bj][m][n]; acc[ai][bj][m][n] = xn;
;                         if (MODE == 0) *(f32x4*)(X + (size_t)row * D + col) = xn;
;                         sacc += (xn[0] * xn[0] + xn[1] * xn[1]) + (xn[2] * xn[2] + xn[3] * xn[3]); }
;                 asm volatile("" : "+v"(zoff) : "v"(sacc));
;                 sacc += shfl_xor_l(sacc, 16); sacc += shfl_xor_l(sacc, 32);
;                 ss[ai][m] = sacc; __builtin_amdgcn_sched_barrier(0); }
	v_pk_fma_f32 v[70:71], v[70:71], v[184:185], v[246:247]
	v_pk_fma_f32 v[68:69], v[68:69], v[182:183], v[244:245]
	s_waitcnt vmcnt(0)
	v_pk_fma_f32 v[64:65], v[64:65], v[178:179], v[248:249]
	v_pk_mov_b32 v[182:183], v[154:155], v[152:153] op_sel:[1,0]
	v_mov_b32_e32 v155, v153
	v_pk_mov_b32 v[152:153], v[176:177], v[174:175] op_sel:[1,0]
	v_mov_b32_e32 v177, v175
	v_pk_fma_f32 v[66:67], v[66:67], v[180:181], v[250:251]
	v_mul_f32_e32 v181, v65, v65
	v_mul_f32_e32 v178, v69, v69
	v_mul_f32_e32 v180, v71, v71
	v_pk_add_f32 v[154:155], v[182:183], v[154:155]
	v_pk_add_f32 v[152:153], v[152:153], v[176:177]
	v_mul_f32_e32 v173, v64, v64
	v_mul_f32_e32 v184, v66, v66
	v_mul_f32_e32 v185, v67, v67
	v_pk_fma_f32 v[174:175], v[68:69], v[68:69], v[178:179] op_sel_hi:[1,1,0]
	v_pk_fma_f32 v[178:179], v[70:71], v[70:71], v[180:181] op_sel_hi:[1,1,0]
	v_pk_add_f32 v[154:155], v[154:155], v[154:155] op_sel:[0,1] op_sel_hi:[1,0]
	v_pk_add_f32 v[152:153], v[152:153], v[152:153] op_sel:[0,1] op_sel_hi:[1,0]
	v_mov_b32_e32 v175, v184
	v_mov_b32_e32 v179, v185
	v_mov_b32_e32 v155, v173
	v_mov_b32_e32 v153, v181
	v_pk_add_f32 v[174:175], v[174:175], v[178:179]
	v_pk_add_f32 v[152:153], v[154:155], v[152:153]
	s_nop 0
	v_pk_add_f32 v[152:153], v[152:153], v[174:175]
	s_nop 0
	v_add_f32_e32 v152, v152, v153
	v_mov_b32_e32 v153, v166
	v_lshlrev_b32_e32 v151, 2, v151
	v_xor_b32_e32 v151, 64, v151
	ds_bpermute_b32 v151, v151, v152
	s_waitcnt lgkmcnt(0)
	v_add_f32_e32 v173, v152, v151
	v_lshlrev_b32_e32 v153, 2, v153
	v_xor_b32_e32 v151, 0x80, v153
	ds_bpermute_b32 v174, v151, v173
	v_add3_u32 v188, v150, v157, s58
	v_ashrrev_i32_e32 v189, 31, v188
	v_lshlrev_b64 v[188:189], 12, v[188:189]
	v_lshl_add_u64 v[188:189], s[14:15], 0, v[188:189]
	v_lshl_add_u64 v[200:201], v[188:189], 0, v[144:145]
	global_load_dwordx4 v[234:237], v[200:201], off
	global_load_dwordx4 v[240:243], v[200:201], off offset:16
	global_load_dwordx4 v[244:247], v[200:201], off offset:512
	global_load_dwordx4 v[248:251], v[200:201], off offset:528
	s_nop 0
	v_mov_b32_e32 v151, v166
	v_pk_mul_f32 v[154:155], v[220:221], 0.5 op_sel_hi:[1,0]
	v_pk_mul_f32 v[178:179], v[224:225], 0.5 op_sel_hi:[1,0]
	v_pk_mul_f32 v[176:177], v[222:223], 0.5 op_sel_hi:[1,0]
	v_pk_mul_f32 v[152:153], v[218:219], 0.5 op_sel_hi:[1,0]
	s_waitcnt vmcnt(3)
	v_pk_fma_f32 v[62:63], v[62:63], v[178:179], v[236:237]
	v_pk_fma_f32 v[60:61], v[60:61], v[176:177], v[234:235]
	s_waitcnt vmcnt(2)
	v_pk_fma_f32 v[58:59], v[58:59], v[154:155], v[242:243]
	v_pk_fma_f32 v[56:57], v[56:57], v[152:153], v[240:241]
	v_pk_mul_f32 v[186:187], v[232:233], 0.5 op_sel_hi:[1,0]
	v_pk_mul_f32 v[184:185], v[230:231], 0.5 op_sel_hi:[1,0]
	v_pk_mul_f32 v[180:181], v[226:227], 0.5 op_sel_hi:[1,0]
	v_pk_mul_f32 v[152:153], v[62:63], v[62:63]
	v_pk_mul_f32 v[154:155], v[60:61], v[60:61]
	v_pk_mul_f32 v[176:177], v[58:59], v[58:59]
	v_pk_mul_f32 v[178:179], v[56:57], v[56:57]
	v_pk_mul_f32 v[182:183], v[228:229], 0.5 op_sel_hi:[1,0]
	s_waitcnt vmcnt(1)
	v_pk_fma_f32 v[54:55], v[54:55], v[186:187], v[246:247]
	v_pk_fma_f32 v[52:53], v[52:53], v[184:185], v[244:245]
	s_waitcnt vmcnt(0)
	v_pk_fma_f32 v[48:49], v[48:49], v[180:181], v[248:249]
	v_pk_mov_b32 v[184:185], v[154:155], v[152:153] op_sel:[1,0]
	v_mov_b32_e32 v155, v153
	v_pk_mov_b32 v[152:153], v[178:179], v[176:177] op_sel:[1,0]
	v_mov_b32_e32 v179, v177
	v_pk_fma_f32 v[50:51], v[50:51], v[182:183], v[250:251]
	v_mul_f32_e32 v183, v49, v49
	v_mul_f32_e32 v180, v53, v53
	v_mul_f32_e32 v182, v55, v55
	v_pk_add_f32 v[154:155], v[184:185], v[154:155]
	v_pk_add_f32 v[152:153], v[152:153], v[178:179]
	v_mul_f32_e32 v175, v48, v48
	v_mul_f32_e32 v186, v50, v50
	v_mul_f32_e32 v187, v51, v51
	v_pk_fma_f32 v[176:177], v[52:53], v[52:53], v[180:181] op_sel_hi:[1,1,0]
	v_pk_fma_f32 v[180:181], v[54:55], v[54:55], v[182:183] op_sel_hi:[1,1,0]
	v_pk_add_f32 v[154:155], v[154:155], v[154:155] op_sel:[0,1] op_sel_hi:[1,0]
	v_pk_add_f32 v[152:153], v[152:153], v[152:153] op_sel:[0,1] op_sel_hi:[1,0]
	v_mov_b32_e32 v177, v186
	v_mov_b32_e32 v181, v187
	v_mov_b32_e32 v155, v175
	v_mov_b32_e32 v153, v183
	v_pk_add_f32 v[176:177], v[176:177], v[180:181]
	v_pk_add_f32 v[152:153], v[154:155], v[152:153]
	s_nop 0
	v_pk_add_f32 v[152:153], v[152:153], v[176:177]
	s_nop 0
	v_add_f32_e32 v152, v152, v153
	v_mov_b32_e32 v153, v166
	v_lshlrev_b32_e32 v151, 2, v151
	v_xor_b32_e32 v151, 64, v151
	ds_bpermute_b32 v151, v151, v152
	s_waitcnt lgkmcnt(0)
	v_add_f32_e32 v175, v152, v151
	v_lshlrev_b32_e32 v153, 2, v153
	v_xor_b32_e32 v151, 0x80, v153
	ds_bpermute_b32 v176, v151, v175
	v_add3_u32 v190, v150, v157, s59
	v_ashrrev_i32_e32 v191, 31, v190
	v_lshlrev_b64 v[190:191], 12, v[190:191]
	v_lshl_add_u64 v[190:191], s[14:15], 0, v[190:191]
	v_lshl_add_u64 v[202:203], v[190:191], 0, v[144:145]
	global_load_dwordx4 v[234:237], v[202:203], off
	global_load_dwordx4 v[240:243], v[202:203], off offset:16
	global_load_dwordx4 v[244:247], v[202:203], off offset:512
	global_load_dwordx4 v[248:251], v[202:203], off offset:528
	s_nop 0
	v_mov_b32_e32 v151, v166
	v_pk_mul_f32 v[154:155], v[220:221], 0.5 op_sel_hi:[1,0]
	v_pk_mul_f32 v[180:181], v[224:225], 0.5 op_sel_hi:[1,0]
	v_pk_mul_f32 v[178:179], v[222:223], 0.5 op_sel_hi:[1,0]
	v_pk_mul_f32 v[152:153], v[218:219], 0.5 op_sel_hi:[1,0]
	s_waitcnt vmcnt(3)
	v_pk_fma_f32 v[46:47], v[46:47], v[180:181], v[236:237]
	v_pk_fma_f32 v[44:45], v[44:45], v[178:179], v[234:235]
	s_waitcnt vmcnt(2)
; __device__ __forceinline__ float shfl_xor_l(float v, int o) { const int idx = (opq(lane_now()) ^ o) << 2; return __builtin_bit_cast(float, __builtin_amdgcn_ds_bpermute(idx, __builtin_bit_cast(int, v))); }
;     __device__ __forceinline__ void operator()(AccT& acc, const pg8::Unit& u, int wr, int wc, int fr_, int fq_) const {
;     ...
;         for (int ai = 0; ai < 2; ++ai)
; #pragma unroll
;             for (int m = 0; m < 4; ++m) { const int row = u.pm * 256 + ai * 128 + wr * 64 + m * 16 + fr + zoff;
;                 const float* xin = xp ? xp + (size_t)row * D : X + (size_t)row * D; float sacc = 0.f;
; #pragma unroll
;                 for (int bj = 0; bj < 2; ++bj)
; #pragma unroll
;                     for (int n = 0; n < 2; ++n) { const int col = u.pn * 256 + bj * 128 + wc * 32 + 8 * fq + 4 * n;
;                         const f32x4 xv = *(const f32x4*)(xin + col), gv = *(const f32x4*)(gt + col);
;                         const f32x4 xn = xv + (gv * coef) * acc[ai][bj][m][n]; acc[ai][bj][m][n] = xn;
;                         if (MODE == 0) *(f32x4*)(X + (size_t)row * D + col) = xn;
;                         sacc += (xn[0] * xn[0] + xn[1] * xn[1]) + (xn[2] * xn[2] + xn[3] * xn[3]); }
;                 asm volatile("" : "+v"(zoff) : "v"(sacc));
;                 sacc += shfl_xor_l(sacc, 16); sacc += shfl_xor_l(sacc, 32);
;                 ss[ai][m] = sacc; __builtin_amdgcn_sched_barrier(0); }
	v_pk_fma_f32 v[42:43], v[42:43], v[154:155], v[242:243]
	v_pk_fma_f32 v[40:41], v[40:41], v[152:153], v[240:241]
	v_pk_mul_f32 v[188:189], v[232:233], 0.5 op_sel_hi:[1,0]
	v_pk_mul_f32 v[186:187], v[230:231], 0.5 op_sel_hi:[1,0]
	v_pk_mul_f32 v[182:183], v[226:227], 0.5 op_sel_hi:[1,0]
	v_pk_mul_f32 v[152:153], v[46:47], v[46:47]
	v_pk_mul_f32 v[154:155], v[44:45], v[44:45]
	v_pk_mul_f32 v[178:179], v[42:43], v[42:43]
	v_pk_mul_f32 v[180:181], v[40:41], v[40:41]
	v_pk_mul_f32 v[184:185], v[228:229], 0.5 op_sel_hi:[1,0]
	s_waitcnt vmcnt(1)
	v_pk_fma_f32 v[38:39], v[38:39], v[188:189], v[246:247]
	v_pk_fma_f32 v[36:37], v[36:37], v[186:187], v[244:245]
	s_waitcnt vmcnt(0)
	v_pk_fma_f32 v[32:33], v[32:33], v[182:183], v[248:249]
	v_pk_mov_b32 v[186:187], v[154:155], v[152:153] op_sel:[1,0]
	v_mov_b32_e32 v155, v153
	v_pk_mov_b32 v[152:153], v[180:181], v[178:179] op_sel:[1,0]
	v_mov_b32_e32 v181, v179
	v_pk_fma_f32 v[34:35], v[34:35], v[184:185], v[250:251]
	v_mul_f32_e32 v185, v33, v33
	v_mul_f32_e32 v182, v37, v37
	v_mul_f32_e32 v184, v39, v39
	v_pk_add_f32 v[154:155], v[186:187], v[154:155]
	v_pk_add_f32 v[152:153], v[152:153], v[180:181]
	v_mul_f32_e32 v177, v32, v32
	v_mul_f32_e32 v188, v34, v34
	v_mul_f32_e32 v189, v35, v35
	v_pk_fma_f32 v[178:179], v[36:37], v[36:37], v[182:183] op_sel_hi:[1,1,0]
	v_pk_fma_f32 v[182:183], v[38:39], v[38:39], v[184:185] op_sel_hi:[1,1,0]
	v_pk_add_f32 v[154:155], v[154:155], v[154:155] op_sel:[0,1] op_sel_hi:[1,0]
	v_pk_add_f32 v[152:153], v[152:153], v[152:153] op_sel:[0,1] op_sel_hi:[1,0]
	v_mov_b32_e32 v179, v188
	v_mov_b32_e32 v183, v189
	v_mov_b32_e32 v155, v177
	v_mov_b32_e32 v153, v185
	v_pk_add_f32 v[178:179], v[178:179], v[182:183]
	v_pk_add_f32 v[152:153], v[154:155], v[152:153]
	s_nop 0
	v_pk_add_f32 v[152:153], v[152:153], v[178:179]
	s_nop 0
	v_add_f32_e32 v152, v152, v153
	v_mov_b32_e32 v153, v166
	v_lshlrev_b32_e32 v151, 2, v151
	v_xor_b32_e32 v151, 64, v151
	ds_bpermute_b32 v151, v151, v152
	s_waitcnt lgkmcnt(0)
	v_add_f32_e32 v177, v152, v151
	v_lshlrev_b32_e32 v153, 2, v153
	v_xor_b32_e32 v151, 0x80, v153
	ds_bpermute_b32 v178, v151, v177
	v_add3_u32 v192, v150, v157, s60
	v_ashrrev_i32_e32 v193, 31, v192
	v_lshlrev_b64 v[192:193], 12, v[192:193]
	v_lshl_add_u64 v[192:193], s[14:15], 0, v[192:193]
	v_lshl_add_u64 v[204:205], v[192:193], 0, v[144:145]
	global_load_dwordx4 v[234:237], v[204:205], off
	global_load_dwordx4 v[240:243], v[204:205], off offset:16
	global_load_dwordx4 v[244:247], v[204:205], off offset:512
	global_load_dwordx4 v[248:251], v[204:205], off offset:528
	s_nop 0
	v_mov_b32_e32 v151, v166
	v_pk_mul_f32 v[154:155], v[220:221], 0.5 op_sel_hi:[1,0]
	v_pk_mul_f32 v[182:183], v[224:225], 0.5 op_sel_hi:[1,0]
	v_pk_mul_f32 v[180:181], v[222:223], 0.5 op_sel_hi:[1,0]
	v_pk_mul_f32 v[152:153], v[218:219], 0.5 op_sel_hi:[1,0]
	s_waitcnt vmcnt(3)
	v_pk_fma_f32 v[30:31], v[30:31], v[182:183], v[236:237]
	v_pk_fma_f32 v[28:29], v[28:29], v[180:181], v[234:235]
	s_waitcnt vmcnt(2)
	v_pk_fma_f32 v[26:27], v[26:27], v[154:155], v[242:243]
	v_pk_fma_f32 v[24:25], v[24:25], v[152:153], v[240:241]
	v_pk_mul_f32 v[190:191], v[232:233], 0.5 op_sel_hi:[1,0]
	v_pk_mul_f32 v[188:189], v[230:231], 0.5 op_sel_hi:[1,0]
	v_pk_mul_f32 v[184:185], v[226:227], 0.5 op_sel_hi:[1,0]
	v_pk_mul_f32 v[152:153], v[30:31], v[30:31]
	v_pk_mul_f32 v[154:155], v[28:29], v[28:29]
	v_pk_mul_f32 v[180:181], v[26:27], v[26:27]
	v_pk_mul_f32 v[182:183], v[24:25], v[24:25]
	v_pk_mul_f32 v[186:187], v[228:229], 0.5 op_sel_hi:[1,0]
	s_waitcnt vmcnt(1)
	v_pk_fma_f32 v[22:23], v[22:23], v[190:191], v[246:247]
	v_pk_fma_f32 v[20:21], v[20:21], v[188:189], v[244:245]
	s_waitcnt vmcnt(0)
; __device__ __forceinline__ float shfl_xor_l(float v, int o) { const int idx = (opq(lane_now()) ^ o) << 2; return __builtin_bit_cast(float, __builtin_amdgcn_ds_bpermute(idx, __builtin_bit_cast(int, v))); }
;     __device__ __forceinline__ void operator()(AccT& acc, const pg8::Unit& u, int wr, int wc, int fr_, int fq_) const {
;     ...
;         for (int ai = 0; ai < 2; ++ai)
; #pragma unroll
;             for (int m = 0; m < 4; ++m) { const int row = u.pm * 256 + ai * 128 + wr * 64 + m * 16 + fr + zoff;
;                 const float* xin = xp ? xp + (size_t)row * D : X + (size_t)row * D; float sacc = 0.f;
; #pragma unroll
;                 for (int bj = 0; bj < 2; ++bj)
; #pragma unroll
;                     for (int n = 0; n < 2; ++n) { const int col = u.pn * 256 + bj * 128 + wc * 32 + 8 * fq + 4 * n;
;                         const f32x4 xv = *(const f32x4*)(xin + col), gv = *(const f32x4*)(gt + col);
;                         const f32x4 xn = xv + (gv * coef) * acc[ai][bj][m][n]; acc[ai][bj][m][n] = xn;
;                         if (MODE == 0) *(f32x4*)(X + (size_t)row * D + col) = xn;
;                         sacc += (xn[0] * xn[0] + xn[1] * xn[1]) + (xn[2] * xn[2] + xn[3] * xn[3]); }
;                 asm volatile("" : "+v"(zoff) : "v"(sacc));
;                 sacc += shfl_xor_l(sacc, 16); sacc += shfl_xor_l(sacc, 32);
;                 ss[ai][m] = sacc; __builtin_amdgcn_sched_barrier(0); }
;         if (fq == 0) {
; #pragma unroll
;             for (int ai = 0; ai < 2; ++ai)
; #pragma unroll
;                 for (int m = 0; m < 4; ++m) sred[wc * 256 + ai * 128 + wr * 64 + m * 16 + fr] = ss[ai][m]; }
	v_pk_fma_f32 v[16:17], v[16:17], v[184:185], v[248:249]
	v_pk_mov_b32 v[188:189], v[154:155], v[152:153] op_sel:[1,0]
	v_mov_b32_e32 v155, v153
	v_pk_mov_b32 v[152:153], v[182:183], v[180:181] op_sel:[1,0]
	v_mov_b32_e32 v183, v181
	v_pk_fma_f32 v[18:19], v[18:19], v[186:187], v[250:251]
	v_mul_f32_e32 v187, v17, v17
	v_mul_f32_e32 v184, v21, v21
	v_mul_f32_e32 v186, v23, v23
	v_pk_add_f32 v[154:155], v[188:189], v[154:155]
	v_pk_add_f32 v[152:153], v[152:153], v[182:183]
	v_mul_f32_e32 v179, v16, v16
	v_mul_f32_e32 v190, v18, v18
	v_mul_f32_e32 v191, v19, v19
	v_pk_fma_f32 v[180:181], v[20:21], v[20:21], v[184:185] op_sel_hi:[1,1,0]
	v_pk_fma_f32 v[184:185], v[22:23], v[22:23], v[186:187] op_sel_hi:[1,1,0]
	v_pk_add_f32 v[154:155], v[154:155], v[154:155] op_sel:[0,1] op_sel_hi:[1,0]
	v_pk_add_f32 v[152:153], v[152:153], v[152:153] op_sel:[0,1] op_sel_hi:[1,0]
	v_mov_b32_e32 v181, v190
	v_mov_b32_e32 v185, v191
	v_mov_b32_e32 v155, v179
	v_mov_b32_e32 v153, v187
	v_pk_add_f32 v[180:181], v[180:181], v[184:185]
	v_pk_add_f32 v[152:153], v[154:155], v[152:153]
	s_nop 0
	v_pk_add_f32 v[152:153], v[152:153], v[180:181]
	s_nop 0
	v_add_f32_e32 v152, v152, v153
	v_mov_b32_e32 v153, v166
	v_lshlrev_b32_e32 v151, 2, v151
	v_xor_b32_e32 v151, 64, v151
	ds_bpermute_b32 v151, v151, v152
	s_waitcnt lgkmcnt(0)
	v_add_f32_e32 v179, v152, v151
	v_lshlrev_b32_e32 v153, 2, v153
	v_xor_b32_e32 v151, 0x80, v153
	ds_bpermute_b32 v180, v151, v179
	v_add3_u32 v190, v150, v157, s61
	v_ashrrev_i32_e32 v191, 31, v190
	v_lshlrev_b64 v[190:191], 12, v[190:191]
	v_lshl_add_u64 v[190:191], s[14:15], 0, v[190:191]
	s_nop 0
	v_lshl_add_u64 v[202:203], v[190:191], 0, v[144:145]
	global_load_dwordx4 v[234:237], v[202:203], off
	global_load_dwordx4 v[240:243], v[202:203], off offset:16
	global_load_dwordx4 v[244:247], v[202:203], off offset:512
	global_load_dwordx4 v[248:251], v[202:203], off offset:528
	s_nop 0
	v_mov_b32_e32 v181, v166
	v_pk_mul_f32 v[206:207], v[220:221], 0.5 op_sel_hi:[1,0]
	v_pk_mul_f32 v[184:185], v[224:225], 0.5 op_sel_hi:[1,0]
	v_pk_mul_f32 v[182:183], v[222:223], 0.5 op_sel_hi:[1,0]
	v_pk_mul_f32 v[208:209], v[218:219], 0.5 op_sel_hi:[1,0]
	v_pk_mul_f32 v[210:211], v[232:233], 0.5 op_sel_hi:[1,0]
	v_pk_mul_f32 v[212:213], v[230:231], 0.5 op_sel_hi:[1,0]
	v_pk_mul_f32 v[188:189], v[228:229], 0.5 op_sel_hi:[1,0]
	v_pk_mul_f32 v[186:187], v[226:227], 0.5 op_sel_hi:[1,0]
	s_waitcnt vmcnt(3)
	v_pk_fma_f32 v[152:153], v[14:15], v[184:185], v[236:237]
	v_pk_fma_f32 v[154:155], v[12:13], v[182:183], v[234:235]
	s_waitcnt vmcnt(2)
	v_pk_fma_f32 v[148:149], v[10:11], v[206:207], v[242:243]
	v_pk_fma_f32 v[150:151], v[8:9], v[208:209], v[240:241]
	s_waitcnt vmcnt(1)
	v_pk_fma_f32 v[12:13], v[6:7], v[210:211], v[246:247]
	v_pk_fma_f32 v[14:15], v[4:5], v[212:213], v[244:245]
	s_waitcnt vmcnt(0)
	v_pk_fma_f32 v[8:9], v[2:3], v[188:189], v[250:251]
	v_pk_fma_f32 v[10:11], v[0:1], v[186:187], v[248:249]
	v_pk_mul_f32 v[0:1], v[152:153], v[152:153]
	v_pk_mul_f32 v[2:3], v[154:155], v[154:155]
	v_pk_mul_f32 v[4:5], v[148:149], v[148:149]
	v_pk_mul_f32 v[6:7], v[150:151], v[150:151]
	v_pk_mov_b32 v[186:187], v[2:3], v[0:1] op_sel:[1,0]
	v_mov_b32_e32 v3, v1
	v_pk_mov_b32 v[0:1], v[6:7], v[4:5] op_sel:[1,0]
	v_mov_b32_e32 v7, v5
	v_mul_f32_e32 v185, v10, v10
	v_mul_f32_e32 v182, v15, v15
	v_mul_f32_e32 v184, v13, v13
	v_pk_add_f32 v[2:3], v[186:187], v[2:3]
	v_pk_add_f32 v[0:1], v[0:1], v[6:7]
	v_mul_f32_e32 v188, v11, v11
	v_mul_f32_e32 v189, v8, v8
	v_mul_f32_e32 v190, v9, v9
	v_pk_fma_f32 v[4:5], v[14:15], v[14:15], v[182:183] op_sel_hi:[1,1,0]
	v_pk_fma_f32 v[182:183], v[12:13], v[12:13], v[184:185] op_sel_hi:[1,1,0]
	v_pk_add_f32 v[2:3], v[2:3], v[2:3] op_sel:[0,1] op_sel_hi:[1,0]
	v_pk_add_f32 v[0:1], v[0:1], v[0:1] op_sel:[0,1] op_sel_hi:[1,0]
	v_mov_b32_e32 v5, v189
	v_mov_b32_e32 v183, v190
	v_mov_b32_e32 v3, v185
	v_mov_b32_e32 v1, v188
	v_pk_add_f32 v[4:5], v[4:5], v[182:183]
	v_pk_add_f32 v[0:1], v[2:3], v[0:1]
	v_mov_b32_e32 v2, v166
	v_pk_add_f32 v[0:1], v[0:1], v[4:5]
	s_nop 0
	v_add_f32_e32 v0, v0, v1
	s_nop 0
	v_lshlrev_b32_e32 v1, 2, v181
	v_xor_b32_e32 v1, 64, v1
	ds_bpermute_b32 v1, v1, v0
	v_lshlrev_b32_e32 v2, 2, v2
	s_waitcnt lgkmcnt(0)
	v_add_f32_e32 v0, v0, v1
	v_xor_b32_e32 v1, 0x80, v2
	ds_bpermute_b32 v1, v1, v0
	v_cmp_eq_u32_e32 vcc, 0, v156
	s_and_saveexec_b64 s[4:5], vcc
	s_cbranch_execz .LBB0_2328
	v_add_f32_e32 v7, v169, v170
	v_add_f32_e32 v157, v158, v159
	s_waitcnt lgkmcnt(0)
	v_add_f32_e32 v0, v0, v1
	v_lshl_add_u32 v1, v147, 2, s55
	v_add_f32_e32 v2, v179, v180
	v_add_f32_e32 v3, v177, v178
	v_add_f32_e32 v4, v175, v176
	v_add_f32_e32 v5, v173, v174
	v_add_f32_e32 v6, v171, v172
	ds_write2_b32 v1, v157, v7 offset1:16
	ds_write2_b32 v1, v6, v5 offset0:32 offset1:48
	ds_write2_b32 v1, v4, v3 offset0:128 offset1:144
	ds_write2_b32 v1, v2, v0 offset0:160 offset1:176

; __global__ void __launch_bounds__(NTHR, 2) fwd_megakernel(Params P) {
	.amdhsa_kernel _Z14fwd_megakernel6Params
		.amdhsa_group_segment_fixed_size 0
		.amdhsa_private_segment_fixed_size 0
		.amdhsa_kernarg_size 528
		.amdhsa_user_sgpr_count 2
		.amdhsa_user_sgpr_dispatch_ptr 0
		.amdhsa_user_sgpr_queue_ptr 0
		.amdhsa_user_sgpr_kernarg_segment_ptr 1
		.amdhsa_user_sgpr_dispatch_id 0
		.amdhsa_user_sgpr_kernarg_preload_length 0
		.amdhsa_user_sgpr_kernarg_preload_offset 0
		.amdhsa_user_sgpr_private_segment_size 0
		.amdhsa_uses_dynamic_stack 0
		.amdhsa_enable_private_segment 0
		.amdhsa_system_sgpr_workgroup_id_x 1
		.amdhsa_system_sgpr_workgroup_id_y 0
		.amdhsa_system_sgpr_workgroup_id_z 0
		.amdhsa_system_sgpr_workgroup_info 0
		.amdhsa_system_vgpr_workitem_id 0
		.amdhsa_next_free_vgpr 256
		.amdhsa_next_free_sgpr 98
		.amdhsa_accum_offset 256
		.amdhsa_reserve_vcc 1
		.amdhsa_float_round_mode_32 0
		.amdhsa_float_round_mode_16_64 0
		.amdhsa_float_denorm_mode_32 3
		.amdhsa_float_denorm_mode_16_64 3
		.amdhsa_dx10_clamp 1
		.amdhsa_ieee_mode 1
		.amdhsa_fp16_overflow 0
		.amdhsa_tg_split 0
		.amdhsa_exception_fp_ieee_invalid_op 0
		.amdhsa_exception_fp_denorm_src 0
		.amdhsa_exception_fp_ieee_div_zero 0
		.amdhsa_exception_fp_ieee_overflow 0
		.amdhsa_exception_fp_ieee_underflow 0
		.amdhsa_exception_fp_ieee_inexact 0
		.amdhsa_exception_int_div_zero 0
	.end_amdhsa_kernel

; __global__ void __launch_bounds__(NTHR, 2) fwd_megakernel(Params P) {
amdhsa.kernels:
  - .agpr_count:     0
    .args:
      - .offset:         0
        .size:           272
        .value_kind:     by_value
      - .offset:         272
        .size:           4
        .value_kind:     hidden_block_count_x
      - .offset:         276
        .size:           4
        .value_kind:     hidden_block_count_y
      - .offset:         280
        .size:           4
        .value_kind:     hidden_block_count_z
      - .offset:         284
        .size:           2
        .value_kind:     hidden_group_size_x
      - .offset:         286
        .size:           2
        .value_kind:     hidden_group_size_y
      - .offset:         288
        .size:           2
        .value_kind:     hidden_group_size_z
      - .offset:         290
        .size:           2
        .value_kind:     hidden_remainder_x
      - .offset:         292
        .size:           2
        .value_kind:     hidden_remainder_y
      - .offset:         294
        .size:           2
        .value_kind:     hidden_remainder_z
      - .offset:         312
        .size:           8
        .value_kind:     hidden_global_offset_x
      - .offset:         320
        .size:           8
        .value_kind:     hidden_global_offset_y
      - .offset:         328
        .size:           8
        .value_kind:     hidden_global_offset_z
      - .offset:         336
        .size:           2
        .value_kind:     hidden_grid_dims
      - .offset:         392
        .size:           4
        .value_kind:     hidden_dynamic_lds_size
    .group_segment_fixed_size: 0
    .kernarg_segment_align: 8
    .kernarg_segment_size: 528
    .language:       OpenCL C
    .language_version:
      - 2
      - 0
    .max_flat_workgroup_size: 512
    .name:           _Z14fwd_megakernel6Params
    .private_segment_fixed_size: 0
    .sgpr_count:     104
    .sgpr_spill_count: 26
    .symbol:         _Z14fwd_megakernel6Params.kd
    .uniform_work_group_size: 1
    .uses_dynamic_stack: false
    .vgpr_count:     256
    .vgpr_spill_count: 0
    .wavefront_size: 64
